# P11 parameters fetched once per workgroup and shared through LDS (8x fewer hot-line L2 requests), first two rows requested before the parameter wait
# speedup vs baseline: 1.0023x; 1.0023x over previous
; __global__ void __launch_bounds__(NWAVES * 64, 2) mk_fwd(Args args) {
;     ...
;         const int per = (ML + F.NGW - 1) / F.NGW, per2 = (per + 1) & ~1, rbeg = F.gw * per2;
;         int rcur = -1; f32x4 PA[8];
;         for (int row0 = rbeg; row0 < rbeg + per2 && row0 < ML; row0 += 2) {
;             f32x4 v[2][8]; u32x2 yw[2][8];
; #pragma unroll
;             for (int q = 0; q < 2; ++q) { const int row = row0 + q; load_row_f32(args.out + (size_t)row * DM, F.lane, v[q]);
;                 const bf16_t* yr = Y + (size_t)row * DM;
; #pragma unroll
;                 for (int j = 0; j < 8; ++j) yw[q][j] = *(const u32x2*)(yr + 4 * F.lane + 256 * j); }
; #pragma unroll
;             for (int q = 0; q < 2; ++q) { const int row = row0 + q; const int r = row / SEQ;
;                 if (r != rcur) { const float* m1 = mod + (size_t)(9 + r) * 6144; rcur = r;
; #pragma unroll
;                     for (int j = 0; j < 8; ++j) { const int col = 4 * F.lane + 256 * j; PA[j] = *(const f32x4*)(m1 + 2 * DM + col) * *(const f32x4*)(post_norm + DM + col); } }
.LBB0_1288:
	s_cmp_gt_i32 s86, 11
	s_cselect_b64 s[2:3], -1, 0
	s_xor_b64 s[0:1], s[0:1], -1
	s_or_b64 s[0:1], s[2:3], s[0:1]
	s_and_b64 vcc, exec, s[0:1]
	s_cbranch_vccnz .LBB0_1296
	s_cmpk_lg_i32 s63, 0x100
	s_cbranch_scc1 .Lp11_generic
	v_and_b32_e32 v194, 63, v198
	v_lshlrev_b32_e32 v192, 4, v194
	v_add_u32_e32 v193, 0x1000, v192
	v_lshlrev_b32_e32 v194, 3, v194
	v_mov_b32_e32 v195, 0x358637bd
	s_lshr_b32 s0, s33, 8
	s_mul_i32 s1, s0, 0x6000
	s_add_u32 s8, s84, s1
	s_addc_u32 s9, s85, 0
	s_add_u32 s8, s8, 0x4000
	s_addc_u32 s9, s9, 0
	s_add_u32 s10, s8, 0x36000
	s_addc_u32 s11, s9, 0
	s_add_u32 s12, s82, 0x2000
	s_addc_u32 s13, s83, 0
	s_lshl_b32 s0, s33, 16
	s_add_u32 s14, s68, s0
	s_addc_u32 s15, s69, 0
	s_add_u32 s18, s94, s0
	s_addc_u32 s19, s95, 0
	s_lshl_b32 s0, s33, 15
	s_add_u32 s16, s84, s0
	s_addc_u32 s17, s85, 0
	s_add_u32 s22, s16, 0x8800000
	s_addc_u32 s23, s17, 0
	s_add_u32 s16, s16, 0x11800000
	s_addc_u32 s17, s17, 0
	v_readfirstlane_b32 s0, v198
	s_lshr_b32 s0, s0, 6
	s_lshl_b32 s0, s0, 10
	v_add_u32_e32 v204, s0, v192
	global_load_dwordx4 v[200:203], v204, s[8:9]
	global_load_dwordx4 v[208:211], v204, s[82:83]
	global_load_dwordx4 v[216:219], v204, s[10:11]
	global_load_dwordx4 v[212:215], v204, s[12:13]
	global_load_dwordx4 v[0:3], v192, s[14:15] offset:0 nt
	global_load_dwordx4 v[4:7], v192, s[14:15] offset:1024 nt
	global_load_dwordx4 v[8:11], v192, s[14:15] offset:2048 nt
	global_load_dwordx4 v[12:15], v192, s[14:15] offset:3072 nt
	global_load_dwordx4 v[16:19], v193, s[14:15] offset:0 nt
	global_load_dwordx4 v[20:23], v193, s[14:15] offset:1024 nt
	global_load_dwordx4 v[24:27], v193, s[14:15] offset:2048 nt
	global_load_dwordx4 v[28:31], v193, s[14:15] offset:3072 nt
	global_load_dwordx2 v[64:65], v194, s[16:17] offset:0
	global_load_dwordx2 v[66:67], v194, s[16:17] offset:512
	global_load_dwordx2 v[68:69], v194, s[16:17] offset:1024
	global_load_dwordx2 v[70:71], v194, s[16:17] offset:1536
	global_load_dwordx2 v[72:73], v194, s[16:17] offset:2048
	global_load_dwordx2 v[74:75], v194, s[16:17] offset:2560
	global_load_dwordx2 v[76:77], v194, s[16:17] offset:3072
	global_load_dwordx2 v[78:79], v194, s[16:17] offset:3584
	global_load_dwordx2 v[96:97], v194, s[22:23] offset:0
	global_load_dwordx2 v[98:99], v194, s[22:23] offset:512
	global_load_dwordx2 v[100:101], v194, s[22:23] offset:1024
	global_load_dwordx2 v[102:103], v194, s[22:23] offset:1536
	global_load_dwordx2 v[104:105], v194, s[22:23] offset:2048
	global_load_dwordx2 v[106:107], v194, s[22:23] offset:2560
	global_load_dwordx2 v[108:109], v194, s[22:23] offset:3072
	global_load_dwordx2 v[110:111], v194, s[22:23] offset:3584
	s_add_u32 s14, s14, 0x2000
	s_addc_u32 s15, s15, 0
	s_add_u32 s16, s16, 0x1000
	s_addc_u32 s17, s17, 0
	s_add_u32 s22, s22, 0x1000
	s_addc_u32 s23, s23, 0
	global_load_dwordx4 v[32:35], v192, s[14:15] offset:0 nt
	global_load_dwordx4 v[36:39], v192, s[14:15] offset:1024 nt
	global_load_dwordx4 v[40:43], v192, s[14:15] offset:2048 nt
	global_load_dwordx4 v[44:47], v192, s[14:15] offset:3072 nt
	global_load_dwordx4 v[48:51], v193, s[14:15] offset:0 nt
	global_load_dwordx4 v[52:55], v193, s[14:15] offset:1024 nt
	global_load_dwordx4 v[56:59], v193, s[14:15] offset:2048 nt
	global_load_dwordx4 v[60:63], v193, s[14:15] offset:3072 nt
	global_load_dwordx2 v[80:81], v194, s[16:17] offset:0
	global_load_dwordx2 v[82:83], v194, s[16:17] offset:512
	global_load_dwordx2 v[84:85], v194, s[16:17] offset:1024
	global_load_dwordx2 v[86:87], v194, s[16:17] offset:1536
	global_load_dwordx2 v[88:89], v194, s[16:17] offset:2048
	global_load_dwordx2 v[90:91], v194, s[16:17] offset:2560
	global_load_dwordx2 v[92:93], v194, s[16:17] offset:3072
	global_load_dwordx2 v[94:95], v194, s[16:17] offset:3584
	global_load_dwordx2 v[112:113], v194, s[22:23] offset:0
	global_load_dwordx2 v[114:115], v194, s[22:23] offset:512
	global_load_dwordx2 v[116:117], v194, s[22:23] offset:1024
	global_load_dwordx2 v[118:119], v194, s[22:23] offset:1536
	global_load_dwordx2 v[120:121], v194, s[22:23] offset:2048
	global_load_dwordx2 v[122:123], v194, s[22:23] offset:2560
	global_load_dwordx2 v[124:125], v194, s[22:23] offset:3072
	global_load_dwordx2 v[126:127], v194, s[22:23] offset:3584
	s_add_u32 s14, s14, 0x2000
	s_addc_u32 s15, s15, 0
	s_add_u32 s16, s16, 0x1000
	s_addc_u32 s17, s17, 0
	s_add_u32 s22, s22, 0x1000
	s_addc_u32 s23, s23, 0
	s_waitcnt vmcnt(48)
	v_mul_f32_e32 v200, v200, v208
	v_mul_f32_e32 v201, v201, v209
	v_mul_f32_e32 v202, v202, v210
	v_mul_f32_e32 v203, v203, v211
	v_mul_f32_e32 v216, v216, v212
	v_mul_f32_e32 v217, v217, v213
	v_mul_f32_e32 v218, v218, v214
	v_mul_f32_e32 v219, v219, v215
	ds_write_b128 v204, v[200:203]
	ds_write_b128 v204, v[216:219] offset:8192
	s_waitcnt lgkmcnt(0)
	s_barrier
; __device__ __forceinline__ float bf_lo(unsigned w) { return __uint_as_float(w << 16); }
; __device__ __forceinline__ float bf_hi(unsigned w) { return __uint_as_float(w & 0xffff0000u); }
; __device__ __forceinline__ float wave_sum(float v) {
; #pragma unroll
;     for (int o = 1; o < 64; o <<= 1) v += __shfl_xor(v, o);
;     return v;
; }
; __global__ void __launch_bounds__(NWAVES * 64, 2) mk_fwd(Args args) {
;     ...
;             for (int q = 0; q < 2; ++q) { const int row = row0 + q; load_row_f32(args.out + (size_t)row * DM, F.lane, v[q]);
;                 const bf16_t* yr = Y + (size_t)row * DM;
; #pragma unroll
;                 for (int j = 0; j < 8; ++j) yw[q][j] = *(const u32x2*)(yr + 4 * F.lane + 256 * j); }
; #pragma unroll
;             for (int q = 0; q < 2; ++q) { const int row = row0 + q; const int r = row / SEQ;
;                 if (r != rcur) { const float* m1 = mod + (size_t)(9 + r) * 6144; rcur = r;
; #pragma unroll
;                     for (int j = 0; j < 8; ++j) { const int col = 4 * F.lane + 256 * j; PA[j] = *(const f32x4*)(m1 + 2 * DM + col) * *(const f32x4*)(post_norm + DM + col); } }
;                 float sy = 0.f;
; #pragma unroll
;                 for (int j = 0; j < 8; ++j) { const float a = bf_lo(yw[q][j].x), b = bf_hi(yw[q][j].x), c2 = bf_lo(yw[q][j].y), d = bf_hi(yw[q][j].y); sy += (a * a + b * b) + (c2 * c2 + d * d); }
;                 const float rsy = __builtin_amdgcn_rsqf(wave_sum(sy) * (1.f / DM) + EPS);
	ds_read_b128 v[128:131], v192 offset:0
	ds_read_b128 v[160:163], v192 offset:8192
	ds_read_b128 v[132:135], v192 offset:1024
	ds_read_b128 v[164:167], v192 offset:9216
	ds_read_b128 v[136:139], v192 offset:2048
	ds_read_b128 v[168:171], v192 offset:10240
	ds_read_b128 v[140:143], v192 offset:3072
	ds_read_b128 v[172:175], v192 offset:11264
	ds_read_b128 v[144:147], v192 offset:4096
	ds_read_b128 v[176:179], v192 offset:12288
	ds_read_b128 v[148:151], v192 offset:5120
	ds_read_b128 v[180:183], v192 offset:13312
	ds_read_b128 v[152:155], v192 offset:6144
	ds_read_b128 v[184:187], v192 offset:14336
	ds_read_b128 v[156:159], v192 offset:7168
	ds_read_b128 v[188:191], v192 offset:15360
	s_waitcnt lgkmcnt(0)
	s_waitcnt vmcnt(24)
	v_lshlrev_b32_e32 v200, 16, v64
	v_and_b32_e32 v201, 0xffff0000, v64
	v_lshlrev_b32_e32 v202, 16, v65
	v_and_b32_e32 v203, 0xffff0000, v65
	v_mul_f32_e32 v208, v200, v200
	v_mul_f32_e32 v209, v201, v201
	v_fmac_f32_e32 v208, v202, v202
	v_fmac_f32_e32 v209, v203, v203
	v_lshlrev_b32_e32 v204, 16, v96
	v_and_b32_e32 v205, 0xffff0000, v96
	v_lshlrev_b32_e32 v206, 16, v97
	v_and_b32_e32 v207, 0xffff0000, v97
	v_mul_f32_e32 v210, v204, v204
	v_mul_f32_e32 v211, v205, v205
	v_fmac_f32_e32 v210, v206, v206
	v_fmac_f32_e32 v211, v207, v207
	v_lshlrev_b32_e32 v200, 16, v66
	v_and_b32_e32 v201, 0xffff0000, v66
	v_lshlrev_b32_e32 v202, 16, v67
	v_and_b32_e32 v203, 0xffff0000, v67
	v_fmac_f32_e32 v208, v200, v200
	v_fmac_f32_e32 v209, v201, v201
	v_fmac_f32_e32 v208, v202, v202
	v_fmac_f32_e32 v209, v203, v203
	v_lshlrev_b32_e32 v204, 16, v98
	v_and_b32_e32 v205, 0xffff0000, v98
	v_lshlrev_b32_e32 v206, 16, v99
	v_and_b32_e32 v207, 0xffff0000, v99
	v_fmac_f32_e32 v210, v204, v204
	v_fmac_f32_e32 v211, v205, v205
	v_fmac_f32_e32 v210, v206, v206
	v_fmac_f32_e32 v211, v207, v207
	v_lshlrev_b32_e32 v200, 16, v68
	v_and_b32_e32 v201, 0xffff0000, v68
	v_lshlrev_b32_e32 v202, 16, v69
	v_and_b32_e32 v203, 0xffff0000, v69
	v_fmac_f32_e32 v208, v200, v200
	v_fmac_f32_e32 v209, v201, v201
	v_fmac_f32_e32 v208, v202, v202
	v_fmac_f32_e32 v209, v203, v203
	v_lshlrev_b32_e32 v204, 16, v100
	v_and_b32_e32 v205, 0xffff0000, v100
	v_lshlrev_b32_e32 v206, 16, v101
	v_and_b32_e32 v207, 0xffff0000, v101
	v_fmac_f32_e32 v210, v204, v204
	v_fmac_f32_e32 v211, v205, v205
	v_fmac_f32_e32 v210, v206, v206
	v_fmac_f32_e32 v211, v207, v207
	v_lshlrev_b32_e32 v200, 16, v70
	v_and_b32_e32 v201, 0xffff0000, v70
	v_lshlrev_b32_e32 v202, 16, v71
	v_and_b32_e32 v203, 0xffff0000, v71
	v_fmac_f32_e32 v208, v200, v200
	v_fmac_f32_e32 v209, v201, v201
	v_fmac_f32_e32 v208, v202, v202
	v_fmac_f32_e32 v209, v203, v203
	v_lshlrev_b32_e32 v204, 16, v102
	v_and_b32_e32 v205, 0xffff0000, v102
	v_lshlrev_b32_e32 v206, 16, v103
	v_and_b32_e32 v207, 0xffff0000, v103
	v_fmac_f32_e32 v210, v204, v204
	v_fmac_f32_e32 v211, v205, v205
	v_fmac_f32_e32 v210, v206, v206
	v_fmac_f32_e32 v211, v207, v207
	v_lshlrev_b32_e32 v200, 16, v72
	v_and_b32_e32 v201, 0xffff0000, v72
	v_lshlrev_b32_e32 v202, 16, v73
	v_and_b32_e32 v203, 0xffff0000, v73
	v_fmac_f32_e32 v208, v200, v200
	v_fmac_f32_e32 v209, v201, v201
	v_fmac_f32_e32 v208, v202, v202
	v_fmac_f32_e32 v209, v203, v203
	v_lshlrev_b32_e32 v204, 16, v104
	v_and_b32_e32 v205, 0xffff0000, v104
	v_lshlrev_b32_e32 v206, 16, v105
	v_and_b32_e32 v207, 0xffff0000, v105
	v_fmac_f32_e32 v210, v204, v204
	v_fmac_f32_e32 v211, v205, v205
	v_fmac_f32_e32 v210, v206, v206
	v_fmac_f32_e32 v211, v207, v207
	v_lshlrev_b32_e32 v200, 16, v74
	v_and_b32_e32 v201, 0xffff0000, v74
	v_lshlrev_b32_e32 v202, 16, v75
	v_and_b32_e32 v203, 0xffff0000, v75
	v_fmac_f32_e32 v208, v200, v200
	v_fmac_f32_e32 v209, v201, v201
	v_fmac_f32_e32 v208, v202, v202
	v_fmac_f32_e32 v209, v203, v203
	v_lshlrev_b32_e32 v204, 16, v106
	v_and_b32_e32 v205, 0xffff0000, v106
	v_lshlrev_b32_e32 v206, 16, v107
	v_and_b32_e32 v207, 0xffff0000, v107
	v_fmac_f32_e32 v210, v204, v204
	v_fmac_f32_e32 v211, v205, v205
	v_fmac_f32_e32 v210, v206, v206
	v_fmac_f32_e32 v211, v207, v207
	v_lshlrev_b32_e32 v200, 16, v76
	v_and_b32_e32 v201, 0xffff0000, v76
	v_lshlrev_b32_e32 v202, 16, v77
	v_and_b32_e32 v203, 0xffff0000, v77
	v_fmac_f32_e32 v208, v200, v200
	v_fmac_f32_e32 v209, v201, v201
	v_fmac_f32_e32 v208, v202, v202
	v_fmac_f32_e32 v209, v203, v203
	v_lshlrev_b32_e32 v204, 16, v108
	v_and_b32_e32 v205, 0xffff0000, v108
	v_lshlrev_b32_e32 v206, 16, v109
	v_and_b32_e32 v207, 0xffff0000, v109
	v_fmac_f32_e32 v210, v204, v204
	v_fmac_f32_e32 v211, v205, v205
	v_fmac_f32_e32 v210, v206, v206
	v_fmac_f32_e32 v211, v207, v207
	v_lshlrev_b32_e32 v200, 16, v78
	v_and_b32_e32 v201, 0xffff0000, v78
	v_lshlrev_b32_e32 v202, 16, v79
	v_and_b32_e32 v203, 0xffff0000, v79
	v_fmac_f32_e32 v208, v200, v200
	v_fmac_f32_e32 v209, v201, v201
	v_fmac_f32_e32 v208, v202, v202
	v_fmac_f32_e32 v209, v203, v203
	v_lshlrev_b32_e32 v204, 16, v110
	v_and_b32_e32 v205, 0xffff0000, v110
	v_lshlrev_b32_e32 v206, 16, v111
	v_and_b32_e32 v207, 0xffff0000, v111
	v_fmac_f32_e32 v210, v204, v204
	v_fmac_f32_e32 v211, v205, v205
	v_fmac_f32_e32 v210, v206, v206
	v_fmac_f32_e32 v211, v207, v207
	v_add_f32_e32 v208, v208, v209
	v_add_f32_e32 v210, v210, v211
	s_nop 0
	v_add_f32_dpp v212, v208, v208 quad_perm:[1,0,3,2] row_mask:0xf bank_mask:0xf
	v_add_f32_dpp v213, v210, v210 quad_perm:[1,0,3,2] row_mask:0xf bank_mask:0xf
	s_nop 0
	v_add_f32_dpp v212, v212, v212 quad_perm:[2,3,0,1] row_mask:0xf bank_mask:0xf
	v_add_f32_dpp v213, v213, v213 quad_perm:[2,3,0,1] row_mask:0xf bank_mask:0xf
	s_nop 0
	v_add_f32_dpp v212, v212, v212 row_half_mirror row_mask:0xf bank_mask:0xf
	v_add_f32_dpp v213, v213, v213 row_half_mirror row_mask:0xf bank_mask:0xf
; __device__ __forceinline__ float bf_lo(unsigned w) { return __uint_as_float(w << 16); }
; __device__ __forceinline__ float bf_hi(unsigned w) { return __uint_as_float(w & 0xffff0000u); }
; __global__ void __launch_bounds__(NWAVES * 64, 2) mk_fwd(Args args) {
;     ...
;                 const float rsy = __builtin_amdgcn_rsqf(wave_sum(sy) * (1.f / DM) + EPS);
; #pragma unroll
;                 for (int j = 0; j < 8; ++j) { const int col = 4 * F.lane + 256 * j;
;                     const f32x4 y4 = (f32x4){bf_lo(yw[q][j].x), bf_hi(yw[q][j].x), bf_lo(yw[q][j].y), bf_hi(yw[q][j].y)};
;                     *(f32x4*)(args.out + (size_t)row * DM + col) = v[q][j] + PA[j] * (y4 * rsy); }
	s_nop 0
	v_add_f32_dpp v212, v212, v212 row_mirror row_mask:0xf bank_mask:0xf
	v_add_f32_dpp v213, v213, v213 row_mirror row_mask:0xf bank_mask:0xf
	s_nop 0
	v_readlane_b32 s4, v212, 0
	v_readlane_b32 s5, v212, 16
	v_readlane_b32 s6, v212, 32
	v_readlane_b32 s7, v212, 48
	v_readlane_b32 s24, v213, 0
	v_readlane_b32 s25, v213, 16
	v_readlane_b32 s26, v213, 32
	v_readlane_b32 s27, v213, 48
	s_nop 1
	v_mov_b32_e32 v214, s4
	v_mov_b32_e32 v215, s24
	v_add_f32_e32 v214, s5, v214
	v_add_f32_e32 v215, s25, v215
	v_add_f32_e32 v214, s6, v214
	v_add_f32_e32 v215, s26, v215
	v_add_f32_e32 v214, s7, v214
	v_add_f32_e32 v215, s27, v215
	v_fmamk_f32 v214, v214, 0x3a000000, v195
	v_fmamk_f32 v215, v215, 0x3a000000, v195
	v_rsq_f32_e32 v214, v214
	v_rsq_f32_e32 v215, v215
	s_nop 0
	v_lshlrev_b32_e32 v200, 16, v64
	v_and_b32_e32 v201, 0xffff0000, v64
	v_lshlrev_b32_e32 v202, 16, v65
	v_and_b32_e32 v203, 0xffff0000, v65
	v_lshlrev_b32_e32 v204, 16, v96
	v_and_b32_e32 v205, 0xffff0000, v96
	v_lshlrev_b32_e32 v206, 16, v97
	v_and_b32_e32 v207, 0xffff0000, v97
	v_mul_f32_e32 v200, v214, v200
	v_mul_f32_e32 v201, v214, v201
	v_mul_f32_e32 v202, v214, v202
	v_mul_f32_e32 v203, v214, v203
	v_mul_f32_e32 v204, v215, v204
	v_mul_f32_e32 v205, v215, v205
	v_mul_f32_e32 v206, v215, v206
	v_mul_f32_e32 v207, v215, v207
	v_fmac_f32_e32 v0, v128, v200
	v_fmac_f32_e32 v1, v129, v201
	v_fmac_f32_e32 v2, v130, v202
	v_fmac_f32_e32 v3, v131, v203
	v_fmac_f32_e32 v0, v160, v204
	v_fmac_f32_e32 v1, v161, v205
	v_fmac_f32_e32 v2, v162, v206
	v_fmac_f32_e32 v3, v163, v207
	global_store_dwordx4 v192, v[0:3], s[18:19] offset:0
	v_lshlrev_b32_e32 v200, 16, v66
	v_and_b32_e32 v201, 0xffff0000, v66
	v_lshlrev_b32_e32 v202, 16, v67
	v_and_b32_e32 v203, 0xffff0000, v67
	v_lshlrev_b32_e32 v204, 16, v98
	v_and_b32_e32 v205, 0xffff0000, v98
	v_lshlrev_b32_e32 v206, 16, v99
	v_and_b32_e32 v207, 0xffff0000, v99
	v_mul_f32_e32 v200, v214, v200
	v_mul_f32_e32 v201, v214, v201
	v_mul_f32_e32 v202, v214, v202
	v_mul_f32_e32 v203, v214, v203
	v_mul_f32_e32 v204, v215, v204
	v_mul_f32_e32 v205, v215, v205
	v_mul_f32_e32 v206, v215, v206
	v_mul_f32_e32 v207, v215, v207
	v_fmac_f32_e32 v4, v132, v200
	v_fmac_f32_e32 v5, v133, v201
	v_fmac_f32_e32 v6, v134, v202
	v_fmac_f32_e32 v7, v135, v203
	v_fmac_f32_e32 v4, v164, v204
	v_fmac_f32_e32 v5, v165, v205
	v_fmac_f32_e32 v6, v166, v206
	v_fmac_f32_e32 v7, v167, v207
	global_store_dwordx4 v192, v[4:7], s[18:19] offset:1024
	v_lshlrev_b32_e32 v200, 16, v68
	v_and_b32_e32 v201, 0xffff0000, v68
	v_lshlrev_b32_e32 v202, 16, v69
	v_and_b32_e32 v203, 0xffff0000, v69
	v_lshlrev_b32_e32 v204, 16, v100
	v_and_b32_e32 v205, 0xffff0000, v100
	v_lshlrev_b32_e32 v206, 16, v101
	v_and_b32_e32 v207, 0xffff0000, v101
	v_mul_f32_e32 v200, v214, v200
	v_mul_f32_e32 v201, v214, v201
	v_mul_f32_e32 v202, v214, v202
	v_mul_f32_e32 v203, v214, v203
	v_mul_f32_e32 v204, v215, v204
	v_mul_f32_e32 v205, v215, v205
	v_mul_f32_e32 v206, v215, v206
	v_mul_f32_e32 v207, v215, v207
	v_fmac_f32_e32 v8, v136, v200
	v_fmac_f32_e32 v9, v137, v201
	v_fmac_f32_e32 v10, v138, v202
	v_fmac_f32_e32 v11, v139, v203
	v_fmac_f32_e32 v8, v168, v204
	v_fmac_f32_e32 v9, v169, v205
	v_fmac_f32_e32 v10, v170, v206
	v_fmac_f32_e32 v11, v171, v207
	global_store_dwordx4 v192, v[8:11], s[18:19] offset:2048
	v_lshlrev_b32_e32 v200, 16, v70
	v_and_b32_e32 v201, 0xffff0000, v70
	v_lshlrev_b32_e32 v202, 16, v71
	v_and_b32_e32 v203, 0xffff0000, v71
	v_lshlrev_b32_e32 v204, 16, v102
	v_and_b32_e32 v205, 0xffff0000, v102
	v_lshlrev_b32_e32 v206, 16, v103
	v_and_b32_e32 v207, 0xffff0000, v103
	v_mul_f32_e32 v200, v214, v200
	v_mul_f32_e32 v201, v214, v201
	v_mul_f32_e32 v202, v214, v202
	v_mul_f32_e32 v203, v214, v203
	v_mul_f32_e32 v204, v215, v204
	v_mul_f32_e32 v205, v215, v205
	v_mul_f32_e32 v206, v215, v206
	v_mul_f32_e32 v207, v215, v207
	v_fmac_f32_e32 v12, v140, v200
	v_fmac_f32_e32 v13, v141, v201
	v_fmac_f32_e32 v14, v142, v202
	v_fmac_f32_e32 v15, v143, v203
	v_fmac_f32_e32 v12, v172, v204
	v_fmac_f32_e32 v13, v173, v205
	v_fmac_f32_e32 v14, v174, v206
	v_fmac_f32_e32 v15, v175, v207
	global_store_dwordx4 v192, v[12:15], s[18:19] offset:3072
	v_lshlrev_b32_e32 v200, 16, v72
	v_and_b32_e32 v201, 0xffff0000, v72
	v_lshlrev_b32_e32 v202, 16, v73
	v_and_b32_e32 v203, 0xffff0000, v73
	v_lshlrev_b32_e32 v204, 16, v104
	v_and_b32_e32 v205, 0xffff0000, v104
	v_lshlrev_b32_e32 v206, 16, v105
	v_and_b32_e32 v207, 0xffff0000, v105
	v_mul_f32_e32 v200, v214, v200
	v_mul_f32_e32 v201, v214, v201
	v_mul_f32_e32 v202, v214, v202
	v_mul_f32_e32 v203, v214, v203
	v_mul_f32_e32 v204, v215, v204
	v_mul_f32_e32 v205, v215, v205
	v_mul_f32_e32 v206, v215, v206
	v_mul_f32_e32 v207, v215, v207
	v_fmac_f32_e32 v16, v144, v200
	v_fmac_f32_e32 v17, v145, v201
	v_fmac_f32_e32 v18, v146, v202
	v_fmac_f32_e32 v19, v147, v203
	v_fmac_f32_e32 v16, v176, v204
	v_fmac_f32_e32 v17, v177, v205
	v_fmac_f32_e32 v18, v178, v206
	v_fmac_f32_e32 v19, v179, v207
	global_store_dwordx4 v193, v[16:19], s[18:19] offset:0
	v_lshlrev_b32_e32 v200, 16, v74
	v_and_b32_e32 v201, 0xffff0000, v74
	v_lshlrev_b32_e32 v202, 16, v75
	v_and_b32_e32 v203, 0xffff0000, v75
	v_lshlrev_b32_e32 v204, 16, v106
	v_and_b32_e32 v205, 0xffff0000, v106
	v_lshlrev_b32_e32 v206, 16, v107
	v_and_b32_e32 v207, 0xffff0000, v107
	v_mul_f32_e32 v200, v214, v200
	v_mul_f32_e32 v201, v214, v201
	v_mul_f32_e32 v202, v214, v202
	v_mul_f32_e32 v203, v214, v203
	v_mul_f32_e32 v204, v215, v204
	v_mul_f32_e32 v205, v215, v205
	v_mul_f32_e32 v206, v215, v206
	v_mul_f32_e32 v207, v215, v207
	v_fmac_f32_e32 v20, v148, v200
	v_fmac_f32_e32 v21, v149, v201
	v_fmac_f32_e32 v22, v150, v202
; __device__ __forceinline__ float bf_lo(unsigned w) { return __uint_as_float(w << 16); }
; __device__ __forceinline__ float bf_hi(unsigned w) { return __uint_as_float(w & 0xffff0000u); }
; __global__ void __launch_bounds__(NWAVES * 64, 2) mk_fwd(Args args) {
;     ...
;         for (int row0 = rbeg; row0 < rbeg + per2 && row0 < ML; row0 += 2) {
;             f32x4 v[2][8]; u32x2 yw[2][8];
; #pragma unroll
;             for (int q = 0; q < 2; ++q) { const int row = row0 + q; load_row_f32(args.out + (size_t)row * DM, F.lane, v[q]);
;                 const bf16_t* yr = Y + (size_t)row * DM;
; #pragma unroll
;                 for (int j = 0; j < 8; ++j) yw[q][j] = *(const u32x2*)(yr + 4 * F.lane + 256 * j); }
; #pragma unroll
;             for (int q = 0; q < 2; ++q) { const int row = row0 + q; const int r = row / SEQ;
;                 if (r != rcur) { const float* m1 = mod + (size_t)(9 + r) * 6144; rcur = r;
; #pragma unroll
;                     for (int j = 0; j < 8; ++j) { const int col = 4 * F.lane + 256 * j; PA[j] = *(const f32x4*)(m1 + 2 * DM + col) * *(const f32x4*)(post_norm + DM + col); } }
;                 float sy = 0.f;
; #pragma unroll
;                 for (int j = 0; j < 8; ++j) { const float a = bf_lo(yw[q][j].x), b = bf_hi(yw[q][j].x), c2 = bf_lo(yw[q][j].y), d = bf_hi(yw[q][j].y); sy += (a * a + b * b) + (c2 * c2 + d * d); }
;                 const float rsy = __builtin_amdgcn_rsqf(wave_sum(sy) * (1.f / DM) + EPS);
; #pragma unroll
;                 for (int j = 0; j < 8; ++j) { const int col = 4 * F.lane + 256 * j;
;                     const f32x4 y4 = (f32x4){bf_lo(yw[q][j].x), bf_hi(yw[q][j].x), bf_lo(yw[q][j].y), bf_hi(yw[q][j].y)};
;                     *(f32x4*)(args.out + (size_t)row * DM + col) = v[q][j] + PA[j] * (y4 * rsy); }
	v_fmac_f32_e32 v23, v151, v203
	v_fmac_f32_e32 v20, v180, v204
	v_fmac_f32_e32 v21, v181, v205
	v_fmac_f32_e32 v22, v182, v206
	v_fmac_f32_e32 v23, v183, v207
	global_store_dwordx4 v193, v[20:23], s[18:19] offset:1024
	v_lshlrev_b32_e32 v200, 16, v76
	v_and_b32_e32 v201, 0xffff0000, v76
	v_lshlrev_b32_e32 v202, 16, v77
	v_and_b32_e32 v203, 0xffff0000, v77
	v_lshlrev_b32_e32 v204, 16, v108
	v_and_b32_e32 v205, 0xffff0000, v108
	v_lshlrev_b32_e32 v206, 16, v109
	v_and_b32_e32 v207, 0xffff0000, v109
	v_mul_f32_e32 v200, v214, v200
	v_mul_f32_e32 v201, v214, v201
	v_mul_f32_e32 v202, v214, v202
	v_mul_f32_e32 v203, v214, v203
	v_mul_f32_e32 v204, v215, v204
	v_mul_f32_e32 v205, v215, v205
	v_mul_f32_e32 v206, v215, v206
	v_mul_f32_e32 v207, v215, v207
	v_fmac_f32_e32 v24, v152, v200
	v_fmac_f32_e32 v25, v153, v201
	v_fmac_f32_e32 v26, v154, v202
	v_fmac_f32_e32 v27, v155, v203
	v_fmac_f32_e32 v24, v184, v204
	v_fmac_f32_e32 v25, v185, v205
	v_fmac_f32_e32 v26, v186, v206
	v_fmac_f32_e32 v27, v187, v207
	global_store_dwordx4 v193, v[24:27], s[18:19] offset:2048
	v_lshlrev_b32_e32 v200, 16, v78
	v_and_b32_e32 v201, 0xffff0000, v78
	v_lshlrev_b32_e32 v202, 16, v79
	v_and_b32_e32 v203, 0xffff0000, v79
	v_lshlrev_b32_e32 v204, 16, v110
	v_and_b32_e32 v205, 0xffff0000, v110
	v_lshlrev_b32_e32 v206, 16, v111
	v_and_b32_e32 v207, 0xffff0000, v111
	v_mul_f32_e32 v200, v214, v200
	v_mul_f32_e32 v201, v214, v201
	v_mul_f32_e32 v202, v214, v202
	v_mul_f32_e32 v203, v214, v203
	v_mul_f32_e32 v204, v215, v204
	v_mul_f32_e32 v205, v215, v205
	v_mul_f32_e32 v206, v215, v206
	v_mul_f32_e32 v207, v215, v207
	v_fmac_f32_e32 v28, v156, v200
	v_fmac_f32_e32 v29, v157, v201
	v_fmac_f32_e32 v30, v158, v202
	v_fmac_f32_e32 v31, v159, v203
	v_fmac_f32_e32 v28, v188, v204
	v_fmac_f32_e32 v29, v189, v205
	v_fmac_f32_e32 v30, v190, v206
	v_fmac_f32_e32 v31, v191, v207
	global_store_dwordx4 v193, v[28:31], s[18:19] offset:3072
	s_add_u32 s18, s18, 0x2000
	s_addc_u32 s19, s19, 0
	global_load_dwordx4 v[0:3], v192, s[14:15] offset:0 nt
	global_load_dwordx4 v[4:7], v192, s[14:15] offset:1024 nt
	global_load_dwordx4 v[8:11], v192, s[14:15] offset:2048 nt
	global_load_dwordx4 v[12:15], v192, s[14:15] offset:3072 nt
	global_load_dwordx4 v[16:19], v193, s[14:15] offset:0 nt
	global_load_dwordx4 v[20:23], v193, s[14:15] offset:1024 nt
	global_load_dwordx4 v[24:27], v193, s[14:15] offset:2048 nt
	global_load_dwordx4 v[28:31], v193, s[14:15] offset:3072 nt
	global_load_dwordx2 v[64:65], v194, s[16:17] offset:0
	global_load_dwordx2 v[66:67], v194, s[16:17] offset:512
	global_load_dwordx2 v[68:69], v194, s[16:17] offset:1024
	global_load_dwordx2 v[70:71], v194, s[16:17] offset:1536
	global_load_dwordx2 v[72:73], v194, s[16:17] offset:2048
	global_load_dwordx2 v[74:75], v194, s[16:17] offset:2560
	global_load_dwordx2 v[76:77], v194, s[16:17] offset:3072
	global_load_dwordx2 v[78:79], v194, s[16:17] offset:3584
	global_load_dwordx2 v[96:97], v194, s[22:23] offset:0
	global_load_dwordx2 v[98:99], v194, s[22:23] offset:512
	global_load_dwordx2 v[100:101], v194, s[22:23] offset:1024
	global_load_dwordx2 v[102:103], v194, s[22:23] offset:1536
	global_load_dwordx2 v[104:105], v194, s[22:23] offset:2048
	global_load_dwordx2 v[106:107], v194, s[22:23] offset:2560
	global_load_dwordx2 v[108:109], v194, s[22:23] offset:3072
	global_load_dwordx2 v[110:111], v194, s[22:23] offset:3584
	s_add_u32 s14, s14, 0x2000
	s_addc_u32 s15, s15, 0
	s_add_u32 s16, s16, 0x1000
	s_addc_u32 s17, s17, 0
	s_add_u32 s22, s22, 0x1000
	s_addc_u32 s23, s23, 0
	s_waitcnt vmcnt(32)
	v_lshlrev_b32_e32 v200, 16, v80
	v_and_b32_e32 v201, 0xffff0000, v80
	v_lshlrev_b32_e32 v202, 16, v81
	v_and_b32_e32 v203, 0xffff0000, v81
	v_mul_f32_e32 v208, v200, v200
	v_mul_f32_e32 v209, v201, v201
	v_fmac_f32_e32 v208, v202, v202
	v_fmac_f32_e32 v209, v203, v203
	v_lshlrev_b32_e32 v204, 16, v112
	v_and_b32_e32 v205, 0xffff0000, v112
	v_lshlrev_b32_e32 v206, 16, v113
	v_and_b32_e32 v207, 0xffff0000, v113
	v_mul_f32_e32 v210, v204, v204
	v_mul_f32_e32 v211, v205, v205
	v_fmac_f32_e32 v210, v206, v206
	v_fmac_f32_e32 v211, v207, v207
	v_lshlrev_b32_e32 v200, 16, v82
	v_and_b32_e32 v201, 0xffff0000, v82
	v_lshlrev_b32_e32 v202, 16, v83
	v_and_b32_e32 v203, 0xffff0000, v83
	v_fmac_f32_e32 v208, v200, v200
	v_fmac_f32_e32 v209, v201, v201
	v_fmac_f32_e32 v208, v202, v202
	v_fmac_f32_e32 v209, v203, v203
	v_lshlrev_b32_e32 v204, 16, v114
	v_and_b32_e32 v205, 0xffff0000, v114
	v_lshlrev_b32_e32 v206, 16, v115
	v_and_b32_e32 v207, 0xffff0000, v115
	v_fmac_f32_e32 v210, v204, v204
	v_fmac_f32_e32 v211, v205, v205
	v_fmac_f32_e32 v210, v206, v206
	v_fmac_f32_e32 v211, v207, v207
	v_lshlrev_b32_e32 v200, 16, v84
	v_and_b32_e32 v201, 0xffff0000, v84
	v_lshlrev_b32_e32 v202, 16, v85
	v_and_b32_e32 v203, 0xffff0000, v85
	v_fmac_f32_e32 v208, v200, v200
	v_fmac_f32_e32 v209, v201, v201
	v_fmac_f32_e32 v208, v202, v202
	v_fmac_f32_e32 v209, v203, v203
	v_lshlrev_b32_e32 v204, 16, v116
	v_and_b32_e32 v205, 0xffff0000, v116
	v_lshlrev_b32_e32 v206, 16, v117
	v_and_b32_e32 v207, 0xffff0000, v117
	v_fmac_f32_e32 v210, v204, v204
	v_fmac_f32_e32 v211, v205, v205
	v_fmac_f32_e32 v210, v206, v206
	v_fmac_f32_e32 v211, v207, v207
	v_lshlrev_b32_e32 v200, 16, v86
	v_and_b32_e32 v201, 0xffff0000, v86
	v_lshlrev_b32_e32 v202, 16, v87
	v_and_b32_e32 v203, 0xffff0000, v87
	v_fmac_f32_e32 v208, v200, v200
	v_fmac_f32_e32 v209, v201, v201
	v_fmac_f32_e32 v208, v202, v202
	v_fmac_f32_e32 v209, v203, v203
	v_lshlrev_b32_e32 v204, 16, v118
	v_and_b32_e32 v205, 0xffff0000, v118
	v_lshlrev_b32_e32 v206, 16, v119
	v_and_b32_e32 v207, 0xffff0000, v119
	v_fmac_f32_e32 v210, v204, v204
; __device__ __forceinline__ float bf_lo(unsigned w) { return __uint_as_float(w << 16); }
; __device__ __forceinline__ float bf_hi(unsigned w) { return __uint_as_float(w & 0xffff0000u); }
; __global__ void __launch_bounds__(NWAVES * 64, 2) mk_fwd(Args args) {
;     ...
;                 float sy = 0.f;
; #pragma unroll
;                 for (int j = 0; j < 8; ++j) { const float a = bf_lo(yw[q][j].x), b = bf_hi(yw[q][j].x), c2 = bf_lo(yw[q][j].y), d = bf_hi(yw[q][j].y); sy += (a * a + b * b) + (c2 * c2 + d * d); }
;                 const float rsy = __builtin_amdgcn_rsqf(wave_sum(sy) * (1.f / DM) + EPS);
; #pragma unroll
;                 for (int j = 0; j < 8; ++j) { const int col = 4 * F.lane + 256 * j;
;                     const f32x4 y4 = (f32x4){bf_lo(yw[q][j].x), bf_hi(yw[q][j].x), bf_lo(yw[q][j].y), bf_hi(yw[q][j].y)};
;                     *(f32x4*)(args.out + (size_t)row * DM + col) = v[q][j] + PA[j] * (y4 * rsy); }
	v_fmac_f32_e32 v211, v205, v205
	v_fmac_f32_e32 v210, v206, v206
	v_fmac_f32_e32 v211, v207, v207
	v_lshlrev_b32_e32 v200, 16, v88
	v_and_b32_e32 v201, 0xffff0000, v88
	v_lshlrev_b32_e32 v202, 16, v89
	v_and_b32_e32 v203, 0xffff0000, v89
	v_fmac_f32_e32 v208, v200, v200
	v_fmac_f32_e32 v209, v201, v201
	v_fmac_f32_e32 v208, v202, v202
	v_fmac_f32_e32 v209, v203, v203
	v_lshlrev_b32_e32 v204, 16, v120
	v_and_b32_e32 v205, 0xffff0000, v120
	v_lshlrev_b32_e32 v206, 16, v121
	v_and_b32_e32 v207, 0xffff0000, v121
	v_fmac_f32_e32 v210, v204, v204
	v_fmac_f32_e32 v211, v205, v205
	v_fmac_f32_e32 v210, v206, v206
	v_fmac_f32_e32 v211, v207, v207
	v_lshlrev_b32_e32 v200, 16, v90
	v_and_b32_e32 v201, 0xffff0000, v90
	v_lshlrev_b32_e32 v202, 16, v91
	v_and_b32_e32 v203, 0xffff0000, v91
	v_fmac_f32_e32 v208, v200, v200
	v_fmac_f32_e32 v209, v201, v201
	v_fmac_f32_e32 v208, v202, v202
	v_fmac_f32_e32 v209, v203, v203
	v_lshlrev_b32_e32 v204, 16, v122
	v_and_b32_e32 v205, 0xffff0000, v122
	v_lshlrev_b32_e32 v206, 16, v123
	v_and_b32_e32 v207, 0xffff0000, v123
	v_fmac_f32_e32 v210, v204, v204
	v_fmac_f32_e32 v211, v205, v205
	v_fmac_f32_e32 v210, v206, v206
	v_fmac_f32_e32 v211, v207, v207
	v_lshlrev_b32_e32 v200, 16, v92
	v_and_b32_e32 v201, 0xffff0000, v92
	v_lshlrev_b32_e32 v202, 16, v93
	v_and_b32_e32 v203, 0xffff0000, v93
	v_fmac_f32_e32 v208, v200, v200
	v_fmac_f32_e32 v209, v201, v201
	v_fmac_f32_e32 v208, v202, v202
	v_fmac_f32_e32 v209, v203, v203
	v_lshlrev_b32_e32 v204, 16, v124
	v_and_b32_e32 v205, 0xffff0000, v124
	v_lshlrev_b32_e32 v206, 16, v125
	v_and_b32_e32 v207, 0xffff0000, v125
	v_fmac_f32_e32 v210, v204, v204
	v_fmac_f32_e32 v211, v205, v205
	v_fmac_f32_e32 v210, v206, v206
	v_fmac_f32_e32 v211, v207, v207
	v_lshlrev_b32_e32 v200, 16, v94
	v_and_b32_e32 v201, 0xffff0000, v94
	v_lshlrev_b32_e32 v202, 16, v95
	v_and_b32_e32 v203, 0xffff0000, v95
	v_fmac_f32_e32 v208, v200, v200
	v_fmac_f32_e32 v209, v201, v201
	v_fmac_f32_e32 v208, v202, v202
	v_fmac_f32_e32 v209, v203, v203
	v_lshlrev_b32_e32 v204, 16, v126
	v_and_b32_e32 v205, 0xffff0000, v126
	v_lshlrev_b32_e32 v206, 16, v127
	v_and_b32_e32 v207, 0xffff0000, v127
	v_fmac_f32_e32 v210, v204, v204
	v_fmac_f32_e32 v211, v205, v205
	v_fmac_f32_e32 v210, v206, v206
	v_fmac_f32_e32 v211, v207, v207
	v_add_f32_e32 v208, v208, v209
	v_add_f32_e32 v210, v210, v211
	s_nop 0
	v_add_f32_dpp v212, v208, v208 quad_perm:[1,0,3,2] row_mask:0xf bank_mask:0xf
	v_add_f32_dpp v213, v210, v210 quad_perm:[1,0,3,2] row_mask:0xf bank_mask:0xf
	s_nop 0
	v_add_f32_dpp v212, v212, v212 quad_perm:[2,3,0,1] row_mask:0xf bank_mask:0xf
	v_add_f32_dpp v213, v213, v213 quad_perm:[2,3,0,1] row_mask:0xf bank_mask:0xf
	s_nop 0
	v_add_f32_dpp v212, v212, v212 row_half_mirror row_mask:0xf bank_mask:0xf
	v_add_f32_dpp v213, v213, v213 row_half_mirror row_mask:0xf bank_mask:0xf
	s_nop 0
	v_add_f32_dpp v212, v212, v212 row_mirror row_mask:0xf bank_mask:0xf
	v_add_f32_dpp v213, v213, v213 row_mirror row_mask:0xf bank_mask:0xf
	s_nop 0
	v_readlane_b32 s4, v212, 0
	v_readlane_b32 s5, v212, 16
	v_readlane_b32 s6, v212, 32
	v_readlane_b32 s7, v212, 48
	v_readlane_b32 s24, v213, 0
	v_readlane_b32 s25, v213, 16
	v_readlane_b32 s26, v213, 32
	v_readlane_b32 s27, v213, 48
	s_nop 1
	v_mov_b32_e32 v214, s4
	v_mov_b32_e32 v215, s24
	v_add_f32_e32 v214, s5, v214
	v_add_f32_e32 v215, s25, v215
	v_add_f32_e32 v214, s6, v214
	v_add_f32_e32 v215, s26, v215
	v_add_f32_e32 v214, s7, v214
	v_add_f32_e32 v215, s27, v215
	v_fmamk_f32 v214, v214, 0x3a000000, v195
	v_fmamk_f32 v215, v215, 0x3a000000, v195
	v_rsq_f32_e32 v214, v214
	v_rsq_f32_e32 v215, v215
	s_nop 0
	v_lshlrev_b32_e32 v200, 16, v80
	v_and_b32_e32 v201, 0xffff0000, v80
	v_lshlrev_b32_e32 v202, 16, v81
	v_and_b32_e32 v203, 0xffff0000, v81
	v_lshlrev_b32_e32 v204, 16, v112
	v_and_b32_e32 v205, 0xffff0000, v112
	v_lshlrev_b32_e32 v206, 16, v113
	v_and_b32_e32 v207, 0xffff0000, v113
	v_mul_f32_e32 v200, v214, v200
	v_mul_f32_e32 v201, v214, v201
	v_mul_f32_e32 v202, v214, v202
	v_mul_f32_e32 v203, v214, v203
	v_mul_f32_e32 v204, v215, v204
	v_mul_f32_e32 v205, v215, v205
	v_mul_f32_e32 v206, v215, v206
	v_mul_f32_e32 v207, v215, v207
	v_fmac_f32_e32 v32, v128, v200
	v_fmac_f32_e32 v33, v129, v201
	v_fmac_f32_e32 v34, v130, v202
	v_fmac_f32_e32 v35, v131, v203
	v_fmac_f32_e32 v32, v160, v204
	v_fmac_f32_e32 v33, v161, v205
	v_fmac_f32_e32 v34, v162, v206
	v_fmac_f32_e32 v35, v163, v207
	global_store_dwordx4 v192, v[32:35], s[18:19] offset:0
	v_lshlrev_b32_e32 v200, 16, v82
	v_and_b32_e32 v201, 0xffff0000, v82
	v_lshlrev_b32_e32 v202, 16, v83
	v_and_b32_e32 v203, 0xffff0000, v83
	v_lshlrev_b32_e32 v204, 16, v114
	v_and_b32_e32 v205, 0xffff0000, v114
	v_lshlrev_b32_e32 v206, 16, v115
	v_and_b32_e32 v207, 0xffff0000, v115
	v_mul_f32_e32 v200, v214, v200
	v_mul_f32_e32 v201, v214, v201
	v_mul_f32_e32 v202, v214, v202
	v_mul_f32_e32 v203, v214, v203
	v_mul_f32_e32 v204, v215, v204
	v_mul_f32_e32 v205, v215, v205
	v_mul_f32_e32 v206, v215, v206
	v_mul_f32_e32 v207, v215, v207
	v_fmac_f32_e32 v36, v132, v200
	v_fmac_f32_e32 v37, v133, v201
	v_fmac_f32_e32 v38, v134, v202
	v_fmac_f32_e32 v39, v135, v203
	v_fmac_f32_e32 v36, v164, v204
	v_fmac_f32_e32 v37, v165, v205
	v_fmac_f32_e32 v38, v166, v206
	v_fmac_f32_e32 v39, v167, v207
	global_store_dwordx4 v192, v[36:39], s[18:19] offset:1024
	v_lshlrev_b32_e32 v200, 16, v84
	v_and_b32_e32 v201, 0xffff0000, v84
	v_lshlrev_b32_e32 v202, 16, v85
	v_and_b32_e32 v203, 0xffff0000, v85
	v_lshlrev_b32_e32 v204, 16, v116
	v_and_b32_e32 v205, 0xffff0000, v116
	v_lshlrev_b32_e32 v206, 16, v117
	v_and_b32_e32 v207, 0xffff0000, v117
	v_mul_f32_e32 v200, v214, v200
; __device__ __forceinline__ float bf_lo(unsigned w) { return __uint_as_float(w << 16); }
; __device__ __forceinline__ float bf_hi(unsigned w) { return __uint_as_float(w & 0xffff0000u); }
; __global__ void __launch_bounds__(NWAVES * 64, 2) mk_fwd(Args args) {
;     ...
;         for (int row0 = rbeg; row0 < rbeg + per2 && row0 < ML; row0 += 2) {
;             f32x4 v[2][8]; u32x2 yw[2][8];
; #pragma unroll
;             for (int q = 0; q < 2; ++q) { const int row = row0 + q; load_row_f32(args.out + (size_t)row * DM, F.lane, v[q]);
;                 const bf16_t* yr = Y + (size_t)row * DM;
; #pragma unroll
;                 for (int j = 0; j < 8; ++j) yw[q][j] = *(const u32x2*)(yr + 4 * F.lane + 256 * j); }
; #pragma unroll
;             for (int q = 0; q < 2; ++q) { const int row = row0 + q; const int r = row / SEQ;
;                 if (r != rcur) { const float* m1 = mod + (size_t)(9 + r) * 6144; rcur = r;
; #pragma unroll
;                     for (int j = 0; j < 8; ++j) { const int col = 4 * F.lane + 256 * j; PA[j] = *(const f32x4*)(m1 + 2 * DM + col) * *(const f32x4*)(post_norm + DM + col); } }
;                 float sy = 0.f;
; #pragma unroll
;                 for (int j = 0; j < 8; ++j) { const float a = bf_lo(yw[q][j].x), b = bf_hi(yw[q][j].x), c2 = bf_lo(yw[q][j].y), d = bf_hi(yw[q][j].y); sy += (a * a + b * b) + (c2 * c2 + d * d); }
;                 const float rsy = __builtin_amdgcn_rsqf(wave_sum(sy) * (1.f / DM) + EPS);
; #pragma unroll
;                 for (int j = 0; j < 8; ++j) { const int col = 4 * F.lane + 256 * j;
;                     const f32x4 y4 = (f32x4){bf_lo(yw[q][j].x), bf_hi(yw[q][j].x), bf_lo(yw[q][j].y), bf_hi(yw[q][j].y)};
;                     *(f32x4*)(args.out + (size_t)row * DM + col) = v[q][j] + PA[j] * (y4 * rsy); }
	v_mul_f32_e32 v201, v214, v201
	v_mul_f32_e32 v202, v214, v202
	v_mul_f32_e32 v203, v214, v203
	v_mul_f32_e32 v204, v215, v204
	v_mul_f32_e32 v205, v215, v205
	v_mul_f32_e32 v206, v215, v206
	v_mul_f32_e32 v207, v215, v207
	v_fmac_f32_e32 v40, v136, v200
	v_fmac_f32_e32 v41, v137, v201
	v_fmac_f32_e32 v42, v138, v202
	v_fmac_f32_e32 v43, v139, v203
	v_fmac_f32_e32 v40, v168, v204
	v_fmac_f32_e32 v41, v169, v205
	v_fmac_f32_e32 v42, v170, v206
	v_fmac_f32_e32 v43, v171, v207
	global_store_dwordx4 v192, v[40:43], s[18:19] offset:2048
	v_lshlrev_b32_e32 v200, 16, v86
	v_and_b32_e32 v201, 0xffff0000, v86
	v_lshlrev_b32_e32 v202, 16, v87
	v_and_b32_e32 v203, 0xffff0000, v87
	v_lshlrev_b32_e32 v204, 16, v118
	v_and_b32_e32 v205, 0xffff0000, v118
	v_lshlrev_b32_e32 v206, 16, v119
	v_and_b32_e32 v207, 0xffff0000, v119
	v_mul_f32_e32 v200, v214, v200
	v_mul_f32_e32 v201, v214, v201
	v_mul_f32_e32 v202, v214, v202
	v_mul_f32_e32 v203, v214, v203
	v_mul_f32_e32 v204, v215, v204
	v_mul_f32_e32 v205, v215, v205
	v_mul_f32_e32 v206, v215, v206
	v_mul_f32_e32 v207, v215, v207
	v_fmac_f32_e32 v44, v140, v200
	v_fmac_f32_e32 v45, v141, v201
	v_fmac_f32_e32 v46, v142, v202
	v_fmac_f32_e32 v47, v143, v203
	v_fmac_f32_e32 v44, v172, v204
	v_fmac_f32_e32 v45, v173, v205
	v_fmac_f32_e32 v46, v174, v206
	v_fmac_f32_e32 v47, v175, v207
	global_store_dwordx4 v192, v[44:47], s[18:19] offset:3072
	v_lshlrev_b32_e32 v200, 16, v88
	v_and_b32_e32 v201, 0xffff0000, v88
	v_lshlrev_b32_e32 v202, 16, v89
	v_and_b32_e32 v203, 0xffff0000, v89
	v_lshlrev_b32_e32 v204, 16, v120
	v_and_b32_e32 v205, 0xffff0000, v120
	v_lshlrev_b32_e32 v206, 16, v121
	v_and_b32_e32 v207, 0xffff0000, v121
	v_mul_f32_e32 v200, v214, v200
	v_mul_f32_e32 v201, v214, v201
	v_mul_f32_e32 v202, v214, v202
	v_mul_f32_e32 v203, v214, v203
	v_mul_f32_e32 v204, v215, v204
	v_mul_f32_e32 v205, v215, v205
	v_mul_f32_e32 v206, v215, v206
	v_mul_f32_e32 v207, v215, v207
	v_fmac_f32_e32 v48, v144, v200
	v_fmac_f32_e32 v49, v145, v201
	v_fmac_f32_e32 v50, v146, v202
	v_fmac_f32_e32 v51, v147, v203
	v_fmac_f32_e32 v48, v176, v204
	v_fmac_f32_e32 v49, v177, v205
	v_fmac_f32_e32 v50, v178, v206
	v_fmac_f32_e32 v51, v179, v207
	global_store_dwordx4 v193, v[48:51], s[18:19] offset:0
	v_lshlrev_b32_e32 v200, 16, v90
	v_and_b32_e32 v201, 0xffff0000, v90
	v_lshlrev_b32_e32 v202, 16, v91
	v_and_b32_e32 v203, 0xffff0000, v91
	v_lshlrev_b32_e32 v204, 16, v122
	v_and_b32_e32 v205, 0xffff0000, v122
	v_lshlrev_b32_e32 v206, 16, v123
	v_and_b32_e32 v207, 0xffff0000, v123
	v_mul_f32_e32 v200, v214, v200
	v_mul_f32_e32 v201, v214, v201
	v_mul_f32_e32 v202, v214, v202
	v_mul_f32_e32 v203, v214, v203
	v_mul_f32_e32 v204, v215, v204
	v_mul_f32_e32 v205, v215, v205
	v_mul_f32_e32 v206, v215, v206
	v_mul_f32_e32 v207, v215, v207
	v_fmac_f32_e32 v52, v148, v200
	v_fmac_f32_e32 v53, v149, v201
	v_fmac_f32_e32 v54, v150, v202
	v_fmac_f32_e32 v55, v151, v203
	v_fmac_f32_e32 v52, v180, v204
	v_fmac_f32_e32 v53, v181, v205
	v_fmac_f32_e32 v54, v182, v206
	v_fmac_f32_e32 v55, v183, v207
	global_store_dwordx4 v193, v[52:55], s[18:19] offset:1024
	v_lshlrev_b32_e32 v200, 16, v92
	v_and_b32_e32 v201, 0xffff0000, v92
	v_lshlrev_b32_e32 v202, 16, v93
	v_and_b32_e32 v203, 0xffff0000, v93
	v_lshlrev_b32_e32 v204, 16, v124
	v_and_b32_e32 v205, 0xffff0000, v124
	v_lshlrev_b32_e32 v206, 16, v125
	v_and_b32_e32 v207, 0xffff0000, v125
	v_mul_f32_e32 v200, v214, v200
	v_mul_f32_e32 v201, v214, v201
	v_mul_f32_e32 v202, v214, v202
	v_mul_f32_e32 v203, v214, v203
	v_mul_f32_e32 v204, v215, v204
	v_mul_f32_e32 v205, v215, v205
	v_mul_f32_e32 v206, v215, v206
	v_mul_f32_e32 v207, v215, v207
	v_fmac_f32_e32 v56, v152, v200
	v_fmac_f32_e32 v57, v153, v201
	v_fmac_f32_e32 v58, v154, v202
	v_fmac_f32_e32 v59, v155, v203
	v_fmac_f32_e32 v56, v184, v204
	v_fmac_f32_e32 v57, v185, v205
	v_fmac_f32_e32 v58, v186, v206
	v_fmac_f32_e32 v59, v187, v207
	global_store_dwordx4 v193, v[56:59], s[18:19] offset:2048
	v_lshlrev_b32_e32 v200, 16, v94
	v_and_b32_e32 v201, 0xffff0000, v94
	v_lshlrev_b32_e32 v202, 16, v95
	v_and_b32_e32 v203, 0xffff0000, v95
	v_lshlrev_b32_e32 v204, 16, v126
	v_and_b32_e32 v205, 0xffff0000, v126
	v_lshlrev_b32_e32 v206, 16, v127
	v_and_b32_e32 v207, 0xffff0000, v127
	v_mul_f32_e32 v200, v214, v200
	v_mul_f32_e32 v201, v214, v201
	v_mul_f32_e32 v202, v214, v202
	v_mul_f32_e32 v203, v214, v203
	v_mul_f32_e32 v204, v215, v204
	v_mul_f32_e32 v205, v215, v205
	v_mul_f32_e32 v206, v215, v206
	v_mul_f32_e32 v207, v215, v207
	v_fmac_f32_e32 v60, v156, v200
	v_fmac_f32_e32 v61, v157, v201
	v_fmac_f32_e32 v62, v158, v202
	v_fmac_f32_e32 v63, v159, v203
	v_fmac_f32_e32 v60, v188, v204
	v_fmac_f32_e32 v61, v189, v205
	v_fmac_f32_e32 v62, v190, v206
	v_fmac_f32_e32 v63, v191, v207
	global_store_dwordx4 v193, v[60:63], s[18:19] offset:3072
	s_add_u32 s18, s18, 0x2000
	s_addc_u32 s19, s19, 0
	global_load_dwordx4 v[32:35], v192, s[14:15] offset:0 nt
	global_load_dwordx4 v[36:39], v192, s[14:15] offset:1024 nt
	global_load_dwordx4 v[40:43], v192, s[14:15] offset:2048 nt
	global_load_dwordx4 v[44:47], v192, s[14:15] offset:3072 nt
	global_load_dwordx4 v[48:51], v193, s[14:15] offset:0 nt
	global_load_dwordx4 v[52:55], v193, s[14:15] offset:1024 nt
	global_load_dwordx4 v[56:59], v193, s[14:15] offset:2048 nt
	global_load_dwordx4 v[60:63], v193, s[14:15] offset:3072 nt
	global_load_dwordx2 v[80:81], v194, s[16:17] offset:0
	global_load_dwordx2 v[82:83], v194, s[16:17] offset:512
	global_load_dwordx2 v[84:85], v194, s[16:17] offset:1024
	global_load_dwordx2 v[86:87], v194, s[16:17] offset:1536
	global_load_dwordx2 v[88:89], v194, s[16:17] offset:2048
	global_load_dwordx2 v[90:91], v194, s[16:17] offset:2560
	global_load_dwordx2 v[92:93], v194, s[16:17] offset:3072
	global_load_dwordx2 v[94:95], v194, s[16:17] offset:3584
	global_load_dwordx2 v[112:113], v194, s[22:23] offset:0
	global_load_dwordx2 v[114:115], v194, s[22:23] offset:512
	global_load_dwordx2 v[116:117], v194, s[22:23] offset:1024
	global_load_dwordx2 v[118:119], v194, s[22:23] offset:1536
	global_load_dwordx2 v[120:121], v194, s[22:23] offset:2048
	global_load_dwordx2 v[122:123], v194, s[22:23] offset:2560
	global_load_dwordx2 v[124:125], v194, s[22:23] offset:3072
	global_load_dwordx2 v[126:127], v194, s[22:23] offset:3584
	s_add_u32 s14, s14, 0x2000
	s_addc_u32 s15, s15, 0
	s_add_u32 s16, s16, 0x1000
	s_addc_u32 s17, s17, 0
	s_add_u32 s22, s22, 0x1000
	s_addc_u32 s23, s23, 0
	s_waitcnt vmcnt(32)
; __device__ __forceinline__ float bf_lo(unsigned w) { return __uint_as_float(w << 16); }
; __device__ __forceinline__ float bf_hi(unsigned w) { return __uint_as_float(w & 0xffff0000u); }
; __global__ void __launch_bounds__(NWAVES * 64, 2) mk_fwd(Args args) {
;     ...
;                 float sy = 0.f;
; #pragma unroll
;                 for (int j = 0; j < 8; ++j) { const float a = bf_lo(yw[q][j].x), b = bf_hi(yw[q][j].x), c2 = bf_lo(yw[q][j].y), d = bf_hi(yw[q][j].y); sy += (a * a + b * b) + (c2 * c2 + d * d); }
;                 const float rsy = __builtin_amdgcn_rsqf(wave_sum(sy) * (1.f / DM) + EPS);
	v_lshlrev_b32_e32 v200, 16, v64
	v_and_b32_e32 v201, 0xffff0000, v64
	v_lshlrev_b32_e32 v202, 16, v65
	v_and_b32_e32 v203, 0xffff0000, v65
	v_mul_f32_e32 v208, v200, v200
	v_mul_f32_e32 v209, v201, v201
	v_fmac_f32_e32 v208, v202, v202
	v_fmac_f32_e32 v209, v203, v203
	v_lshlrev_b32_e32 v204, 16, v96
	v_and_b32_e32 v205, 0xffff0000, v96
	v_lshlrev_b32_e32 v206, 16, v97
	v_and_b32_e32 v207, 0xffff0000, v97
	v_mul_f32_e32 v210, v204, v204
	v_mul_f32_e32 v211, v205, v205
	v_fmac_f32_e32 v210, v206, v206
	v_fmac_f32_e32 v211, v207, v207
	v_lshlrev_b32_e32 v200, 16, v66
	v_and_b32_e32 v201, 0xffff0000, v66
	v_lshlrev_b32_e32 v202, 16, v67
	v_and_b32_e32 v203, 0xffff0000, v67
	v_fmac_f32_e32 v208, v200, v200
	v_fmac_f32_e32 v209, v201, v201
	v_fmac_f32_e32 v208, v202, v202
	v_fmac_f32_e32 v209, v203, v203
	v_lshlrev_b32_e32 v204, 16, v98
	v_and_b32_e32 v205, 0xffff0000, v98
	v_lshlrev_b32_e32 v206, 16, v99
	v_and_b32_e32 v207, 0xffff0000, v99
	v_fmac_f32_e32 v210, v204, v204
	v_fmac_f32_e32 v211, v205, v205
	v_fmac_f32_e32 v210, v206, v206
	v_fmac_f32_e32 v211, v207, v207
	v_lshlrev_b32_e32 v200, 16, v68
	v_and_b32_e32 v201, 0xffff0000, v68
	v_lshlrev_b32_e32 v202, 16, v69
	v_and_b32_e32 v203, 0xffff0000, v69
	v_fmac_f32_e32 v208, v200, v200
	v_fmac_f32_e32 v209, v201, v201
	v_fmac_f32_e32 v208, v202, v202
	v_fmac_f32_e32 v209, v203, v203
	v_lshlrev_b32_e32 v204, 16, v100
	v_and_b32_e32 v205, 0xffff0000, v100
	v_lshlrev_b32_e32 v206, 16, v101
	v_and_b32_e32 v207, 0xffff0000, v101
	v_fmac_f32_e32 v210, v204, v204
	v_fmac_f32_e32 v211, v205, v205
	v_fmac_f32_e32 v210, v206, v206
	v_fmac_f32_e32 v211, v207, v207
	v_lshlrev_b32_e32 v200, 16, v70
	v_and_b32_e32 v201, 0xffff0000, v70
	v_lshlrev_b32_e32 v202, 16, v71
	v_and_b32_e32 v203, 0xffff0000, v71
	v_fmac_f32_e32 v208, v200, v200
	v_fmac_f32_e32 v209, v201, v201
	v_fmac_f32_e32 v208, v202, v202
	v_fmac_f32_e32 v209, v203, v203
	v_lshlrev_b32_e32 v204, 16, v102
	v_and_b32_e32 v205, 0xffff0000, v102
	v_lshlrev_b32_e32 v206, 16, v103
	v_and_b32_e32 v207, 0xffff0000, v103
	v_fmac_f32_e32 v210, v204, v204
	v_fmac_f32_e32 v211, v205, v205
	v_fmac_f32_e32 v210, v206, v206
	v_fmac_f32_e32 v211, v207, v207
	v_lshlrev_b32_e32 v200, 16, v72
	v_and_b32_e32 v201, 0xffff0000, v72
	v_lshlrev_b32_e32 v202, 16, v73
	v_and_b32_e32 v203, 0xffff0000, v73
	v_fmac_f32_e32 v208, v200, v200
	v_fmac_f32_e32 v209, v201, v201
	v_fmac_f32_e32 v208, v202, v202
	v_fmac_f32_e32 v209, v203, v203
	v_lshlrev_b32_e32 v204, 16, v104
	v_and_b32_e32 v205, 0xffff0000, v104
	v_lshlrev_b32_e32 v206, 16, v105
	v_and_b32_e32 v207, 0xffff0000, v105
	v_fmac_f32_e32 v210, v204, v204
	v_fmac_f32_e32 v211, v205, v205
	v_fmac_f32_e32 v210, v206, v206
	v_fmac_f32_e32 v211, v207, v207
	v_lshlrev_b32_e32 v200, 16, v74
	v_and_b32_e32 v201, 0xffff0000, v74
	v_lshlrev_b32_e32 v202, 16, v75
	v_and_b32_e32 v203, 0xffff0000, v75
	v_fmac_f32_e32 v208, v200, v200
	v_fmac_f32_e32 v209, v201, v201
	v_fmac_f32_e32 v208, v202, v202
	v_fmac_f32_e32 v209, v203, v203
	v_lshlrev_b32_e32 v204, 16, v106
	v_and_b32_e32 v205, 0xffff0000, v106
	v_lshlrev_b32_e32 v206, 16, v107
	v_and_b32_e32 v207, 0xffff0000, v107
	v_fmac_f32_e32 v210, v204, v204
	v_fmac_f32_e32 v211, v205, v205
	v_fmac_f32_e32 v210, v206, v206
	v_fmac_f32_e32 v211, v207, v207
	v_lshlrev_b32_e32 v200, 16, v76
	v_and_b32_e32 v201, 0xffff0000, v76
	v_lshlrev_b32_e32 v202, 16, v77
	v_and_b32_e32 v203, 0xffff0000, v77
	v_fmac_f32_e32 v208, v200, v200
	v_fmac_f32_e32 v209, v201, v201
	v_fmac_f32_e32 v208, v202, v202
	v_fmac_f32_e32 v209, v203, v203
	v_lshlrev_b32_e32 v204, 16, v108
	v_and_b32_e32 v205, 0xffff0000, v108
	v_lshlrev_b32_e32 v206, 16, v109
	v_and_b32_e32 v207, 0xffff0000, v109
	v_fmac_f32_e32 v210, v204, v204
	v_fmac_f32_e32 v211, v205, v205
	v_fmac_f32_e32 v210, v206, v206
	v_fmac_f32_e32 v211, v207, v207
	v_lshlrev_b32_e32 v200, 16, v78
	v_and_b32_e32 v201, 0xffff0000, v78
	v_lshlrev_b32_e32 v202, 16, v79
	v_and_b32_e32 v203, 0xffff0000, v79
	v_fmac_f32_e32 v208, v200, v200
	v_fmac_f32_e32 v209, v201, v201
	v_fmac_f32_e32 v208, v202, v202
	v_fmac_f32_e32 v209, v203, v203
	v_lshlrev_b32_e32 v204, 16, v110
	v_and_b32_e32 v205, 0xffff0000, v110
	v_lshlrev_b32_e32 v206, 16, v111
	v_and_b32_e32 v207, 0xffff0000, v111
	v_fmac_f32_e32 v210, v204, v204
	v_fmac_f32_e32 v211, v205, v205
	v_fmac_f32_e32 v210, v206, v206
	v_fmac_f32_e32 v211, v207, v207
	v_add_f32_e32 v208, v208, v209
	v_add_f32_e32 v210, v210, v211
	s_nop 0
	v_add_f32_dpp v212, v208, v208 quad_perm:[1,0,3,2] row_mask:0xf bank_mask:0xf
	v_add_f32_dpp v213, v210, v210 quad_perm:[1,0,3,2] row_mask:0xf bank_mask:0xf
	s_nop 0
	v_add_f32_dpp v212, v212, v212 quad_perm:[2,3,0,1] row_mask:0xf bank_mask:0xf
	v_add_f32_dpp v213, v213, v213 quad_perm:[2,3,0,1] row_mask:0xf bank_mask:0xf
	s_nop 0
	v_add_f32_dpp v212, v212, v212 row_half_mirror row_mask:0xf bank_mask:0xf
	v_add_f32_dpp v213, v213, v213 row_half_mirror row_mask:0xf bank_mask:0xf
	s_nop 0
	v_add_f32_dpp v212, v212, v212 row_mirror row_mask:0xf bank_mask:0xf
	v_add_f32_dpp v213, v213, v213 row_mirror row_mask:0xf bank_mask:0xf
	s_nop 0
	v_readlane_b32 s4, v212, 0
	v_readlane_b32 s5, v212, 16
	v_readlane_b32 s6, v212, 32
	v_readlane_b32 s7, v212, 48
	v_readlane_b32 s24, v213, 0
	v_readlane_b32 s25, v213, 16
	v_readlane_b32 s26, v213, 32
	v_readlane_b32 s27, v213, 48
	s_nop 1
	v_mov_b32_e32 v214, s4
	v_mov_b32_e32 v215, s24
	v_add_f32_e32 v214, s5, v214
	v_add_f32_e32 v215, s25, v215
	v_add_f32_e32 v214, s6, v214
	v_add_f32_e32 v215, s26, v215
	v_add_f32_e32 v214, s7, v214
	v_add_f32_e32 v215, s27, v215
	v_fmamk_f32 v214, v214, 0x3a000000, v195
	v_fmamk_f32 v215, v215, 0x3a000000, v195
; __device__ __forceinline__ float bf_lo(unsigned w) { return __uint_as_float(w << 16); }
; __device__ __forceinline__ float bf_hi(unsigned w) { return __uint_as_float(w & 0xffff0000u); }
; __global__ void __launch_bounds__(NWAVES * 64, 2) mk_fwd(Args args) {
;     ...
;                 const float rsy = __builtin_amdgcn_rsqf(wave_sum(sy) * (1.f / DM) + EPS);
; #pragma unroll
;                 for (int j = 0; j < 8; ++j) { const int col = 4 * F.lane + 256 * j;
;                     const f32x4 y4 = (f32x4){bf_lo(yw[q][j].x), bf_hi(yw[q][j].x), bf_lo(yw[q][j].y), bf_hi(yw[q][j].y)};
;                     *(f32x4*)(args.out + (size_t)row * DM + col) = v[q][j] + PA[j] * (y4 * rsy); }
	v_rsq_f32_e32 v214, v214
	v_rsq_f32_e32 v215, v215
	s_nop 0
	v_lshlrev_b32_e32 v200, 16, v64
	v_and_b32_e32 v201, 0xffff0000, v64
	v_lshlrev_b32_e32 v202, 16, v65
	v_and_b32_e32 v203, 0xffff0000, v65
	v_lshlrev_b32_e32 v204, 16, v96
	v_and_b32_e32 v205, 0xffff0000, v96
	v_lshlrev_b32_e32 v206, 16, v97
	v_and_b32_e32 v207, 0xffff0000, v97
	v_mul_f32_e32 v200, v214, v200
	v_mul_f32_e32 v201, v214, v201
	v_mul_f32_e32 v202, v214, v202
	v_mul_f32_e32 v203, v214, v203
	v_mul_f32_e32 v204, v215, v204
	v_mul_f32_e32 v205, v215, v205
	v_mul_f32_e32 v206, v215, v206
	v_mul_f32_e32 v207, v215, v207
	v_fmac_f32_e32 v0, v128, v200
	v_fmac_f32_e32 v1, v129, v201
	v_fmac_f32_e32 v2, v130, v202
	v_fmac_f32_e32 v3, v131, v203
	v_fmac_f32_e32 v0, v160, v204
	v_fmac_f32_e32 v1, v161, v205
	v_fmac_f32_e32 v2, v162, v206
	v_fmac_f32_e32 v3, v163, v207
	global_store_dwordx4 v192, v[0:3], s[18:19] offset:0
	v_lshlrev_b32_e32 v200, 16, v66
	v_and_b32_e32 v201, 0xffff0000, v66
	v_lshlrev_b32_e32 v202, 16, v67
	v_and_b32_e32 v203, 0xffff0000, v67
	v_lshlrev_b32_e32 v204, 16, v98
	v_and_b32_e32 v205, 0xffff0000, v98
	v_lshlrev_b32_e32 v206, 16, v99
	v_and_b32_e32 v207, 0xffff0000, v99
	v_mul_f32_e32 v200, v214, v200
	v_mul_f32_e32 v201, v214, v201
	v_mul_f32_e32 v202, v214, v202
	v_mul_f32_e32 v203, v214, v203
	v_mul_f32_e32 v204, v215, v204
	v_mul_f32_e32 v205, v215, v205
	v_mul_f32_e32 v206, v215, v206
	v_mul_f32_e32 v207, v215, v207
	v_fmac_f32_e32 v4, v132, v200
	v_fmac_f32_e32 v5, v133, v201
	v_fmac_f32_e32 v6, v134, v202
	v_fmac_f32_e32 v7, v135, v203
	v_fmac_f32_e32 v4, v164, v204
	v_fmac_f32_e32 v5, v165, v205
	v_fmac_f32_e32 v6, v166, v206
	v_fmac_f32_e32 v7, v167, v207
	global_store_dwordx4 v192, v[4:7], s[18:19] offset:1024
	v_lshlrev_b32_e32 v200, 16, v68
	v_and_b32_e32 v201, 0xffff0000, v68
	v_lshlrev_b32_e32 v202, 16, v69
	v_and_b32_e32 v203, 0xffff0000, v69
	v_lshlrev_b32_e32 v204, 16, v100
	v_and_b32_e32 v205, 0xffff0000, v100
	v_lshlrev_b32_e32 v206, 16, v101
	v_and_b32_e32 v207, 0xffff0000, v101
	v_mul_f32_e32 v200, v214, v200
	v_mul_f32_e32 v201, v214, v201
	v_mul_f32_e32 v202, v214, v202
	v_mul_f32_e32 v203, v214, v203
	v_mul_f32_e32 v204, v215, v204
	v_mul_f32_e32 v205, v215, v205
	v_mul_f32_e32 v206, v215, v206
	v_mul_f32_e32 v207, v215, v207
	v_fmac_f32_e32 v8, v136, v200
	v_fmac_f32_e32 v9, v137, v201
	v_fmac_f32_e32 v10, v138, v202
	v_fmac_f32_e32 v11, v139, v203
	v_fmac_f32_e32 v8, v168, v204
	v_fmac_f32_e32 v9, v169, v205
	v_fmac_f32_e32 v10, v170, v206
	v_fmac_f32_e32 v11, v171, v207
	global_store_dwordx4 v192, v[8:11], s[18:19] offset:2048
	v_lshlrev_b32_e32 v200, 16, v70
	v_and_b32_e32 v201, 0xffff0000, v70
	v_lshlrev_b32_e32 v202, 16, v71
	v_and_b32_e32 v203, 0xffff0000, v71
	v_lshlrev_b32_e32 v204, 16, v102
	v_and_b32_e32 v205, 0xffff0000, v102
	v_lshlrev_b32_e32 v206, 16, v103
	v_and_b32_e32 v207, 0xffff0000, v103
	v_mul_f32_e32 v200, v214, v200
	v_mul_f32_e32 v201, v214, v201
	v_mul_f32_e32 v202, v214, v202
	v_mul_f32_e32 v203, v214, v203
	v_mul_f32_e32 v204, v215, v204
	v_mul_f32_e32 v205, v215, v205
	v_mul_f32_e32 v206, v215, v206
	v_mul_f32_e32 v207, v215, v207
	v_fmac_f32_e32 v12, v140, v200
	v_fmac_f32_e32 v13, v141, v201
	v_fmac_f32_e32 v14, v142, v202
	v_fmac_f32_e32 v15, v143, v203
	v_fmac_f32_e32 v12, v172, v204
	v_fmac_f32_e32 v13, v173, v205
	v_fmac_f32_e32 v14, v174, v206
	v_fmac_f32_e32 v15, v175, v207
	global_store_dwordx4 v192, v[12:15], s[18:19] offset:3072
	v_lshlrev_b32_e32 v200, 16, v72
	v_and_b32_e32 v201, 0xffff0000, v72
	v_lshlrev_b32_e32 v202, 16, v73
	v_and_b32_e32 v203, 0xffff0000, v73
	v_lshlrev_b32_e32 v204, 16, v104
	v_and_b32_e32 v205, 0xffff0000, v104
	v_lshlrev_b32_e32 v206, 16, v105
	v_and_b32_e32 v207, 0xffff0000, v105
	v_mul_f32_e32 v200, v214, v200
	v_mul_f32_e32 v201, v214, v201
	v_mul_f32_e32 v202, v214, v202
	v_mul_f32_e32 v203, v214, v203
	v_mul_f32_e32 v204, v215, v204
	v_mul_f32_e32 v205, v215, v205
	v_mul_f32_e32 v206, v215, v206
	v_mul_f32_e32 v207, v215, v207
	v_fmac_f32_e32 v16, v144, v200
	v_fmac_f32_e32 v17, v145, v201
	v_fmac_f32_e32 v18, v146, v202
	v_fmac_f32_e32 v19, v147, v203
	v_fmac_f32_e32 v16, v176, v204
	v_fmac_f32_e32 v17, v177, v205
	v_fmac_f32_e32 v18, v178, v206
	v_fmac_f32_e32 v19, v179, v207
	global_store_dwordx4 v193, v[16:19], s[18:19] offset:0
	v_lshlrev_b32_e32 v200, 16, v74
	v_and_b32_e32 v201, 0xffff0000, v74
	v_lshlrev_b32_e32 v202, 16, v75
	v_and_b32_e32 v203, 0xffff0000, v75
	v_lshlrev_b32_e32 v204, 16, v106
	v_and_b32_e32 v205, 0xffff0000, v106
	v_lshlrev_b32_e32 v206, 16, v107
	v_and_b32_e32 v207, 0xffff0000, v107
	v_mul_f32_e32 v200, v214, v200
	v_mul_f32_e32 v201, v214, v201
	v_mul_f32_e32 v202, v214, v202
	v_mul_f32_e32 v203, v214, v203
	v_mul_f32_e32 v204, v215, v204
	v_mul_f32_e32 v205, v215, v205
	v_mul_f32_e32 v206, v215, v206
	v_mul_f32_e32 v207, v215, v207
	v_fmac_f32_e32 v20, v148, v200
	v_fmac_f32_e32 v21, v149, v201
	v_fmac_f32_e32 v22, v150, v202
	v_fmac_f32_e32 v23, v151, v203
	v_fmac_f32_e32 v20, v180, v204
	v_fmac_f32_e32 v21, v181, v205
	v_fmac_f32_e32 v22, v182, v206
	v_fmac_f32_e32 v23, v183, v207
	global_store_dwordx4 v193, v[20:23], s[18:19] offset:1024
	v_lshlrev_b32_e32 v200, 16, v76
	v_and_b32_e32 v201, 0xffff0000, v76
	v_lshlrev_b32_e32 v202, 16, v77
	v_and_b32_e32 v203, 0xffff0000, v77
	v_lshlrev_b32_e32 v204, 16, v108
	v_and_b32_e32 v205, 0xffff0000, v108
	v_lshlrev_b32_e32 v206, 16, v109
	v_and_b32_e32 v207, 0xffff0000, v109
	v_mul_f32_e32 v200, v214, v200
	v_mul_f32_e32 v201, v214, v201
	v_mul_f32_e32 v202, v214, v202
	v_mul_f32_e32 v203, v214, v203
	v_mul_f32_e32 v204, v215, v204
	v_mul_f32_e32 v205, v215, v205
; __device__ __forceinline__ float bf_lo(unsigned w) { return __uint_as_float(w << 16); }
; __device__ __forceinline__ float bf_hi(unsigned w) { return __uint_as_float(w & 0xffff0000u); }
; __global__ void __launch_bounds__(NWAVES * 64, 2) mk_fwd(Args args) {
;     ...
;         for (int row0 = rbeg; row0 < rbeg + per2 && row0 < ML; row0 += 2) {
;             f32x4 v[2][8]; u32x2 yw[2][8];
; #pragma unroll
;             for (int q = 0; q < 2; ++q) { const int row = row0 + q; load_row_f32(args.out + (size_t)row * DM, F.lane, v[q]);
;                 const bf16_t* yr = Y + (size_t)row * DM;
; #pragma unroll
;                 for (int j = 0; j < 8; ++j) yw[q][j] = *(const u32x2*)(yr + 4 * F.lane + 256 * j); }
; #pragma unroll
;             for (int q = 0; q < 2; ++q) { const int row = row0 + q; const int r = row / SEQ;
;                 if (r != rcur) { const float* m1 = mod + (size_t)(9 + r) * 6144; rcur = r;
; #pragma unroll
;                     for (int j = 0; j < 8; ++j) { const int col = 4 * F.lane + 256 * j; PA[j] = *(const f32x4*)(m1 + 2 * DM + col) * *(const f32x4*)(post_norm + DM + col); } }
;                 float sy = 0.f;
; #pragma unroll
;                 for (int j = 0; j < 8; ++j) { const float a = bf_lo(yw[q][j].x), b = bf_hi(yw[q][j].x), c2 = bf_lo(yw[q][j].y), d = bf_hi(yw[q][j].y); sy += (a * a + b * b) + (c2 * c2 + d * d); }
;                 const float rsy = __builtin_amdgcn_rsqf(wave_sum(sy) * (1.f / DM) + EPS);
	v_mul_f32_e32 v206, v215, v206
	v_mul_f32_e32 v207, v215, v207
	v_fmac_f32_e32 v24, v152, v200
	v_fmac_f32_e32 v25, v153, v201
	v_fmac_f32_e32 v26, v154, v202
	v_fmac_f32_e32 v27, v155, v203
	v_fmac_f32_e32 v24, v184, v204
	v_fmac_f32_e32 v25, v185, v205
	v_fmac_f32_e32 v26, v186, v206
	v_fmac_f32_e32 v27, v187, v207
	global_store_dwordx4 v193, v[24:27], s[18:19] offset:2048
	v_lshlrev_b32_e32 v200, 16, v78
	v_and_b32_e32 v201, 0xffff0000, v78
	v_lshlrev_b32_e32 v202, 16, v79
	v_and_b32_e32 v203, 0xffff0000, v79
	v_lshlrev_b32_e32 v204, 16, v110
	v_and_b32_e32 v205, 0xffff0000, v110
	v_lshlrev_b32_e32 v206, 16, v111
	v_and_b32_e32 v207, 0xffff0000, v111
	v_mul_f32_e32 v200, v214, v200
	v_mul_f32_e32 v201, v214, v201
	v_mul_f32_e32 v202, v214, v202
	v_mul_f32_e32 v203, v214, v203
	v_mul_f32_e32 v204, v215, v204
	v_mul_f32_e32 v205, v215, v205
	v_mul_f32_e32 v206, v215, v206
	v_mul_f32_e32 v207, v215, v207
	v_fmac_f32_e32 v28, v156, v200
	v_fmac_f32_e32 v29, v157, v201
	v_fmac_f32_e32 v30, v158, v202
	v_fmac_f32_e32 v31, v159, v203
	v_fmac_f32_e32 v28, v188, v204
	v_fmac_f32_e32 v29, v189, v205
	v_fmac_f32_e32 v30, v190, v206
	v_fmac_f32_e32 v31, v191, v207
	global_store_dwordx4 v193, v[28:31], s[18:19] offset:3072
	s_add_u32 s18, s18, 0x2000
	s_addc_u32 s19, s19, 0
	global_load_dwordx4 v[0:3], v192, s[14:15] offset:0 nt
	global_load_dwordx4 v[4:7], v192, s[14:15] offset:1024 nt
	global_load_dwordx4 v[8:11], v192, s[14:15] offset:2048 nt
	global_load_dwordx4 v[12:15], v192, s[14:15] offset:3072 nt
	global_load_dwordx4 v[16:19], v193, s[14:15] offset:0 nt
	global_load_dwordx4 v[20:23], v193, s[14:15] offset:1024 nt
	global_load_dwordx4 v[24:27], v193, s[14:15] offset:2048 nt
	global_load_dwordx4 v[28:31], v193, s[14:15] offset:3072 nt
	global_load_dwordx2 v[64:65], v194, s[16:17] offset:0
	global_load_dwordx2 v[66:67], v194, s[16:17] offset:512
	global_load_dwordx2 v[68:69], v194, s[16:17] offset:1024
	global_load_dwordx2 v[70:71], v194, s[16:17] offset:1536
	global_load_dwordx2 v[72:73], v194, s[16:17] offset:2048
	global_load_dwordx2 v[74:75], v194, s[16:17] offset:2560
	global_load_dwordx2 v[76:77], v194, s[16:17] offset:3072
	global_load_dwordx2 v[78:79], v194, s[16:17] offset:3584
	global_load_dwordx2 v[96:97], v194, s[22:23] offset:0
	global_load_dwordx2 v[98:99], v194, s[22:23] offset:512
	global_load_dwordx2 v[100:101], v194, s[22:23] offset:1024
	global_load_dwordx2 v[102:103], v194, s[22:23] offset:1536
	global_load_dwordx2 v[104:105], v194, s[22:23] offset:2048
	global_load_dwordx2 v[106:107], v194, s[22:23] offset:2560
	global_load_dwordx2 v[108:109], v194, s[22:23] offset:3072
	global_load_dwordx2 v[110:111], v194, s[22:23] offset:3584
	s_add_u32 s14, s14, 0x2000
	s_addc_u32 s15, s15, 0
	s_add_u32 s16, s16, 0x1000
	s_addc_u32 s17, s17, 0
	s_add_u32 s22, s22, 0x1000
	s_addc_u32 s23, s23, 0
	s_waitcnt vmcnt(32)
	v_lshlrev_b32_e32 v200, 16, v80
	v_and_b32_e32 v201, 0xffff0000, v80
	v_lshlrev_b32_e32 v202, 16, v81
	v_and_b32_e32 v203, 0xffff0000, v81
	v_mul_f32_e32 v208, v200, v200
	v_mul_f32_e32 v209, v201, v201
	v_fmac_f32_e32 v208, v202, v202
	v_fmac_f32_e32 v209, v203, v203
	v_lshlrev_b32_e32 v204, 16, v112
	v_and_b32_e32 v205, 0xffff0000, v112
	v_lshlrev_b32_e32 v206, 16, v113
	v_and_b32_e32 v207, 0xffff0000, v113
	v_mul_f32_e32 v210, v204, v204
	v_mul_f32_e32 v211, v205, v205
	v_fmac_f32_e32 v210, v206, v206
	v_fmac_f32_e32 v211, v207, v207
	v_lshlrev_b32_e32 v200, 16, v82
	v_and_b32_e32 v201, 0xffff0000, v82
	v_lshlrev_b32_e32 v202, 16, v83
	v_and_b32_e32 v203, 0xffff0000, v83
	v_fmac_f32_e32 v208, v200, v200
	v_fmac_f32_e32 v209, v201, v201
	v_fmac_f32_e32 v208, v202, v202
	v_fmac_f32_e32 v209, v203, v203
	v_lshlrev_b32_e32 v204, 16, v114
	v_and_b32_e32 v205, 0xffff0000, v114
	v_lshlrev_b32_e32 v206, 16, v115
	v_and_b32_e32 v207, 0xffff0000, v115
	v_fmac_f32_e32 v210, v204, v204
	v_fmac_f32_e32 v211, v205, v205
	v_fmac_f32_e32 v210, v206, v206
	v_fmac_f32_e32 v211, v207, v207
	v_lshlrev_b32_e32 v200, 16, v84
	v_and_b32_e32 v201, 0xffff0000, v84
	v_lshlrev_b32_e32 v202, 16, v85
	v_and_b32_e32 v203, 0xffff0000, v85
	v_fmac_f32_e32 v208, v200, v200
	v_fmac_f32_e32 v209, v201, v201
	v_fmac_f32_e32 v208, v202, v202
	v_fmac_f32_e32 v209, v203, v203
	v_lshlrev_b32_e32 v204, 16, v116
	v_and_b32_e32 v205, 0xffff0000, v116
	v_lshlrev_b32_e32 v206, 16, v117
	v_and_b32_e32 v207, 0xffff0000, v117
	v_fmac_f32_e32 v210, v204, v204
	v_fmac_f32_e32 v211, v205, v205
	v_fmac_f32_e32 v210, v206, v206
	v_fmac_f32_e32 v211, v207, v207
	v_lshlrev_b32_e32 v200, 16, v86
	v_and_b32_e32 v201, 0xffff0000, v86
	v_lshlrev_b32_e32 v202, 16, v87
	v_and_b32_e32 v203, 0xffff0000, v87
	v_fmac_f32_e32 v208, v200, v200
	v_fmac_f32_e32 v209, v201, v201
	v_fmac_f32_e32 v208, v202, v202
	v_fmac_f32_e32 v209, v203, v203
	v_lshlrev_b32_e32 v204, 16, v118
	v_and_b32_e32 v205, 0xffff0000, v118
	v_lshlrev_b32_e32 v206, 16, v119
	v_and_b32_e32 v207, 0xffff0000, v119
	v_fmac_f32_e32 v210, v204, v204
	v_fmac_f32_e32 v211, v205, v205
	v_fmac_f32_e32 v210, v206, v206
	v_fmac_f32_e32 v211, v207, v207
	v_lshlrev_b32_e32 v200, 16, v88
	v_and_b32_e32 v201, 0xffff0000, v88
	v_lshlrev_b32_e32 v202, 16, v89
	v_and_b32_e32 v203, 0xffff0000, v89
	v_fmac_f32_e32 v208, v200, v200
	v_fmac_f32_e32 v209, v201, v201
	v_fmac_f32_e32 v208, v202, v202
	v_fmac_f32_e32 v209, v203, v203
	v_lshlrev_b32_e32 v204, 16, v120
	v_and_b32_e32 v205, 0xffff0000, v120
	v_lshlrev_b32_e32 v206, 16, v121
	v_and_b32_e32 v207, 0xffff0000, v121
	v_fmac_f32_e32 v210, v204, v204
	v_fmac_f32_e32 v211, v205, v205
	v_fmac_f32_e32 v210, v206, v206
	v_fmac_f32_e32 v211, v207, v207
	v_lshlrev_b32_e32 v200, 16, v90
; __device__ __forceinline__ float bf_lo(unsigned w) { return __uint_as_float(w << 16); }
; __device__ __forceinline__ float bf_hi(unsigned w) { return __uint_as_float(w & 0xffff0000u); }
; __global__ void __launch_bounds__(NWAVES * 64, 2) mk_fwd(Args args) {
;     ...
;                 float sy = 0.f;
; #pragma unroll
;                 for (int j = 0; j < 8; ++j) { const float a = bf_lo(yw[q][j].x), b = bf_hi(yw[q][j].x), c2 = bf_lo(yw[q][j].y), d = bf_hi(yw[q][j].y); sy += (a * a + b * b) + (c2 * c2 + d * d); }
;                 const float rsy = __builtin_amdgcn_rsqf(wave_sum(sy) * (1.f / DM) + EPS);
; #pragma unroll
;                 for (int j = 0; j < 8; ++j) { const int col = 4 * F.lane + 256 * j;
;                     const f32x4 y4 = (f32x4){bf_lo(yw[q][j].x), bf_hi(yw[q][j].x), bf_lo(yw[q][j].y), bf_hi(yw[q][j].y)};
;                     *(f32x4*)(args.out + (size_t)row * DM + col) = v[q][j] + PA[j] * (y4 * rsy); }
	v_and_b32_e32 v201, 0xffff0000, v90
	v_lshlrev_b32_e32 v202, 16, v91
	v_and_b32_e32 v203, 0xffff0000, v91
	v_fmac_f32_e32 v208, v200, v200
	v_fmac_f32_e32 v209, v201, v201
	v_fmac_f32_e32 v208, v202, v202
	v_fmac_f32_e32 v209, v203, v203
	v_lshlrev_b32_e32 v204, 16, v122
	v_and_b32_e32 v205, 0xffff0000, v122
	v_lshlrev_b32_e32 v206, 16, v123
	v_and_b32_e32 v207, 0xffff0000, v123
	v_fmac_f32_e32 v210, v204, v204
	v_fmac_f32_e32 v211, v205, v205
	v_fmac_f32_e32 v210, v206, v206
	v_fmac_f32_e32 v211, v207, v207
	v_lshlrev_b32_e32 v200, 16, v92
	v_and_b32_e32 v201, 0xffff0000, v92
	v_lshlrev_b32_e32 v202, 16, v93
	v_and_b32_e32 v203, 0xffff0000, v93
	v_fmac_f32_e32 v208, v200, v200
	v_fmac_f32_e32 v209, v201, v201
	v_fmac_f32_e32 v208, v202, v202
	v_fmac_f32_e32 v209, v203, v203
	v_lshlrev_b32_e32 v204, 16, v124
	v_and_b32_e32 v205, 0xffff0000, v124
	v_lshlrev_b32_e32 v206, 16, v125
	v_and_b32_e32 v207, 0xffff0000, v125
	v_fmac_f32_e32 v210, v204, v204
	v_fmac_f32_e32 v211, v205, v205
	v_fmac_f32_e32 v210, v206, v206
	v_fmac_f32_e32 v211, v207, v207
	v_lshlrev_b32_e32 v200, 16, v94
	v_and_b32_e32 v201, 0xffff0000, v94
	v_lshlrev_b32_e32 v202, 16, v95
	v_and_b32_e32 v203, 0xffff0000, v95
	v_fmac_f32_e32 v208, v200, v200
	v_fmac_f32_e32 v209, v201, v201
	v_fmac_f32_e32 v208, v202, v202
	v_fmac_f32_e32 v209, v203, v203
	v_lshlrev_b32_e32 v204, 16, v126
	v_and_b32_e32 v205, 0xffff0000, v126
	v_lshlrev_b32_e32 v206, 16, v127
	v_and_b32_e32 v207, 0xffff0000, v127
	v_fmac_f32_e32 v210, v204, v204
	v_fmac_f32_e32 v211, v205, v205
	v_fmac_f32_e32 v210, v206, v206
	v_fmac_f32_e32 v211, v207, v207
	v_add_f32_e32 v208, v208, v209
	v_add_f32_e32 v210, v210, v211
	s_nop 0
	v_add_f32_dpp v212, v208, v208 quad_perm:[1,0,3,2] row_mask:0xf bank_mask:0xf
	v_add_f32_dpp v213, v210, v210 quad_perm:[1,0,3,2] row_mask:0xf bank_mask:0xf
	s_nop 0
	v_add_f32_dpp v212, v212, v212 quad_perm:[2,3,0,1] row_mask:0xf bank_mask:0xf
	v_add_f32_dpp v213, v213, v213 quad_perm:[2,3,0,1] row_mask:0xf bank_mask:0xf
	s_nop 0
	v_add_f32_dpp v212, v212, v212 row_half_mirror row_mask:0xf bank_mask:0xf
	v_add_f32_dpp v213, v213, v213 row_half_mirror row_mask:0xf bank_mask:0xf
	s_nop 0
	v_add_f32_dpp v212, v212, v212 row_mirror row_mask:0xf bank_mask:0xf
	v_add_f32_dpp v213, v213, v213 row_mirror row_mask:0xf bank_mask:0xf
	s_nop 0
	v_readlane_b32 s4, v212, 0
	v_readlane_b32 s5, v212, 16
	v_readlane_b32 s6, v212, 32
	v_readlane_b32 s7, v212, 48
	v_readlane_b32 s24, v213, 0
	v_readlane_b32 s25, v213, 16
	v_readlane_b32 s26, v213, 32
	v_readlane_b32 s27, v213, 48
	s_nop 1
	v_mov_b32_e32 v214, s4
	v_mov_b32_e32 v215, s24
	v_add_f32_e32 v214, s5, v214
	v_add_f32_e32 v215, s25, v215
	v_add_f32_e32 v214, s6, v214
	v_add_f32_e32 v215, s26, v215
	v_add_f32_e32 v214, s7, v214
	v_add_f32_e32 v215, s27, v215
	v_fmamk_f32 v214, v214, 0x3a000000, v195
	v_fmamk_f32 v215, v215, 0x3a000000, v195
	v_rsq_f32_e32 v214, v214
	v_rsq_f32_e32 v215, v215
	s_nop 0
	v_lshlrev_b32_e32 v200, 16, v80
	v_and_b32_e32 v201, 0xffff0000, v80
	v_lshlrev_b32_e32 v202, 16, v81
	v_and_b32_e32 v203, 0xffff0000, v81
	v_lshlrev_b32_e32 v204, 16, v112
	v_and_b32_e32 v205, 0xffff0000, v112
	v_lshlrev_b32_e32 v206, 16, v113
	v_and_b32_e32 v207, 0xffff0000, v113
	v_mul_f32_e32 v200, v214, v200
	v_mul_f32_e32 v201, v214, v201
	v_mul_f32_e32 v202, v214, v202
	v_mul_f32_e32 v203, v214, v203
	v_mul_f32_e32 v204, v215, v204
	v_mul_f32_e32 v205, v215, v205
	v_mul_f32_e32 v206, v215, v206
	v_mul_f32_e32 v207, v215, v207
	v_fmac_f32_e32 v32, v128, v200
	v_fmac_f32_e32 v33, v129, v201
	v_fmac_f32_e32 v34, v130, v202
	v_fmac_f32_e32 v35, v131, v203
	v_fmac_f32_e32 v32, v160, v204
	v_fmac_f32_e32 v33, v161, v205
	v_fmac_f32_e32 v34, v162, v206
	v_fmac_f32_e32 v35, v163, v207
	global_store_dwordx4 v192, v[32:35], s[18:19] offset:0
	v_lshlrev_b32_e32 v200, 16, v82
	v_and_b32_e32 v201, 0xffff0000, v82
	v_lshlrev_b32_e32 v202, 16, v83
	v_and_b32_e32 v203, 0xffff0000, v83
	v_lshlrev_b32_e32 v204, 16, v114
	v_and_b32_e32 v205, 0xffff0000, v114
	v_lshlrev_b32_e32 v206, 16, v115
	v_and_b32_e32 v207, 0xffff0000, v115
	v_mul_f32_e32 v200, v214, v200
	v_mul_f32_e32 v201, v214, v201
	v_mul_f32_e32 v202, v214, v202
	v_mul_f32_e32 v203, v214, v203
	v_mul_f32_e32 v204, v215, v204
	v_mul_f32_e32 v205, v215, v205
	v_mul_f32_e32 v206, v215, v206
	v_mul_f32_e32 v207, v215, v207
	v_fmac_f32_e32 v36, v132, v200
	v_fmac_f32_e32 v37, v133, v201
	v_fmac_f32_e32 v38, v134, v202
	v_fmac_f32_e32 v39, v135, v203
	v_fmac_f32_e32 v36, v164, v204
	v_fmac_f32_e32 v37, v165, v205
	v_fmac_f32_e32 v38, v166, v206
	v_fmac_f32_e32 v39, v167, v207
	global_store_dwordx4 v192, v[36:39], s[18:19] offset:1024
	v_lshlrev_b32_e32 v200, 16, v84
	v_and_b32_e32 v201, 0xffff0000, v84
	v_lshlrev_b32_e32 v202, 16, v85
	v_and_b32_e32 v203, 0xffff0000, v85
	v_lshlrev_b32_e32 v204, 16, v116
	v_and_b32_e32 v205, 0xffff0000, v116
	v_lshlrev_b32_e32 v206, 16, v117
	v_and_b32_e32 v207, 0xffff0000, v117
	v_mul_f32_e32 v200, v214, v200
	v_mul_f32_e32 v201, v214, v201
	v_mul_f32_e32 v202, v214, v202
	v_mul_f32_e32 v203, v214, v203
	v_mul_f32_e32 v204, v215, v204
	v_mul_f32_e32 v205, v215, v205
	v_mul_f32_e32 v206, v215, v206
	v_mul_f32_e32 v207, v215, v207
	v_fmac_f32_e32 v40, v136, v200
	v_fmac_f32_e32 v41, v137, v201
	v_fmac_f32_e32 v42, v138, v202
	v_fmac_f32_e32 v43, v139, v203
	v_fmac_f32_e32 v40, v168, v204
	v_fmac_f32_e32 v41, v169, v205
	v_fmac_f32_e32 v42, v170, v206
	v_fmac_f32_e32 v43, v171, v207
	global_store_dwordx4 v192, v[40:43], s[18:19] offset:2048
	v_lshlrev_b32_e32 v200, 16, v86
	v_and_b32_e32 v201, 0xffff0000, v86
	v_lshlrev_b32_e32 v202, 16, v87
	v_and_b32_e32 v203, 0xffff0000, v87
; __device__ __forceinline__ float bf_lo(unsigned w) { return __uint_as_float(w << 16); }
; __device__ __forceinline__ float bf_hi(unsigned w) { return __uint_as_float(w & 0xffff0000u); }
; __global__ void __launch_bounds__(NWAVES * 64, 2) mk_fwd(Args args) {
;     ...
;         for (int row0 = rbeg; row0 < rbeg + per2 && row0 < ML; row0 += 2) {
;             f32x4 v[2][8]; u32x2 yw[2][8];
; #pragma unroll
;             for (int q = 0; q < 2; ++q) { const int row = row0 + q; load_row_f32(args.out + (size_t)row * DM, F.lane, v[q]);
;                 const bf16_t* yr = Y + (size_t)row * DM;
; #pragma unroll
;                 for (int j = 0; j < 8; ++j) yw[q][j] = *(const u32x2*)(yr + 4 * F.lane + 256 * j); }
; #pragma unroll
;             for (int q = 0; q < 2; ++q) { const int row = row0 + q; const int r = row / SEQ;
;                 if (r != rcur) { const float* m1 = mod + (size_t)(9 + r) * 6144; rcur = r;
; #pragma unroll
;                     for (int j = 0; j < 8; ++j) { const int col = 4 * F.lane + 256 * j; PA[j] = *(const f32x4*)(m1 + 2 * DM + col) * *(const f32x4*)(post_norm + DM + col); } }
;                 float sy = 0.f;
; #pragma unroll
;                 for (int j = 0; j < 8; ++j) { const float a = bf_lo(yw[q][j].x), b = bf_hi(yw[q][j].x), c2 = bf_lo(yw[q][j].y), d = bf_hi(yw[q][j].y); sy += (a * a + b * b) + (c2 * c2 + d * d); }
;                 const float rsy = __builtin_amdgcn_rsqf(wave_sum(sy) * (1.f / DM) + EPS);
; #pragma unroll
;                 for (int j = 0; j < 8; ++j) { const int col = 4 * F.lane + 256 * j;
;                     const f32x4 y4 = (f32x4){bf_lo(yw[q][j].x), bf_hi(yw[q][j].x), bf_lo(yw[q][j].y), bf_hi(yw[q][j].y)};
;                     *(f32x4*)(args.out + (size_t)row * DM + col) = v[q][j] + PA[j] * (y4 * rsy); }
	v_lshlrev_b32_e32 v204, 16, v118
	v_and_b32_e32 v205, 0xffff0000, v118
	v_lshlrev_b32_e32 v206, 16, v119
	v_and_b32_e32 v207, 0xffff0000, v119
	v_mul_f32_e32 v200, v214, v200
	v_mul_f32_e32 v201, v214, v201
	v_mul_f32_e32 v202, v214, v202
	v_mul_f32_e32 v203, v214, v203
	v_mul_f32_e32 v204, v215, v204
	v_mul_f32_e32 v205, v215, v205
	v_mul_f32_e32 v206, v215, v206
	v_mul_f32_e32 v207, v215, v207
	v_fmac_f32_e32 v44, v140, v200
	v_fmac_f32_e32 v45, v141, v201
	v_fmac_f32_e32 v46, v142, v202
	v_fmac_f32_e32 v47, v143, v203
	v_fmac_f32_e32 v44, v172, v204
	v_fmac_f32_e32 v45, v173, v205
	v_fmac_f32_e32 v46, v174, v206
	v_fmac_f32_e32 v47, v175, v207
	global_store_dwordx4 v192, v[44:47], s[18:19] offset:3072
	v_lshlrev_b32_e32 v200, 16, v88
	v_and_b32_e32 v201, 0xffff0000, v88
	v_lshlrev_b32_e32 v202, 16, v89
	v_and_b32_e32 v203, 0xffff0000, v89
	v_lshlrev_b32_e32 v204, 16, v120
	v_and_b32_e32 v205, 0xffff0000, v120
	v_lshlrev_b32_e32 v206, 16, v121
	v_and_b32_e32 v207, 0xffff0000, v121
	v_mul_f32_e32 v200, v214, v200
	v_mul_f32_e32 v201, v214, v201
	v_mul_f32_e32 v202, v214, v202
	v_mul_f32_e32 v203, v214, v203
	v_mul_f32_e32 v204, v215, v204
	v_mul_f32_e32 v205, v215, v205
	v_mul_f32_e32 v206, v215, v206
	v_mul_f32_e32 v207, v215, v207
	v_fmac_f32_e32 v48, v144, v200
	v_fmac_f32_e32 v49, v145, v201
	v_fmac_f32_e32 v50, v146, v202
	v_fmac_f32_e32 v51, v147, v203
	v_fmac_f32_e32 v48, v176, v204
	v_fmac_f32_e32 v49, v177, v205
	v_fmac_f32_e32 v50, v178, v206
	v_fmac_f32_e32 v51, v179, v207
	global_store_dwordx4 v193, v[48:51], s[18:19] offset:0
	v_lshlrev_b32_e32 v200, 16, v90
	v_and_b32_e32 v201, 0xffff0000, v90
	v_lshlrev_b32_e32 v202, 16, v91
	v_and_b32_e32 v203, 0xffff0000, v91
	v_lshlrev_b32_e32 v204, 16, v122
	v_and_b32_e32 v205, 0xffff0000, v122
	v_lshlrev_b32_e32 v206, 16, v123
	v_and_b32_e32 v207, 0xffff0000, v123
	v_mul_f32_e32 v200, v214, v200
	v_mul_f32_e32 v201, v214, v201
	v_mul_f32_e32 v202, v214, v202
	v_mul_f32_e32 v203, v214, v203
	v_mul_f32_e32 v204, v215, v204
	v_mul_f32_e32 v205, v215, v205
	v_mul_f32_e32 v206, v215, v206
	v_mul_f32_e32 v207, v215, v207
	v_fmac_f32_e32 v52, v148, v200
	v_fmac_f32_e32 v53, v149, v201
	v_fmac_f32_e32 v54, v150, v202
	v_fmac_f32_e32 v55, v151, v203
	v_fmac_f32_e32 v52, v180, v204
	v_fmac_f32_e32 v53, v181, v205
	v_fmac_f32_e32 v54, v182, v206
	v_fmac_f32_e32 v55, v183, v207
	global_store_dwordx4 v193, v[52:55], s[18:19] offset:1024
	v_lshlrev_b32_e32 v200, 16, v92
	v_and_b32_e32 v201, 0xffff0000, v92
	v_lshlrev_b32_e32 v202, 16, v93
	v_and_b32_e32 v203, 0xffff0000, v93
	v_lshlrev_b32_e32 v204, 16, v124
	v_and_b32_e32 v205, 0xffff0000, v124
	v_lshlrev_b32_e32 v206, 16, v125
	v_and_b32_e32 v207, 0xffff0000, v125
	v_mul_f32_e32 v200, v214, v200
	v_mul_f32_e32 v201, v214, v201
	v_mul_f32_e32 v202, v214, v202
	v_mul_f32_e32 v203, v214, v203
	v_mul_f32_e32 v204, v215, v204
	v_mul_f32_e32 v205, v215, v205
	v_mul_f32_e32 v206, v215, v206
	v_mul_f32_e32 v207, v215, v207
	v_fmac_f32_e32 v56, v152, v200
	v_fmac_f32_e32 v57, v153, v201
	v_fmac_f32_e32 v58, v154, v202
	v_fmac_f32_e32 v59, v155, v203
	v_fmac_f32_e32 v56, v184, v204
	v_fmac_f32_e32 v57, v185, v205
	v_fmac_f32_e32 v58, v186, v206
	v_fmac_f32_e32 v59, v187, v207
	global_store_dwordx4 v193, v[56:59], s[18:19] offset:2048
	v_lshlrev_b32_e32 v200, 16, v94
	v_and_b32_e32 v201, 0xffff0000, v94
	v_lshlrev_b32_e32 v202, 16, v95
	v_and_b32_e32 v203, 0xffff0000, v95
	v_lshlrev_b32_e32 v204, 16, v126
	v_and_b32_e32 v205, 0xffff0000, v126
	v_lshlrev_b32_e32 v206, 16, v127
	v_and_b32_e32 v207, 0xffff0000, v127
	v_mul_f32_e32 v200, v214, v200
	v_mul_f32_e32 v201, v214, v201
	v_mul_f32_e32 v202, v214, v202
	v_mul_f32_e32 v203, v214, v203
	v_mul_f32_e32 v204, v215, v204
	v_mul_f32_e32 v205, v215, v205
	v_mul_f32_e32 v206, v215, v206
	v_mul_f32_e32 v207, v215, v207
	v_fmac_f32_e32 v60, v156, v200
	v_fmac_f32_e32 v61, v157, v201
	v_fmac_f32_e32 v62, v158, v202
	v_fmac_f32_e32 v63, v159, v203
	v_fmac_f32_e32 v60, v188, v204
	v_fmac_f32_e32 v61, v189, v205
	v_fmac_f32_e32 v62, v190, v206
	v_fmac_f32_e32 v63, v191, v207
	global_store_dwordx4 v193, v[60:63], s[18:19] offset:3072
	s_add_u32 s18, s18, 0x2000
	s_addc_u32 s19, s19, 0
	global_load_dwordx4 v[32:35], v192, s[14:15] offset:0 nt
	global_load_dwordx4 v[36:39], v192, s[14:15] offset:1024 nt
	global_load_dwordx4 v[40:43], v192, s[14:15] offset:2048 nt
	global_load_dwordx4 v[44:47], v192, s[14:15] offset:3072 nt
	global_load_dwordx4 v[48:51], v193, s[14:15] offset:0 nt
	global_load_dwordx4 v[52:55], v193, s[14:15] offset:1024 nt
	global_load_dwordx4 v[56:59], v193, s[14:15] offset:2048 nt
	global_load_dwordx4 v[60:63], v193, s[14:15] offset:3072 nt
	global_load_dwordx2 v[80:81], v194, s[16:17] offset:0
	global_load_dwordx2 v[82:83], v194, s[16:17] offset:512
	global_load_dwordx2 v[84:85], v194, s[16:17] offset:1024
	global_load_dwordx2 v[86:87], v194, s[16:17] offset:1536
	global_load_dwordx2 v[88:89], v194, s[16:17] offset:2048
	global_load_dwordx2 v[90:91], v194, s[16:17] offset:2560
	global_load_dwordx2 v[92:93], v194, s[16:17] offset:3072
	global_load_dwordx2 v[94:95], v194, s[16:17] offset:3584
	global_load_dwordx2 v[112:113], v194, s[22:23] offset:0
	global_load_dwordx2 v[114:115], v194, s[22:23] offset:512
	global_load_dwordx2 v[116:117], v194, s[22:23] offset:1024
	global_load_dwordx2 v[118:119], v194, s[22:23] offset:1536
	global_load_dwordx2 v[120:121], v194, s[22:23] offset:2048
	global_load_dwordx2 v[122:123], v194, s[22:23] offset:2560
	global_load_dwordx2 v[124:125], v194, s[22:23] offset:3072
	global_load_dwordx2 v[126:127], v194, s[22:23] offset:3584
	s_add_u32 s14, s14, 0x2000
	s_addc_u32 s15, s15, 0
	s_add_u32 s16, s16, 0x1000
	s_addc_u32 s17, s17, 0
	s_add_u32 s22, s22, 0x1000
	s_addc_u32 s23, s23, 0
	s_waitcnt vmcnt(32)
; __device__ __forceinline__ float bf_lo(unsigned w) { return __uint_as_float(w << 16); }
; __device__ __forceinline__ float bf_hi(unsigned w) { return __uint_as_float(w & 0xffff0000u); }
; __global__ void __launch_bounds__(NWAVES * 64, 2) mk_fwd(Args args) {
;     ...
;                 float sy = 0.f;
; #pragma unroll
;                 for (int j = 0; j < 8; ++j) { const float a = bf_lo(yw[q][j].x), b = bf_hi(yw[q][j].x), c2 = bf_lo(yw[q][j].y), d = bf_hi(yw[q][j].y); sy += (a * a + b * b) + (c2 * c2 + d * d); }
;                 const float rsy = __builtin_amdgcn_rsqf(wave_sum(sy) * (1.f / DM) + EPS);
	v_lshlrev_b32_e32 v200, 16, v64
	v_and_b32_e32 v201, 0xffff0000, v64
	v_lshlrev_b32_e32 v202, 16, v65
	v_and_b32_e32 v203, 0xffff0000, v65
	v_mul_f32_e32 v208, v200, v200
	v_mul_f32_e32 v209, v201, v201
	v_fmac_f32_e32 v208, v202, v202
	v_fmac_f32_e32 v209, v203, v203
	v_lshlrev_b32_e32 v204, 16, v96
	v_and_b32_e32 v205, 0xffff0000, v96
	v_lshlrev_b32_e32 v206, 16, v97
	v_and_b32_e32 v207, 0xffff0000, v97
	v_mul_f32_e32 v210, v204, v204
	v_mul_f32_e32 v211, v205, v205
	v_fmac_f32_e32 v210, v206, v206
	v_fmac_f32_e32 v211, v207, v207
	v_lshlrev_b32_e32 v200, 16, v66
	v_and_b32_e32 v201, 0xffff0000, v66
	v_lshlrev_b32_e32 v202, 16, v67
	v_and_b32_e32 v203, 0xffff0000, v67
	v_fmac_f32_e32 v208, v200, v200
	v_fmac_f32_e32 v209, v201, v201
	v_fmac_f32_e32 v208, v202, v202
	v_fmac_f32_e32 v209, v203, v203
	v_lshlrev_b32_e32 v204, 16, v98
	v_and_b32_e32 v205, 0xffff0000, v98
	v_lshlrev_b32_e32 v206, 16, v99
	v_and_b32_e32 v207, 0xffff0000, v99
	v_fmac_f32_e32 v210, v204, v204
	v_fmac_f32_e32 v211, v205, v205
	v_fmac_f32_e32 v210, v206, v206
	v_fmac_f32_e32 v211, v207, v207
	v_lshlrev_b32_e32 v200, 16, v68
	v_and_b32_e32 v201, 0xffff0000, v68
	v_lshlrev_b32_e32 v202, 16, v69
	v_and_b32_e32 v203, 0xffff0000, v69
	v_fmac_f32_e32 v208, v200, v200
	v_fmac_f32_e32 v209, v201, v201
	v_fmac_f32_e32 v208, v202, v202
	v_fmac_f32_e32 v209, v203, v203
	v_lshlrev_b32_e32 v204, 16, v100
	v_and_b32_e32 v205, 0xffff0000, v100
	v_lshlrev_b32_e32 v206, 16, v101
	v_and_b32_e32 v207, 0xffff0000, v101
	v_fmac_f32_e32 v210, v204, v204
	v_fmac_f32_e32 v211, v205, v205
	v_fmac_f32_e32 v210, v206, v206
	v_fmac_f32_e32 v211, v207, v207
	v_lshlrev_b32_e32 v200, 16, v70
	v_and_b32_e32 v201, 0xffff0000, v70
	v_lshlrev_b32_e32 v202, 16, v71
	v_and_b32_e32 v203, 0xffff0000, v71
	v_fmac_f32_e32 v208, v200, v200
	v_fmac_f32_e32 v209, v201, v201
	v_fmac_f32_e32 v208, v202, v202
	v_fmac_f32_e32 v209, v203, v203
	v_lshlrev_b32_e32 v204, 16, v102
	v_and_b32_e32 v205, 0xffff0000, v102
	v_lshlrev_b32_e32 v206, 16, v103
	v_and_b32_e32 v207, 0xffff0000, v103
	v_fmac_f32_e32 v210, v204, v204
	v_fmac_f32_e32 v211, v205, v205
	v_fmac_f32_e32 v210, v206, v206
	v_fmac_f32_e32 v211, v207, v207
	v_lshlrev_b32_e32 v200, 16, v72
	v_and_b32_e32 v201, 0xffff0000, v72
	v_lshlrev_b32_e32 v202, 16, v73
	v_and_b32_e32 v203, 0xffff0000, v73
	v_fmac_f32_e32 v208, v200, v200
	v_fmac_f32_e32 v209, v201, v201
	v_fmac_f32_e32 v208, v202, v202
	v_fmac_f32_e32 v209, v203, v203
	v_lshlrev_b32_e32 v204, 16, v104
	v_and_b32_e32 v205, 0xffff0000, v104
	v_lshlrev_b32_e32 v206, 16, v105
	v_and_b32_e32 v207, 0xffff0000, v105
	v_fmac_f32_e32 v210, v204, v204
	v_fmac_f32_e32 v211, v205, v205
	v_fmac_f32_e32 v210, v206, v206
	v_fmac_f32_e32 v211, v207, v207
	v_lshlrev_b32_e32 v200, 16, v74
	v_and_b32_e32 v201, 0xffff0000, v74
	v_lshlrev_b32_e32 v202, 16, v75
	v_and_b32_e32 v203, 0xffff0000, v75
	v_fmac_f32_e32 v208, v200, v200
	v_fmac_f32_e32 v209, v201, v201
	v_fmac_f32_e32 v208, v202, v202
	v_fmac_f32_e32 v209, v203, v203
	v_lshlrev_b32_e32 v204, 16, v106
	v_and_b32_e32 v205, 0xffff0000, v106
	v_lshlrev_b32_e32 v206, 16, v107
	v_and_b32_e32 v207, 0xffff0000, v107
	v_fmac_f32_e32 v210, v204, v204
	v_fmac_f32_e32 v211, v205, v205
	v_fmac_f32_e32 v210, v206, v206
	v_fmac_f32_e32 v211, v207, v207
	v_lshlrev_b32_e32 v200, 16, v76
	v_and_b32_e32 v201, 0xffff0000, v76
	v_lshlrev_b32_e32 v202, 16, v77
	v_and_b32_e32 v203, 0xffff0000, v77
	v_fmac_f32_e32 v208, v200, v200
	v_fmac_f32_e32 v209, v201, v201
	v_fmac_f32_e32 v208, v202, v202
	v_fmac_f32_e32 v209, v203, v203
	v_lshlrev_b32_e32 v204, 16, v108
	v_and_b32_e32 v205, 0xffff0000, v108
	v_lshlrev_b32_e32 v206, 16, v109
	v_and_b32_e32 v207, 0xffff0000, v109
	v_fmac_f32_e32 v210, v204, v204
	v_fmac_f32_e32 v211, v205, v205
	v_fmac_f32_e32 v210, v206, v206
	v_fmac_f32_e32 v211, v207, v207
	v_lshlrev_b32_e32 v200, 16, v78
	v_and_b32_e32 v201, 0xffff0000, v78
	v_lshlrev_b32_e32 v202, 16, v79
	v_and_b32_e32 v203, 0xffff0000, v79
	v_fmac_f32_e32 v208, v200, v200
	v_fmac_f32_e32 v209, v201, v201
	v_fmac_f32_e32 v208, v202, v202
	v_fmac_f32_e32 v209, v203, v203
	v_lshlrev_b32_e32 v204, 16, v110
	v_and_b32_e32 v205, 0xffff0000, v110
	v_lshlrev_b32_e32 v206, 16, v111
	v_and_b32_e32 v207, 0xffff0000, v111
	v_fmac_f32_e32 v210, v204, v204
	v_fmac_f32_e32 v211, v205, v205
	v_fmac_f32_e32 v210, v206, v206
	v_fmac_f32_e32 v211, v207, v207
	v_add_f32_e32 v208, v208, v209
	v_add_f32_e32 v210, v210, v211
	s_nop 0
	v_add_f32_dpp v212, v208, v208 quad_perm:[1,0,3,2] row_mask:0xf bank_mask:0xf
	v_add_f32_dpp v213, v210, v210 quad_perm:[1,0,3,2] row_mask:0xf bank_mask:0xf
	s_nop 0
	v_add_f32_dpp v212, v212, v212 quad_perm:[2,3,0,1] row_mask:0xf bank_mask:0xf
	v_add_f32_dpp v213, v213, v213 quad_perm:[2,3,0,1] row_mask:0xf bank_mask:0xf
	s_nop 0
	v_add_f32_dpp v212, v212, v212 row_half_mirror row_mask:0xf bank_mask:0xf
	v_add_f32_dpp v213, v213, v213 row_half_mirror row_mask:0xf bank_mask:0xf
	s_nop 0
	v_add_f32_dpp v212, v212, v212 row_mirror row_mask:0xf bank_mask:0xf
	v_add_f32_dpp v213, v213, v213 row_mirror row_mask:0xf bank_mask:0xf
	s_nop 0
	v_readlane_b32 s4, v212, 0
	v_readlane_b32 s5, v212, 16
	v_readlane_b32 s6, v212, 32
	v_readlane_b32 s7, v212, 48
	v_readlane_b32 s24, v213, 0
	v_readlane_b32 s25, v213, 16
	v_readlane_b32 s26, v213, 32
	v_readlane_b32 s27, v213, 48
	s_nop 1
	v_mov_b32_e32 v214, s4
	v_mov_b32_e32 v215, s24
	v_add_f32_e32 v214, s5, v214
	v_add_f32_e32 v215, s25, v215
	v_add_f32_e32 v214, s6, v214
	v_add_f32_e32 v215, s26, v215
	v_add_f32_e32 v214, s7, v214
	v_add_f32_e32 v215, s27, v215
	v_fmamk_f32 v214, v214, 0x3a000000, v195
	v_fmamk_f32 v215, v215, 0x3a000000, v195
; __device__ __forceinline__ float bf_lo(unsigned w) { return __uint_as_float(w << 16); }
; __device__ __forceinline__ float bf_hi(unsigned w) { return __uint_as_float(w & 0xffff0000u); }
; __global__ void __launch_bounds__(NWAVES * 64, 2) mk_fwd(Args args) {
;     ...
;                 const float rsy = __builtin_amdgcn_rsqf(wave_sum(sy) * (1.f / DM) + EPS);
; #pragma unroll
;                 for (int j = 0; j < 8; ++j) { const int col = 4 * F.lane + 256 * j;
;                     const f32x4 y4 = (f32x4){bf_lo(yw[q][j].x), bf_hi(yw[q][j].x), bf_lo(yw[q][j].y), bf_hi(yw[q][j].y)};
;                     *(f32x4*)(args.out + (size_t)row * DM + col) = v[q][j] + PA[j] * (y4 * rsy); }
	v_rsq_f32_e32 v214, v214
	v_rsq_f32_e32 v215, v215
	s_nop 0
	v_lshlrev_b32_e32 v200, 16, v64
	v_and_b32_e32 v201, 0xffff0000, v64
	v_lshlrev_b32_e32 v202, 16, v65
	v_and_b32_e32 v203, 0xffff0000, v65
	v_lshlrev_b32_e32 v204, 16, v96
	v_and_b32_e32 v205, 0xffff0000, v96
	v_lshlrev_b32_e32 v206, 16, v97
	v_and_b32_e32 v207, 0xffff0000, v97
	v_mul_f32_e32 v200, v214, v200
	v_mul_f32_e32 v201, v214, v201
	v_mul_f32_e32 v202, v214, v202
	v_mul_f32_e32 v203, v214, v203
	v_mul_f32_e32 v204, v215, v204
	v_mul_f32_e32 v205, v215, v205
	v_mul_f32_e32 v206, v215, v206
	v_mul_f32_e32 v207, v215, v207
	v_fmac_f32_e32 v0, v128, v200
	v_fmac_f32_e32 v1, v129, v201
	v_fmac_f32_e32 v2, v130, v202
	v_fmac_f32_e32 v3, v131, v203
	v_fmac_f32_e32 v0, v160, v204
	v_fmac_f32_e32 v1, v161, v205
	v_fmac_f32_e32 v2, v162, v206
	v_fmac_f32_e32 v3, v163, v207
	global_store_dwordx4 v192, v[0:3], s[18:19] offset:0
	v_lshlrev_b32_e32 v200, 16, v66
	v_and_b32_e32 v201, 0xffff0000, v66
	v_lshlrev_b32_e32 v202, 16, v67
	v_and_b32_e32 v203, 0xffff0000, v67
	v_lshlrev_b32_e32 v204, 16, v98
	v_and_b32_e32 v205, 0xffff0000, v98
	v_lshlrev_b32_e32 v206, 16, v99
	v_and_b32_e32 v207, 0xffff0000, v99
	v_mul_f32_e32 v200, v214, v200
	v_mul_f32_e32 v201, v214, v201
	v_mul_f32_e32 v202, v214, v202
	v_mul_f32_e32 v203, v214, v203
	v_mul_f32_e32 v204, v215, v204
	v_mul_f32_e32 v205, v215, v205
	v_mul_f32_e32 v206, v215, v206
	v_mul_f32_e32 v207, v215, v207
	v_fmac_f32_e32 v4, v132, v200
	v_fmac_f32_e32 v5, v133, v201
	v_fmac_f32_e32 v6, v134, v202
	v_fmac_f32_e32 v7, v135, v203
	v_fmac_f32_e32 v4, v164, v204
	v_fmac_f32_e32 v5, v165, v205
	v_fmac_f32_e32 v6, v166, v206
	v_fmac_f32_e32 v7, v167, v207
	global_store_dwordx4 v192, v[4:7], s[18:19] offset:1024
	v_lshlrev_b32_e32 v200, 16, v68
	v_and_b32_e32 v201, 0xffff0000, v68
	v_lshlrev_b32_e32 v202, 16, v69
	v_and_b32_e32 v203, 0xffff0000, v69
	v_lshlrev_b32_e32 v204, 16, v100
	v_and_b32_e32 v205, 0xffff0000, v100
	v_lshlrev_b32_e32 v206, 16, v101
	v_and_b32_e32 v207, 0xffff0000, v101
	v_mul_f32_e32 v200, v214, v200
	v_mul_f32_e32 v201, v214, v201
	v_mul_f32_e32 v202, v214, v202
	v_mul_f32_e32 v203, v214, v203
	v_mul_f32_e32 v204, v215, v204
	v_mul_f32_e32 v205, v215, v205
	v_mul_f32_e32 v206, v215, v206
	v_mul_f32_e32 v207, v215, v207
	v_fmac_f32_e32 v8, v136, v200
	v_fmac_f32_e32 v9, v137, v201
	v_fmac_f32_e32 v10, v138, v202
	v_fmac_f32_e32 v11, v139, v203
	v_fmac_f32_e32 v8, v168, v204
	v_fmac_f32_e32 v9, v169, v205
	v_fmac_f32_e32 v10, v170, v206
	v_fmac_f32_e32 v11, v171, v207
	global_store_dwordx4 v192, v[8:11], s[18:19] offset:2048
	v_lshlrev_b32_e32 v200, 16, v70
	v_and_b32_e32 v201, 0xffff0000, v70
	v_lshlrev_b32_e32 v202, 16, v71
	v_and_b32_e32 v203, 0xffff0000, v71
	v_lshlrev_b32_e32 v204, 16, v102
	v_and_b32_e32 v205, 0xffff0000, v102
	v_lshlrev_b32_e32 v206, 16, v103
	v_and_b32_e32 v207, 0xffff0000, v103
	v_mul_f32_e32 v200, v214, v200
	v_mul_f32_e32 v201, v214, v201
	v_mul_f32_e32 v202, v214, v202
	v_mul_f32_e32 v203, v214, v203
	v_mul_f32_e32 v204, v215, v204
	v_mul_f32_e32 v205, v215, v205
	v_mul_f32_e32 v206, v215, v206
	v_mul_f32_e32 v207, v215, v207
	v_fmac_f32_e32 v12, v140, v200
	v_fmac_f32_e32 v13, v141, v201
	v_fmac_f32_e32 v14, v142, v202
	v_fmac_f32_e32 v15, v143, v203
	v_fmac_f32_e32 v12, v172, v204
	v_fmac_f32_e32 v13, v173, v205
	v_fmac_f32_e32 v14, v174, v206
	v_fmac_f32_e32 v15, v175, v207
	global_store_dwordx4 v192, v[12:15], s[18:19] offset:3072
	v_lshlrev_b32_e32 v200, 16, v72
	v_and_b32_e32 v201, 0xffff0000, v72
	v_lshlrev_b32_e32 v202, 16, v73
	v_and_b32_e32 v203, 0xffff0000, v73
	v_lshlrev_b32_e32 v204, 16, v104
	v_and_b32_e32 v205, 0xffff0000, v104
	v_lshlrev_b32_e32 v206, 16, v105
	v_and_b32_e32 v207, 0xffff0000, v105
	v_mul_f32_e32 v200, v214, v200
	v_mul_f32_e32 v201, v214, v201
	v_mul_f32_e32 v202, v214, v202
	v_mul_f32_e32 v203, v214, v203
	v_mul_f32_e32 v204, v215, v204
	v_mul_f32_e32 v205, v215, v205
	v_mul_f32_e32 v206, v215, v206
	v_mul_f32_e32 v207, v215, v207
	v_fmac_f32_e32 v16, v144, v200
	v_fmac_f32_e32 v17, v145, v201
	v_fmac_f32_e32 v18, v146, v202
	v_fmac_f32_e32 v19, v147, v203
	v_fmac_f32_e32 v16, v176, v204
	v_fmac_f32_e32 v17, v177, v205
	v_fmac_f32_e32 v18, v178, v206
	v_fmac_f32_e32 v19, v179, v207
	global_store_dwordx4 v193, v[16:19], s[18:19] offset:0
	v_lshlrev_b32_e32 v200, 16, v74
	v_and_b32_e32 v201, 0xffff0000, v74
	v_lshlrev_b32_e32 v202, 16, v75
	v_and_b32_e32 v203, 0xffff0000, v75
	v_lshlrev_b32_e32 v204, 16, v106
	v_and_b32_e32 v205, 0xffff0000, v106
	v_lshlrev_b32_e32 v206, 16, v107
	v_and_b32_e32 v207, 0xffff0000, v107
	v_mul_f32_e32 v200, v214, v200
	v_mul_f32_e32 v201, v214, v201
	v_mul_f32_e32 v202, v214, v202
	v_mul_f32_e32 v203, v214, v203
	v_mul_f32_e32 v204, v215, v204
	v_mul_f32_e32 v205, v215, v205
	v_mul_f32_e32 v206, v215, v206
	v_mul_f32_e32 v207, v215, v207
	v_fmac_f32_e32 v20, v148, v200
	v_fmac_f32_e32 v21, v149, v201
	v_fmac_f32_e32 v22, v150, v202
	v_fmac_f32_e32 v23, v151, v203
	v_fmac_f32_e32 v20, v180, v204
	v_fmac_f32_e32 v21, v181, v205
	v_fmac_f32_e32 v22, v182, v206
	v_fmac_f32_e32 v23, v183, v207
	global_store_dwordx4 v193, v[20:23], s[18:19] offset:1024
	v_lshlrev_b32_e32 v200, 16, v76
	v_and_b32_e32 v201, 0xffff0000, v76
	v_lshlrev_b32_e32 v202, 16, v77
	v_and_b32_e32 v203, 0xffff0000, v77
	v_lshlrev_b32_e32 v204, 16, v108
	v_and_b32_e32 v205, 0xffff0000, v108
	v_lshlrev_b32_e32 v206, 16, v109
	v_and_b32_e32 v207, 0xffff0000, v109
	v_mul_f32_e32 v200, v214, v200
	v_mul_f32_e32 v201, v214, v201
	v_mul_f32_e32 v202, v214, v202
	v_mul_f32_e32 v203, v214, v203
	v_mul_f32_e32 v204, v215, v204
	v_mul_f32_e32 v205, v215, v205
; __device__ __forceinline__ float bf_lo(unsigned w) { return __uint_as_float(w << 16); }
; __device__ __forceinline__ float bf_hi(unsigned w) { return __uint_as_float(w & 0xffff0000u); }
; __global__ void __launch_bounds__(NWAVES * 64, 2) mk_fwd(Args args) {
;     ...
;         for (int row0 = rbeg; row0 < rbeg + per2 && row0 < ML; row0 += 2) {
;             f32x4 v[2][8]; u32x2 yw[2][8];
; #pragma unroll
;             for (int q = 0; q < 2; ++q) { const int row = row0 + q; load_row_f32(args.out + (size_t)row * DM, F.lane, v[q]);
;                 const bf16_t* yr = Y + (size_t)row * DM;
; #pragma unroll
;                 for (int j = 0; j < 8; ++j) yw[q][j] = *(const u32x2*)(yr + 4 * F.lane + 256 * j); }
; #pragma unroll
;             for (int q = 0; q < 2; ++q) { const int row = row0 + q; const int r = row / SEQ;
;                 if (r != rcur) { const float* m1 = mod + (size_t)(9 + r) * 6144; rcur = r;
; #pragma unroll
;                     for (int j = 0; j < 8; ++j) { const int col = 4 * F.lane + 256 * j; PA[j] = *(const f32x4*)(m1 + 2 * DM + col) * *(const f32x4*)(post_norm + DM + col); } }
;                 float sy = 0.f;
; #pragma unroll
;                 for (int j = 0; j < 8; ++j) { const float a = bf_lo(yw[q][j].x), b = bf_hi(yw[q][j].x), c2 = bf_lo(yw[q][j].y), d = bf_hi(yw[q][j].y); sy += (a * a + b * b) + (c2 * c2 + d * d); }
;                 const float rsy = __builtin_amdgcn_rsqf(wave_sum(sy) * (1.f / DM) + EPS);
	v_mul_f32_e32 v206, v215, v206
	v_mul_f32_e32 v207, v215, v207
	v_fmac_f32_e32 v24, v152, v200
	v_fmac_f32_e32 v25, v153, v201
	v_fmac_f32_e32 v26, v154, v202
	v_fmac_f32_e32 v27, v155, v203
	v_fmac_f32_e32 v24, v184, v204
	v_fmac_f32_e32 v25, v185, v205
	v_fmac_f32_e32 v26, v186, v206
	v_fmac_f32_e32 v27, v187, v207
	global_store_dwordx4 v193, v[24:27], s[18:19] offset:2048
	v_lshlrev_b32_e32 v200, 16, v78
	v_and_b32_e32 v201, 0xffff0000, v78
	v_lshlrev_b32_e32 v202, 16, v79
	v_and_b32_e32 v203, 0xffff0000, v79
	v_lshlrev_b32_e32 v204, 16, v110
	v_and_b32_e32 v205, 0xffff0000, v110
	v_lshlrev_b32_e32 v206, 16, v111
	v_and_b32_e32 v207, 0xffff0000, v111
	v_mul_f32_e32 v200, v214, v200
	v_mul_f32_e32 v201, v214, v201
	v_mul_f32_e32 v202, v214, v202
	v_mul_f32_e32 v203, v214, v203
	v_mul_f32_e32 v204, v215, v204
	v_mul_f32_e32 v205, v215, v205
	v_mul_f32_e32 v206, v215, v206
	v_mul_f32_e32 v207, v215, v207
	v_fmac_f32_e32 v28, v156, v200
	v_fmac_f32_e32 v29, v157, v201
	v_fmac_f32_e32 v30, v158, v202
	v_fmac_f32_e32 v31, v159, v203
	v_fmac_f32_e32 v28, v188, v204
	v_fmac_f32_e32 v29, v189, v205
	v_fmac_f32_e32 v30, v190, v206
	v_fmac_f32_e32 v31, v191, v207
	global_store_dwordx4 v193, v[28:31], s[18:19] offset:3072
	s_add_u32 s18, s18, 0x2000
	s_addc_u32 s19, s19, 0
	global_load_dwordx4 v[0:3], v192, s[14:15] offset:0 nt
	global_load_dwordx4 v[4:7], v192, s[14:15] offset:1024 nt
	global_load_dwordx4 v[8:11], v192, s[14:15] offset:2048 nt
	global_load_dwordx4 v[12:15], v192, s[14:15] offset:3072 nt
	global_load_dwordx4 v[16:19], v193, s[14:15] offset:0 nt
	global_load_dwordx4 v[20:23], v193, s[14:15] offset:1024 nt
	global_load_dwordx4 v[24:27], v193, s[14:15] offset:2048 nt
	global_load_dwordx4 v[28:31], v193, s[14:15] offset:3072 nt
	global_load_dwordx2 v[64:65], v194, s[16:17] offset:0
	global_load_dwordx2 v[66:67], v194, s[16:17] offset:512
	global_load_dwordx2 v[68:69], v194, s[16:17] offset:1024
	global_load_dwordx2 v[70:71], v194, s[16:17] offset:1536
	global_load_dwordx2 v[72:73], v194, s[16:17] offset:2048
	global_load_dwordx2 v[74:75], v194, s[16:17] offset:2560
	global_load_dwordx2 v[76:77], v194, s[16:17] offset:3072
	global_load_dwordx2 v[78:79], v194, s[16:17] offset:3584
	global_load_dwordx2 v[96:97], v194, s[22:23] offset:0
	global_load_dwordx2 v[98:99], v194, s[22:23] offset:512
	global_load_dwordx2 v[100:101], v194, s[22:23] offset:1024
	global_load_dwordx2 v[102:103], v194, s[22:23] offset:1536
	global_load_dwordx2 v[104:105], v194, s[22:23] offset:2048
	global_load_dwordx2 v[106:107], v194, s[22:23] offset:2560
	global_load_dwordx2 v[108:109], v194, s[22:23] offset:3072
	global_load_dwordx2 v[110:111], v194, s[22:23] offset:3584
	s_add_u32 s14, s14, 0x2000
	s_addc_u32 s15, s15, 0
	s_add_u32 s16, s16, 0x1000
	s_addc_u32 s17, s17, 0
	s_add_u32 s22, s22, 0x1000
	s_addc_u32 s23, s23, 0
	s_waitcnt vmcnt(32)
	v_lshlrev_b32_e32 v200, 16, v80
	v_and_b32_e32 v201, 0xffff0000, v80
	v_lshlrev_b32_e32 v202, 16, v81
	v_and_b32_e32 v203, 0xffff0000, v81
	v_mul_f32_e32 v208, v200, v200
	v_mul_f32_e32 v209, v201, v201
	v_fmac_f32_e32 v208, v202, v202
	v_fmac_f32_e32 v209, v203, v203
	v_lshlrev_b32_e32 v204, 16, v112
	v_and_b32_e32 v205, 0xffff0000, v112
	v_lshlrev_b32_e32 v206, 16, v113
	v_and_b32_e32 v207, 0xffff0000, v113
	v_mul_f32_e32 v210, v204, v204
	v_mul_f32_e32 v211, v205, v205
	v_fmac_f32_e32 v210, v206, v206
	v_fmac_f32_e32 v211, v207, v207
	v_lshlrev_b32_e32 v200, 16, v82
	v_and_b32_e32 v201, 0xffff0000, v82
	v_lshlrev_b32_e32 v202, 16, v83
	v_and_b32_e32 v203, 0xffff0000, v83
	v_fmac_f32_e32 v208, v200, v200
	v_fmac_f32_e32 v209, v201, v201
	v_fmac_f32_e32 v208, v202, v202
	v_fmac_f32_e32 v209, v203, v203
	v_lshlrev_b32_e32 v204, 16, v114
	v_and_b32_e32 v205, 0xffff0000, v114
	v_lshlrev_b32_e32 v206, 16, v115
	v_and_b32_e32 v207, 0xffff0000, v115
	v_fmac_f32_e32 v210, v204, v204
	v_fmac_f32_e32 v211, v205, v205
	v_fmac_f32_e32 v210, v206, v206
	v_fmac_f32_e32 v211, v207, v207
	v_lshlrev_b32_e32 v200, 16, v84
	v_and_b32_e32 v201, 0xffff0000, v84
	v_lshlrev_b32_e32 v202, 16, v85
	v_and_b32_e32 v203, 0xffff0000, v85
	v_fmac_f32_e32 v208, v200, v200
	v_fmac_f32_e32 v209, v201, v201
	v_fmac_f32_e32 v208, v202, v202
	v_fmac_f32_e32 v209, v203, v203
	v_lshlrev_b32_e32 v204, 16, v116
	v_and_b32_e32 v205, 0xffff0000, v116
	v_lshlrev_b32_e32 v206, 16, v117
	v_and_b32_e32 v207, 0xffff0000, v117
	v_fmac_f32_e32 v210, v204, v204
	v_fmac_f32_e32 v211, v205, v205
	v_fmac_f32_e32 v210, v206, v206
	v_fmac_f32_e32 v211, v207, v207
	v_lshlrev_b32_e32 v200, 16, v86
	v_and_b32_e32 v201, 0xffff0000, v86
	v_lshlrev_b32_e32 v202, 16, v87
	v_and_b32_e32 v203, 0xffff0000, v87
	v_fmac_f32_e32 v208, v200, v200
	v_fmac_f32_e32 v209, v201, v201
	v_fmac_f32_e32 v208, v202, v202
	v_fmac_f32_e32 v209, v203, v203
	v_lshlrev_b32_e32 v204, 16, v118
	v_and_b32_e32 v205, 0xffff0000, v118
	v_lshlrev_b32_e32 v206, 16, v119
	v_and_b32_e32 v207, 0xffff0000, v119
	v_fmac_f32_e32 v210, v204, v204
	v_fmac_f32_e32 v211, v205, v205
	v_fmac_f32_e32 v210, v206, v206
	v_fmac_f32_e32 v211, v207, v207
	v_lshlrev_b32_e32 v200, 16, v88
	v_and_b32_e32 v201, 0xffff0000, v88
	v_lshlrev_b32_e32 v202, 16, v89
	v_and_b32_e32 v203, 0xffff0000, v89
	v_fmac_f32_e32 v208, v200, v200
	v_fmac_f32_e32 v209, v201, v201
	v_fmac_f32_e32 v208, v202, v202
	v_fmac_f32_e32 v209, v203, v203
	v_lshlrev_b32_e32 v204, 16, v120
	v_and_b32_e32 v205, 0xffff0000, v120
	v_lshlrev_b32_e32 v206, 16, v121
	v_and_b32_e32 v207, 0xffff0000, v121
	v_fmac_f32_e32 v210, v204, v204
	v_fmac_f32_e32 v211, v205, v205
	v_fmac_f32_e32 v210, v206, v206
	v_fmac_f32_e32 v211, v207, v207
	v_lshlrev_b32_e32 v200, 16, v90
; __device__ __forceinline__ float bf_lo(unsigned w) { return __uint_as_float(w << 16); }
; __device__ __forceinline__ float bf_hi(unsigned w) { return __uint_as_float(w & 0xffff0000u); }
; __global__ void __launch_bounds__(NWAVES * 64, 2) mk_fwd(Args args) {
;     ...
;                 float sy = 0.f;
; #pragma unroll
;                 for (int j = 0; j < 8; ++j) { const float a = bf_lo(yw[q][j].x), b = bf_hi(yw[q][j].x), c2 = bf_lo(yw[q][j].y), d = bf_hi(yw[q][j].y); sy += (a * a + b * b) + (c2 * c2 + d * d); }
;                 const float rsy = __builtin_amdgcn_rsqf(wave_sum(sy) * (1.f / DM) + EPS);
; #pragma unroll
;                 for (int j = 0; j < 8; ++j) { const int col = 4 * F.lane + 256 * j;
;                     const f32x4 y4 = (f32x4){bf_lo(yw[q][j].x), bf_hi(yw[q][j].x), bf_lo(yw[q][j].y), bf_hi(yw[q][j].y)};
;                     *(f32x4*)(args.out + (size_t)row * DM + col) = v[q][j] + PA[j] * (y4 * rsy); }
	v_and_b32_e32 v201, 0xffff0000, v90
	v_lshlrev_b32_e32 v202, 16, v91
	v_and_b32_e32 v203, 0xffff0000, v91
	v_fmac_f32_e32 v208, v200, v200
	v_fmac_f32_e32 v209, v201, v201
	v_fmac_f32_e32 v208, v202, v202
	v_fmac_f32_e32 v209, v203, v203
	v_lshlrev_b32_e32 v204, 16, v122
	v_and_b32_e32 v205, 0xffff0000, v122
	v_lshlrev_b32_e32 v206, 16, v123
	v_and_b32_e32 v207, 0xffff0000, v123
	v_fmac_f32_e32 v210, v204, v204
	v_fmac_f32_e32 v211, v205, v205
	v_fmac_f32_e32 v210, v206, v206
	v_fmac_f32_e32 v211, v207, v207
	v_lshlrev_b32_e32 v200, 16, v92
	v_and_b32_e32 v201, 0xffff0000, v92
	v_lshlrev_b32_e32 v202, 16, v93
	v_and_b32_e32 v203, 0xffff0000, v93
	v_fmac_f32_e32 v208, v200, v200
	v_fmac_f32_e32 v209, v201, v201
	v_fmac_f32_e32 v208, v202, v202
	v_fmac_f32_e32 v209, v203, v203
	v_lshlrev_b32_e32 v204, 16, v124
	v_and_b32_e32 v205, 0xffff0000, v124
	v_lshlrev_b32_e32 v206, 16, v125
	v_and_b32_e32 v207, 0xffff0000, v125
	v_fmac_f32_e32 v210, v204, v204
	v_fmac_f32_e32 v211, v205, v205
	v_fmac_f32_e32 v210, v206, v206
	v_fmac_f32_e32 v211, v207, v207
	v_lshlrev_b32_e32 v200, 16, v94
	v_and_b32_e32 v201, 0xffff0000, v94
	v_lshlrev_b32_e32 v202, 16, v95
	v_and_b32_e32 v203, 0xffff0000, v95
	v_fmac_f32_e32 v208, v200, v200
	v_fmac_f32_e32 v209, v201, v201
	v_fmac_f32_e32 v208, v202, v202
	v_fmac_f32_e32 v209, v203, v203
	v_lshlrev_b32_e32 v204, 16, v126
	v_and_b32_e32 v205, 0xffff0000, v126
	v_lshlrev_b32_e32 v206, 16, v127
	v_and_b32_e32 v207, 0xffff0000, v127
	v_fmac_f32_e32 v210, v204, v204
	v_fmac_f32_e32 v211, v205, v205
	v_fmac_f32_e32 v210, v206, v206
	v_fmac_f32_e32 v211, v207, v207
	v_add_f32_e32 v208, v208, v209
	v_add_f32_e32 v210, v210, v211
	s_nop 0
	v_add_f32_dpp v212, v208, v208 quad_perm:[1,0,3,2] row_mask:0xf bank_mask:0xf
	v_add_f32_dpp v213, v210, v210 quad_perm:[1,0,3,2] row_mask:0xf bank_mask:0xf
	s_nop 0
	v_add_f32_dpp v212, v212, v212 quad_perm:[2,3,0,1] row_mask:0xf bank_mask:0xf
	v_add_f32_dpp v213, v213, v213 quad_perm:[2,3,0,1] row_mask:0xf bank_mask:0xf
	s_nop 0
	v_add_f32_dpp v212, v212, v212 row_half_mirror row_mask:0xf bank_mask:0xf
	v_add_f32_dpp v213, v213, v213 row_half_mirror row_mask:0xf bank_mask:0xf
	s_nop 0
	v_add_f32_dpp v212, v212, v212 row_mirror row_mask:0xf bank_mask:0xf
	v_add_f32_dpp v213, v213, v213 row_mirror row_mask:0xf bank_mask:0xf
	s_nop 0
	v_readlane_b32 s4, v212, 0
	v_readlane_b32 s5, v212, 16
	v_readlane_b32 s6, v212, 32
	v_readlane_b32 s7, v212, 48
	v_readlane_b32 s24, v213, 0
	v_readlane_b32 s25, v213, 16
	v_readlane_b32 s26, v213, 32
	v_readlane_b32 s27, v213, 48
	s_nop 1
	v_mov_b32_e32 v214, s4
	v_mov_b32_e32 v215, s24
	v_add_f32_e32 v214, s5, v214
	v_add_f32_e32 v215, s25, v215
	v_add_f32_e32 v214, s6, v214
	v_add_f32_e32 v215, s26, v215
	v_add_f32_e32 v214, s7, v214
	v_add_f32_e32 v215, s27, v215
	v_fmamk_f32 v214, v214, 0x3a000000, v195
	v_fmamk_f32 v215, v215, 0x3a000000, v195
	v_rsq_f32_e32 v214, v214
	v_rsq_f32_e32 v215, v215
	s_nop 0
	v_lshlrev_b32_e32 v200, 16, v80
	v_and_b32_e32 v201, 0xffff0000, v80
	v_lshlrev_b32_e32 v202, 16, v81
	v_and_b32_e32 v203, 0xffff0000, v81
	v_lshlrev_b32_e32 v204, 16, v112
	v_and_b32_e32 v205, 0xffff0000, v112
	v_lshlrev_b32_e32 v206, 16, v113
	v_and_b32_e32 v207, 0xffff0000, v113
	v_mul_f32_e32 v200, v214, v200
	v_mul_f32_e32 v201, v214, v201
	v_mul_f32_e32 v202, v214, v202
	v_mul_f32_e32 v203, v214, v203
	v_mul_f32_e32 v204, v215, v204
	v_mul_f32_e32 v205, v215, v205
	v_mul_f32_e32 v206, v215, v206
	v_mul_f32_e32 v207, v215, v207
	v_fmac_f32_e32 v32, v128, v200
	v_fmac_f32_e32 v33, v129, v201
	v_fmac_f32_e32 v34, v130, v202
	v_fmac_f32_e32 v35, v131, v203
	v_fmac_f32_e32 v32, v160, v204
	v_fmac_f32_e32 v33, v161, v205
	v_fmac_f32_e32 v34, v162, v206
	v_fmac_f32_e32 v35, v163, v207
	global_store_dwordx4 v192, v[32:35], s[18:19] offset:0
	v_lshlrev_b32_e32 v200, 16, v82
	v_and_b32_e32 v201, 0xffff0000, v82
	v_lshlrev_b32_e32 v202, 16, v83
	v_and_b32_e32 v203, 0xffff0000, v83
	v_lshlrev_b32_e32 v204, 16, v114
	v_and_b32_e32 v205, 0xffff0000, v114
	v_lshlrev_b32_e32 v206, 16, v115
	v_and_b32_e32 v207, 0xffff0000, v115
	v_mul_f32_e32 v200, v214, v200
	v_mul_f32_e32 v201, v214, v201
	v_mul_f32_e32 v202, v214, v202
	v_mul_f32_e32 v203, v214, v203
	v_mul_f32_e32 v204, v215, v204
	v_mul_f32_e32 v205, v215, v205
	v_mul_f32_e32 v206, v215, v206
	v_mul_f32_e32 v207, v215, v207
	v_fmac_f32_e32 v36, v132, v200
	v_fmac_f32_e32 v37, v133, v201
	v_fmac_f32_e32 v38, v134, v202
	v_fmac_f32_e32 v39, v135, v203
	v_fmac_f32_e32 v36, v164, v204
	v_fmac_f32_e32 v37, v165, v205
	v_fmac_f32_e32 v38, v166, v206
	v_fmac_f32_e32 v39, v167, v207
	global_store_dwordx4 v192, v[36:39], s[18:19] offset:1024
	v_lshlrev_b32_e32 v200, 16, v84
	v_and_b32_e32 v201, 0xffff0000, v84
	v_lshlrev_b32_e32 v202, 16, v85
	v_and_b32_e32 v203, 0xffff0000, v85
	v_lshlrev_b32_e32 v204, 16, v116
	v_and_b32_e32 v205, 0xffff0000, v116
	v_lshlrev_b32_e32 v206, 16, v117
	v_and_b32_e32 v207, 0xffff0000, v117
	v_mul_f32_e32 v200, v214, v200
	v_mul_f32_e32 v201, v214, v201
	v_mul_f32_e32 v202, v214, v202
	v_mul_f32_e32 v203, v214, v203
	v_mul_f32_e32 v204, v215, v204
	v_mul_f32_e32 v205, v215, v205
	v_mul_f32_e32 v206, v215, v206
	v_mul_f32_e32 v207, v215, v207
	v_fmac_f32_e32 v40, v136, v200
	v_fmac_f32_e32 v41, v137, v201
	v_fmac_f32_e32 v42, v138, v202
	v_fmac_f32_e32 v43, v139, v203
	v_fmac_f32_e32 v40, v168, v204
	v_fmac_f32_e32 v41, v169, v205
	v_fmac_f32_e32 v42, v170, v206
	v_fmac_f32_e32 v43, v171, v207
	global_store_dwordx4 v192, v[40:43], s[18:19] offset:2048
	v_lshlrev_b32_e32 v200, 16, v86
	v_and_b32_e32 v201, 0xffff0000, v86
	v_lshlrev_b32_e32 v202, 16, v87
	v_and_b32_e32 v203, 0xffff0000, v87
; __device__ __forceinline__ float bf_lo(unsigned w) { return __uint_as_float(w << 16); }
; __device__ __forceinline__ float bf_hi(unsigned w) { return __uint_as_float(w & 0xffff0000u); }
; __global__ void __launch_bounds__(NWAVES * 64, 2) mk_fwd(Args args) {
;     ...
;         for (int row0 = rbeg; row0 < rbeg + per2 && row0 < ML; row0 += 2) {
;             f32x4 v[2][8]; u32x2 yw[2][8];
; #pragma unroll
;             for (int q = 0; q < 2; ++q) { const int row = row0 + q; load_row_f32(args.out + (size_t)row * DM, F.lane, v[q]);
;                 const bf16_t* yr = Y + (size_t)row * DM;
; #pragma unroll
;                 for (int j = 0; j < 8; ++j) yw[q][j] = *(const u32x2*)(yr + 4 * F.lane + 256 * j); }
; #pragma unroll
;             for (int q = 0; q < 2; ++q) { const int row = row0 + q; const int r = row / SEQ;
;                 if (r != rcur) { const float* m1 = mod + (size_t)(9 + r) * 6144; rcur = r;
; #pragma unroll
;                     for (int j = 0; j < 8; ++j) { const int col = 4 * F.lane + 256 * j; PA[j] = *(const f32x4*)(m1 + 2 * DM + col) * *(const f32x4*)(post_norm + DM + col); } }
;                 float sy = 0.f;
; #pragma unroll
;                 for (int j = 0; j < 8; ++j) { const float a = bf_lo(yw[q][j].x), b = bf_hi(yw[q][j].x), c2 = bf_lo(yw[q][j].y), d = bf_hi(yw[q][j].y); sy += (a * a + b * b) + (c2 * c2 + d * d); }
;                 const float rsy = __builtin_amdgcn_rsqf(wave_sum(sy) * (1.f / DM) + EPS);
; #pragma unroll
;                 for (int j = 0; j < 8; ++j) { const int col = 4 * F.lane + 256 * j;
;                     const f32x4 y4 = (f32x4){bf_lo(yw[q][j].x), bf_hi(yw[q][j].x), bf_lo(yw[q][j].y), bf_hi(yw[q][j].y)};
;                     *(f32x4*)(args.out + (size_t)row * DM + col) = v[q][j] + PA[j] * (y4 * rsy); }
	v_lshlrev_b32_e32 v204, 16, v118
	v_and_b32_e32 v205, 0xffff0000, v118
	v_lshlrev_b32_e32 v206, 16, v119
	v_and_b32_e32 v207, 0xffff0000, v119
	v_mul_f32_e32 v200, v214, v200
	v_mul_f32_e32 v201, v214, v201
	v_mul_f32_e32 v202, v214, v202
	v_mul_f32_e32 v203, v214, v203
	v_mul_f32_e32 v204, v215, v204
	v_mul_f32_e32 v205, v215, v205
	v_mul_f32_e32 v206, v215, v206
	v_mul_f32_e32 v207, v215, v207
	v_fmac_f32_e32 v44, v140, v200
	v_fmac_f32_e32 v45, v141, v201
	v_fmac_f32_e32 v46, v142, v202
	v_fmac_f32_e32 v47, v143, v203
	v_fmac_f32_e32 v44, v172, v204
	v_fmac_f32_e32 v45, v173, v205
	v_fmac_f32_e32 v46, v174, v206
	v_fmac_f32_e32 v47, v175, v207
	global_store_dwordx4 v192, v[44:47], s[18:19] offset:3072
	v_lshlrev_b32_e32 v200, 16, v88
	v_and_b32_e32 v201, 0xffff0000, v88
	v_lshlrev_b32_e32 v202, 16, v89
	v_and_b32_e32 v203, 0xffff0000, v89
	v_lshlrev_b32_e32 v204, 16, v120
	v_and_b32_e32 v205, 0xffff0000, v120
	v_lshlrev_b32_e32 v206, 16, v121
	v_and_b32_e32 v207, 0xffff0000, v121
	v_mul_f32_e32 v200, v214, v200
	v_mul_f32_e32 v201, v214, v201
	v_mul_f32_e32 v202, v214, v202
	v_mul_f32_e32 v203, v214, v203
	v_mul_f32_e32 v204, v215, v204
	v_mul_f32_e32 v205, v215, v205
	v_mul_f32_e32 v206, v215, v206
	v_mul_f32_e32 v207, v215, v207
	v_fmac_f32_e32 v48, v144, v200
	v_fmac_f32_e32 v49, v145, v201
	v_fmac_f32_e32 v50, v146, v202
	v_fmac_f32_e32 v51, v147, v203
	v_fmac_f32_e32 v48, v176, v204
	v_fmac_f32_e32 v49, v177, v205
	v_fmac_f32_e32 v50, v178, v206
	v_fmac_f32_e32 v51, v179, v207
	global_store_dwordx4 v193, v[48:51], s[18:19] offset:0
	v_lshlrev_b32_e32 v200, 16, v90
	v_and_b32_e32 v201, 0xffff0000, v90
	v_lshlrev_b32_e32 v202, 16, v91
	v_and_b32_e32 v203, 0xffff0000, v91
	v_lshlrev_b32_e32 v204, 16, v122
	v_and_b32_e32 v205, 0xffff0000, v122
	v_lshlrev_b32_e32 v206, 16, v123
	v_and_b32_e32 v207, 0xffff0000, v123
	v_mul_f32_e32 v200, v214, v200
	v_mul_f32_e32 v201, v214, v201
	v_mul_f32_e32 v202, v214, v202
	v_mul_f32_e32 v203, v214, v203
	v_mul_f32_e32 v204, v215, v204
	v_mul_f32_e32 v205, v215, v205
	v_mul_f32_e32 v206, v215, v206
	v_mul_f32_e32 v207, v215, v207
	v_fmac_f32_e32 v52, v148, v200
	v_fmac_f32_e32 v53, v149, v201
	v_fmac_f32_e32 v54, v150, v202
	v_fmac_f32_e32 v55, v151, v203
	v_fmac_f32_e32 v52, v180, v204
	v_fmac_f32_e32 v53, v181, v205
	v_fmac_f32_e32 v54, v182, v206
	v_fmac_f32_e32 v55, v183, v207
	global_store_dwordx4 v193, v[52:55], s[18:19] offset:1024
	v_lshlrev_b32_e32 v200, 16, v92
	v_and_b32_e32 v201, 0xffff0000, v92
	v_lshlrev_b32_e32 v202, 16, v93
	v_and_b32_e32 v203, 0xffff0000, v93
	v_lshlrev_b32_e32 v204, 16, v124
	v_and_b32_e32 v205, 0xffff0000, v124
	v_lshlrev_b32_e32 v206, 16, v125
	v_and_b32_e32 v207, 0xffff0000, v125
	v_mul_f32_e32 v200, v214, v200
	v_mul_f32_e32 v201, v214, v201
	v_mul_f32_e32 v202, v214, v202
	v_mul_f32_e32 v203, v214, v203
	v_mul_f32_e32 v204, v215, v204
	v_mul_f32_e32 v205, v215, v205
	v_mul_f32_e32 v206, v215, v206
	v_mul_f32_e32 v207, v215, v207
	v_fmac_f32_e32 v56, v152, v200
	v_fmac_f32_e32 v57, v153, v201
	v_fmac_f32_e32 v58, v154, v202
	v_fmac_f32_e32 v59, v155, v203
	v_fmac_f32_e32 v56, v184, v204
	v_fmac_f32_e32 v57, v185, v205
	v_fmac_f32_e32 v58, v186, v206
	v_fmac_f32_e32 v59, v187, v207
	global_store_dwordx4 v193, v[56:59], s[18:19] offset:2048
	v_lshlrev_b32_e32 v200, 16, v94
	v_and_b32_e32 v201, 0xffff0000, v94
	v_lshlrev_b32_e32 v202, 16, v95
	v_and_b32_e32 v203, 0xffff0000, v95
	v_lshlrev_b32_e32 v204, 16, v126
	v_and_b32_e32 v205, 0xffff0000, v126
	v_lshlrev_b32_e32 v206, 16, v127
	v_and_b32_e32 v207, 0xffff0000, v127
	v_mul_f32_e32 v200, v214, v200
	v_mul_f32_e32 v201, v214, v201
	v_mul_f32_e32 v202, v214, v202
	v_mul_f32_e32 v203, v214, v203
	v_mul_f32_e32 v204, v215, v204
	v_mul_f32_e32 v205, v215, v205
	v_mul_f32_e32 v206, v215, v206
	v_mul_f32_e32 v207, v215, v207
	v_fmac_f32_e32 v60, v156, v200
	v_fmac_f32_e32 v61, v157, v201
	v_fmac_f32_e32 v62, v158, v202
	v_fmac_f32_e32 v63, v159, v203
	v_fmac_f32_e32 v60, v188, v204
	v_fmac_f32_e32 v61, v189, v205
	v_fmac_f32_e32 v62, v190, v206
	v_fmac_f32_e32 v63, v191, v207
	global_store_dwordx4 v193, v[60:63], s[18:19] offset:3072
	s_add_u32 s18, s18, 0x2000
	s_addc_u32 s19, s19, 0
	global_load_dwordx4 v[32:35], v192, s[14:15] offset:0 nt
	global_load_dwordx4 v[36:39], v192, s[14:15] offset:1024 nt
	global_load_dwordx4 v[40:43], v192, s[14:15] offset:2048 nt
	global_load_dwordx4 v[44:47], v192, s[14:15] offset:3072 nt
	global_load_dwordx4 v[48:51], v193, s[14:15] offset:0 nt
	global_load_dwordx4 v[52:55], v193, s[14:15] offset:1024 nt
	global_load_dwordx4 v[56:59], v193, s[14:15] offset:2048 nt
	global_load_dwordx4 v[60:63], v193, s[14:15] offset:3072 nt
	global_load_dwordx2 v[80:81], v194, s[16:17] offset:0
	global_load_dwordx2 v[82:83], v194, s[16:17] offset:512
	global_load_dwordx2 v[84:85], v194, s[16:17] offset:1024
	global_load_dwordx2 v[86:87], v194, s[16:17] offset:1536
	global_load_dwordx2 v[88:89], v194, s[16:17] offset:2048
	global_load_dwordx2 v[90:91], v194, s[16:17] offset:2560
	global_load_dwordx2 v[92:93], v194, s[16:17] offset:3072
	global_load_dwordx2 v[94:95], v194, s[16:17] offset:3584
	global_load_dwordx2 v[112:113], v194, s[22:23] offset:0
	global_load_dwordx2 v[114:115], v194, s[22:23] offset:512
	global_load_dwordx2 v[116:117], v194, s[22:23] offset:1024
	global_load_dwordx2 v[118:119], v194, s[22:23] offset:1536
	global_load_dwordx2 v[120:121], v194, s[22:23] offset:2048
	global_load_dwordx2 v[122:123], v194, s[22:23] offset:2560
	global_load_dwordx2 v[124:125], v194, s[22:23] offset:3072
	global_load_dwordx2 v[126:127], v194, s[22:23] offset:3584
	s_add_u32 s14, s14, 0x2000
	s_addc_u32 s15, s15, 0
	s_add_u32 s16, s16, 0x1000
	s_addc_u32 s17, s17, 0
	s_add_u32 s22, s22, 0x1000
	s_addc_u32 s23, s23, 0
	s_waitcnt vmcnt(32)
; __device__ __forceinline__ float bf_lo(unsigned w) { return __uint_as_float(w << 16); }
; __device__ __forceinline__ float bf_hi(unsigned w) { return __uint_as_float(w & 0xffff0000u); }
; __global__ void __launch_bounds__(NWAVES * 64, 2) mk_fwd(Args args) {
;     ...
;                 float sy = 0.f;
; #pragma unroll
;                 for (int j = 0; j < 8; ++j) { const float a = bf_lo(yw[q][j].x), b = bf_hi(yw[q][j].x), c2 = bf_lo(yw[q][j].y), d = bf_hi(yw[q][j].y); sy += (a * a + b * b) + (c2 * c2 + d * d); }
;                 const float rsy = __builtin_amdgcn_rsqf(wave_sum(sy) * (1.f / DM) + EPS);
	v_lshlrev_b32_e32 v200, 16, v64
	v_and_b32_e32 v201, 0xffff0000, v64
	v_lshlrev_b32_e32 v202, 16, v65
	v_and_b32_e32 v203, 0xffff0000, v65
	v_mul_f32_e32 v208, v200, v200
	v_mul_f32_e32 v209, v201, v201
	v_fmac_f32_e32 v208, v202, v202
	v_fmac_f32_e32 v209, v203, v203
	v_lshlrev_b32_e32 v204, 16, v96
	v_and_b32_e32 v205, 0xffff0000, v96
	v_lshlrev_b32_e32 v206, 16, v97
	v_and_b32_e32 v207, 0xffff0000, v97
	v_mul_f32_e32 v210, v204, v204
	v_mul_f32_e32 v211, v205, v205
	v_fmac_f32_e32 v210, v206, v206
	v_fmac_f32_e32 v211, v207, v207
	v_lshlrev_b32_e32 v200, 16, v66
	v_and_b32_e32 v201, 0xffff0000, v66
	v_lshlrev_b32_e32 v202, 16, v67
	v_and_b32_e32 v203, 0xffff0000, v67
	v_fmac_f32_e32 v208, v200, v200
	v_fmac_f32_e32 v209, v201, v201
	v_fmac_f32_e32 v208, v202, v202
	v_fmac_f32_e32 v209, v203, v203
	v_lshlrev_b32_e32 v204, 16, v98
	v_and_b32_e32 v205, 0xffff0000, v98
	v_lshlrev_b32_e32 v206, 16, v99
	v_and_b32_e32 v207, 0xffff0000, v99
	v_fmac_f32_e32 v210, v204, v204
	v_fmac_f32_e32 v211, v205, v205
	v_fmac_f32_e32 v210, v206, v206
	v_fmac_f32_e32 v211, v207, v207
	v_lshlrev_b32_e32 v200, 16, v68
	v_and_b32_e32 v201, 0xffff0000, v68
	v_lshlrev_b32_e32 v202, 16, v69
	v_and_b32_e32 v203, 0xffff0000, v69
	v_fmac_f32_e32 v208, v200, v200
	v_fmac_f32_e32 v209, v201, v201
	v_fmac_f32_e32 v208, v202, v202
	v_fmac_f32_e32 v209, v203, v203
	v_lshlrev_b32_e32 v204, 16, v100
	v_and_b32_e32 v205, 0xffff0000, v100
	v_lshlrev_b32_e32 v206, 16, v101
	v_and_b32_e32 v207, 0xffff0000, v101
	v_fmac_f32_e32 v210, v204, v204
	v_fmac_f32_e32 v211, v205, v205
	v_fmac_f32_e32 v210, v206, v206
	v_fmac_f32_e32 v211, v207, v207
	v_lshlrev_b32_e32 v200, 16, v70
	v_and_b32_e32 v201, 0xffff0000, v70
	v_lshlrev_b32_e32 v202, 16, v71
	v_and_b32_e32 v203, 0xffff0000, v71
	v_fmac_f32_e32 v208, v200, v200
	v_fmac_f32_e32 v209, v201, v201
	v_fmac_f32_e32 v208, v202, v202
	v_fmac_f32_e32 v209, v203, v203
	v_lshlrev_b32_e32 v204, 16, v102
	v_and_b32_e32 v205, 0xffff0000, v102
	v_lshlrev_b32_e32 v206, 16, v103
	v_and_b32_e32 v207, 0xffff0000, v103
	v_fmac_f32_e32 v210, v204, v204
	v_fmac_f32_e32 v211, v205, v205
	v_fmac_f32_e32 v210, v206, v206
	v_fmac_f32_e32 v211, v207, v207
	v_lshlrev_b32_e32 v200, 16, v72
	v_and_b32_e32 v201, 0xffff0000, v72
	v_lshlrev_b32_e32 v202, 16, v73
	v_and_b32_e32 v203, 0xffff0000, v73
	v_fmac_f32_e32 v208, v200, v200
	v_fmac_f32_e32 v209, v201, v201
	v_fmac_f32_e32 v208, v202, v202
	v_fmac_f32_e32 v209, v203, v203
	v_lshlrev_b32_e32 v204, 16, v104
	v_and_b32_e32 v205, 0xffff0000, v104
	v_lshlrev_b32_e32 v206, 16, v105
	v_and_b32_e32 v207, 0xffff0000, v105
	v_fmac_f32_e32 v210, v204, v204
	v_fmac_f32_e32 v211, v205, v205
	v_fmac_f32_e32 v210, v206, v206
	v_fmac_f32_e32 v211, v207, v207
	v_lshlrev_b32_e32 v200, 16, v74
	v_and_b32_e32 v201, 0xffff0000, v74
	v_lshlrev_b32_e32 v202, 16, v75
	v_and_b32_e32 v203, 0xffff0000, v75
	v_fmac_f32_e32 v208, v200, v200
	v_fmac_f32_e32 v209, v201, v201
	v_fmac_f32_e32 v208, v202, v202
	v_fmac_f32_e32 v209, v203, v203
	v_lshlrev_b32_e32 v204, 16, v106
	v_and_b32_e32 v205, 0xffff0000, v106
	v_lshlrev_b32_e32 v206, 16, v107
	v_and_b32_e32 v207, 0xffff0000, v107
	v_fmac_f32_e32 v210, v204, v204
	v_fmac_f32_e32 v211, v205, v205
	v_fmac_f32_e32 v210, v206, v206
	v_fmac_f32_e32 v211, v207, v207
	v_lshlrev_b32_e32 v200, 16, v76
	v_and_b32_e32 v201, 0xffff0000, v76
	v_lshlrev_b32_e32 v202, 16, v77
	v_and_b32_e32 v203, 0xffff0000, v77
	v_fmac_f32_e32 v208, v200, v200
	v_fmac_f32_e32 v209, v201, v201
	v_fmac_f32_e32 v208, v202, v202
	v_fmac_f32_e32 v209, v203, v203
	v_lshlrev_b32_e32 v204, 16, v108
	v_and_b32_e32 v205, 0xffff0000, v108
	v_lshlrev_b32_e32 v206, 16, v109
	v_and_b32_e32 v207, 0xffff0000, v109
	v_fmac_f32_e32 v210, v204, v204
	v_fmac_f32_e32 v211, v205, v205
	v_fmac_f32_e32 v210, v206, v206
	v_fmac_f32_e32 v211, v207, v207
	v_lshlrev_b32_e32 v200, 16, v78
	v_and_b32_e32 v201, 0xffff0000, v78
	v_lshlrev_b32_e32 v202, 16, v79
	v_and_b32_e32 v203, 0xffff0000, v79
	v_fmac_f32_e32 v208, v200, v200
	v_fmac_f32_e32 v209, v201, v201
	v_fmac_f32_e32 v208, v202, v202
	v_fmac_f32_e32 v209, v203, v203
	v_lshlrev_b32_e32 v204, 16, v110
	v_and_b32_e32 v205, 0xffff0000, v110
	v_lshlrev_b32_e32 v206, 16, v111
	v_and_b32_e32 v207, 0xffff0000, v111
	v_fmac_f32_e32 v210, v204, v204
	v_fmac_f32_e32 v211, v205, v205
	v_fmac_f32_e32 v210, v206, v206
	v_fmac_f32_e32 v211, v207, v207
	v_add_f32_e32 v208, v208, v209
	v_add_f32_e32 v210, v210, v211
	s_nop 0
	v_add_f32_dpp v212, v208, v208 quad_perm:[1,0,3,2] row_mask:0xf bank_mask:0xf
	v_add_f32_dpp v213, v210, v210 quad_perm:[1,0,3,2] row_mask:0xf bank_mask:0xf
	s_nop 0
	v_add_f32_dpp v212, v212, v212 quad_perm:[2,3,0,1] row_mask:0xf bank_mask:0xf
	v_add_f32_dpp v213, v213, v213 quad_perm:[2,3,0,1] row_mask:0xf bank_mask:0xf
	s_nop 0
	v_add_f32_dpp v212, v212, v212 row_half_mirror row_mask:0xf bank_mask:0xf
	v_add_f32_dpp v213, v213, v213 row_half_mirror row_mask:0xf bank_mask:0xf
	s_nop 0
	v_add_f32_dpp v212, v212, v212 row_mirror row_mask:0xf bank_mask:0xf
	v_add_f32_dpp v213, v213, v213 row_mirror row_mask:0xf bank_mask:0xf
	s_nop 0
	v_readlane_b32 s4, v212, 0
	v_readlane_b32 s5, v212, 16
	v_readlane_b32 s6, v212, 32
	v_readlane_b32 s7, v212, 48
	v_readlane_b32 s24, v213, 0
	v_readlane_b32 s25, v213, 16
	v_readlane_b32 s26, v213, 32
	v_readlane_b32 s27, v213, 48
	s_nop 1
	v_mov_b32_e32 v214, s4
	v_mov_b32_e32 v215, s24
	v_add_f32_e32 v214, s5, v214
	v_add_f32_e32 v215, s25, v215
	v_add_f32_e32 v214, s6, v214
	v_add_f32_e32 v215, s26, v215
	v_add_f32_e32 v214, s7, v214
	v_add_f32_e32 v215, s27, v215
	v_fmamk_f32 v214, v214, 0x3a000000, v195
	v_fmamk_f32 v215, v215, 0x3a000000, v195
; __device__ __forceinline__ float bf_lo(unsigned w) { return __uint_as_float(w << 16); }
; __device__ __forceinline__ float bf_hi(unsigned w) { return __uint_as_float(w & 0xffff0000u); }
; __global__ void __launch_bounds__(NWAVES * 64, 2) mk_fwd(Args args) {
;     ...
;                 const float rsy = __builtin_amdgcn_rsqf(wave_sum(sy) * (1.f / DM) + EPS);
; #pragma unroll
;                 for (int j = 0; j < 8; ++j) { const int col = 4 * F.lane + 256 * j;
;                     const f32x4 y4 = (f32x4){bf_lo(yw[q][j].x), bf_hi(yw[q][j].x), bf_lo(yw[q][j].y), bf_hi(yw[q][j].y)};
;                     *(f32x4*)(args.out + (size_t)row * DM + col) = v[q][j] + PA[j] * (y4 * rsy); }
	v_rsq_f32_e32 v214, v214
	v_rsq_f32_e32 v215, v215
	s_nop 0
	v_lshlrev_b32_e32 v200, 16, v64
	v_and_b32_e32 v201, 0xffff0000, v64
	v_lshlrev_b32_e32 v202, 16, v65
	v_and_b32_e32 v203, 0xffff0000, v65
	v_lshlrev_b32_e32 v204, 16, v96
	v_and_b32_e32 v205, 0xffff0000, v96
	v_lshlrev_b32_e32 v206, 16, v97
	v_and_b32_e32 v207, 0xffff0000, v97
	v_mul_f32_e32 v200, v214, v200
	v_mul_f32_e32 v201, v214, v201
	v_mul_f32_e32 v202, v214, v202
	v_mul_f32_e32 v203, v214, v203
	v_mul_f32_e32 v204, v215, v204
	v_mul_f32_e32 v205, v215, v205
	v_mul_f32_e32 v206, v215, v206
	v_mul_f32_e32 v207, v215, v207
	v_fmac_f32_e32 v0, v128, v200
	v_fmac_f32_e32 v1, v129, v201
	v_fmac_f32_e32 v2, v130, v202
	v_fmac_f32_e32 v3, v131, v203
	v_fmac_f32_e32 v0, v160, v204
	v_fmac_f32_e32 v1, v161, v205
	v_fmac_f32_e32 v2, v162, v206
	v_fmac_f32_e32 v3, v163, v207
	global_store_dwordx4 v192, v[0:3], s[18:19] offset:0
	v_lshlrev_b32_e32 v200, 16, v66
	v_and_b32_e32 v201, 0xffff0000, v66
	v_lshlrev_b32_e32 v202, 16, v67
	v_and_b32_e32 v203, 0xffff0000, v67
	v_lshlrev_b32_e32 v204, 16, v98
	v_and_b32_e32 v205, 0xffff0000, v98
	v_lshlrev_b32_e32 v206, 16, v99
	v_and_b32_e32 v207, 0xffff0000, v99
	v_mul_f32_e32 v200, v214, v200
	v_mul_f32_e32 v201, v214, v201
	v_mul_f32_e32 v202, v214, v202
	v_mul_f32_e32 v203, v214, v203
	v_mul_f32_e32 v204, v215, v204
	v_mul_f32_e32 v205, v215, v205
	v_mul_f32_e32 v206, v215, v206
	v_mul_f32_e32 v207, v215, v207
	v_fmac_f32_e32 v4, v132, v200
	v_fmac_f32_e32 v5, v133, v201
	v_fmac_f32_e32 v6, v134, v202
	v_fmac_f32_e32 v7, v135, v203
	v_fmac_f32_e32 v4, v164, v204
	v_fmac_f32_e32 v5, v165, v205
	v_fmac_f32_e32 v6, v166, v206
	v_fmac_f32_e32 v7, v167, v207
	global_store_dwordx4 v192, v[4:7], s[18:19] offset:1024
	v_lshlrev_b32_e32 v200, 16, v68
	v_and_b32_e32 v201, 0xffff0000, v68
	v_lshlrev_b32_e32 v202, 16, v69
	v_and_b32_e32 v203, 0xffff0000, v69
	v_lshlrev_b32_e32 v204, 16, v100
	v_and_b32_e32 v205, 0xffff0000, v100
	v_lshlrev_b32_e32 v206, 16, v101
	v_and_b32_e32 v207, 0xffff0000, v101
	v_mul_f32_e32 v200, v214, v200
	v_mul_f32_e32 v201, v214, v201
	v_mul_f32_e32 v202, v214, v202
	v_mul_f32_e32 v203, v214, v203
	v_mul_f32_e32 v204, v215, v204
	v_mul_f32_e32 v205, v215, v205
	v_mul_f32_e32 v206, v215, v206
	v_mul_f32_e32 v207, v215, v207
	v_fmac_f32_e32 v8, v136, v200
	v_fmac_f32_e32 v9, v137, v201
	v_fmac_f32_e32 v10, v138, v202
	v_fmac_f32_e32 v11, v139, v203
	v_fmac_f32_e32 v8, v168, v204
	v_fmac_f32_e32 v9, v169, v205
	v_fmac_f32_e32 v10, v170, v206
	v_fmac_f32_e32 v11, v171, v207
	global_store_dwordx4 v192, v[8:11], s[18:19] offset:2048
	v_lshlrev_b32_e32 v200, 16, v70
	v_and_b32_e32 v201, 0xffff0000, v70
	v_lshlrev_b32_e32 v202, 16, v71
	v_and_b32_e32 v203, 0xffff0000, v71
	v_lshlrev_b32_e32 v204, 16, v102
	v_and_b32_e32 v205, 0xffff0000, v102
	v_lshlrev_b32_e32 v206, 16, v103
	v_and_b32_e32 v207, 0xffff0000, v103
	v_mul_f32_e32 v200, v214, v200
	v_mul_f32_e32 v201, v214, v201
	v_mul_f32_e32 v202, v214, v202
	v_mul_f32_e32 v203, v214, v203
	v_mul_f32_e32 v204, v215, v204
	v_mul_f32_e32 v205, v215, v205
	v_mul_f32_e32 v206, v215, v206
	v_mul_f32_e32 v207, v215, v207
	v_fmac_f32_e32 v12, v140, v200
	v_fmac_f32_e32 v13, v141, v201
	v_fmac_f32_e32 v14, v142, v202
	v_fmac_f32_e32 v15, v143, v203
	v_fmac_f32_e32 v12, v172, v204
	v_fmac_f32_e32 v13, v173, v205
	v_fmac_f32_e32 v14, v174, v206
	v_fmac_f32_e32 v15, v175, v207
	global_store_dwordx4 v192, v[12:15], s[18:19] offset:3072
	v_lshlrev_b32_e32 v200, 16, v72
	v_and_b32_e32 v201, 0xffff0000, v72
	v_lshlrev_b32_e32 v202, 16, v73
	v_and_b32_e32 v203, 0xffff0000, v73
	v_lshlrev_b32_e32 v204, 16, v104
	v_and_b32_e32 v205, 0xffff0000, v104
	v_lshlrev_b32_e32 v206, 16, v105
	v_and_b32_e32 v207, 0xffff0000, v105
	v_mul_f32_e32 v200, v214, v200
	v_mul_f32_e32 v201, v214, v201
	v_mul_f32_e32 v202, v214, v202
	v_mul_f32_e32 v203, v214, v203
	v_mul_f32_e32 v204, v215, v204
	v_mul_f32_e32 v205, v215, v205
	v_mul_f32_e32 v206, v215, v206
	v_mul_f32_e32 v207, v215, v207
	v_fmac_f32_e32 v16, v144, v200
	v_fmac_f32_e32 v17, v145, v201
	v_fmac_f32_e32 v18, v146, v202
	v_fmac_f32_e32 v19, v147, v203
	v_fmac_f32_e32 v16, v176, v204
	v_fmac_f32_e32 v17, v177, v205
	v_fmac_f32_e32 v18, v178, v206
	v_fmac_f32_e32 v19, v179, v207
	global_store_dwordx4 v193, v[16:19], s[18:19] offset:0
	v_lshlrev_b32_e32 v200, 16, v74
	v_and_b32_e32 v201, 0xffff0000, v74
	v_lshlrev_b32_e32 v202, 16, v75
	v_and_b32_e32 v203, 0xffff0000, v75
	v_lshlrev_b32_e32 v204, 16, v106
	v_and_b32_e32 v205, 0xffff0000, v106
	v_lshlrev_b32_e32 v206, 16, v107
	v_and_b32_e32 v207, 0xffff0000, v107
	v_mul_f32_e32 v200, v214, v200
	v_mul_f32_e32 v201, v214, v201
	v_mul_f32_e32 v202, v214, v202
	v_mul_f32_e32 v203, v214, v203
	v_mul_f32_e32 v204, v215, v204
	v_mul_f32_e32 v205, v215, v205
	v_mul_f32_e32 v206, v215, v206
	v_mul_f32_e32 v207, v215, v207
	v_fmac_f32_e32 v20, v148, v200
	v_fmac_f32_e32 v21, v149, v201
	v_fmac_f32_e32 v22, v150, v202
	v_fmac_f32_e32 v23, v151, v203
	v_fmac_f32_e32 v20, v180, v204
	v_fmac_f32_e32 v21, v181, v205
	v_fmac_f32_e32 v22, v182, v206
	v_fmac_f32_e32 v23, v183, v207
	global_store_dwordx4 v193, v[20:23], s[18:19] offset:1024
	v_lshlrev_b32_e32 v200, 16, v76
	v_and_b32_e32 v201, 0xffff0000, v76
	v_lshlrev_b32_e32 v202, 16, v77
	v_and_b32_e32 v203, 0xffff0000, v77
	v_lshlrev_b32_e32 v204, 16, v108
	v_and_b32_e32 v205, 0xffff0000, v108
	v_lshlrev_b32_e32 v206, 16, v109
	v_and_b32_e32 v207, 0xffff0000, v109
	v_mul_f32_e32 v200, v214, v200
	v_mul_f32_e32 v201, v214, v201
	v_mul_f32_e32 v202, v214, v202
	v_mul_f32_e32 v203, v214, v203
	v_mul_f32_e32 v204, v215, v204
	v_mul_f32_e32 v205, v215, v205
	v_mul_f32_e32 v206, v215, v206
	v_mul_f32_e32 v207, v215, v207
	v_fmac_f32_e32 v24, v152, v200
	v_fmac_f32_e32 v25, v153, v201
	v_fmac_f32_e32 v26, v154, v202
	v_fmac_f32_e32 v27, v155, v203
	v_fmac_f32_e32 v24, v184, v204
	v_fmac_f32_e32 v25, v185, v205
	v_fmac_f32_e32 v26, v186, v206
	v_fmac_f32_e32 v27, v187, v207
	global_store_dwordx4 v193, v[24:27], s[18:19] offset:2048
	v_lshlrev_b32_e32 v200, 16, v78
	v_and_b32_e32 v201, 0xffff0000, v78
	v_lshlrev_b32_e32 v202, 16, v79
	v_and_b32_e32 v203, 0xffff0000, v79
	v_lshlrev_b32_e32 v204, 16, v110
	v_and_b32_e32 v205, 0xffff0000, v110
	v_lshlrev_b32_e32 v206, 16, v111
	v_and_b32_e32 v207, 0xffff0000, v111
	v_mul_f32_e32 v200, v214, v200
	v_mul_f32_e32 v201, v214, v201
	v_mul_f32_e32 v202, v214, v202
	v_mul_f32_e32 v203, v214, v203
	v_mul_f32_e32 v204, v215, v204
	v_mul_f32_e32 v205, v215, v205
	v_mul_f32_e32 v206, v215, v206
	v_mul_f32_e32 v207, v215, v207
	v_fmac_f32_e32 v28, v156, v200
	v_fmac_f32_e32 v29, v157, v201
	v_fmac_f32_e32 v30, v158, v202
	v_fmac_f32_e32 v31, v159, v203
	v_fmac_f32_e32 v28, v188, v204
	v_fmac_f32_e32 v29, v189, v205
	v_fmac_f32_e32 v30, v190, v206
	v_fmac_f32_e32 v31, v191, v207
	global_store_dwordx4 v193, v[28:31], s[18:19] offset:3072
	s_add_u32 s18, s18, 0x2000
	s_addc_u32 s19, s19, 0
	s_waitcnt vmcnt(8)
; __device__ __forceinline__ float bf_lo(unsigned w) { return __uint_as_float(w << 16); }
; __device__ __forceinline__ float bf_hi(unsigned w) { return __uint_as_float(w & 0xffff0000u); }
; __global__ void __launch_bounds__(NWAVES * 64, 2) mk_fwd(Args args) {
;     ...
;                 float sy = 0.f;
; #pragma unroll
;                 for (int j = 0; j < 8; ++j) { const float a = bf_lo(yw[q][j].x), b = bf_hi(yw[q][j].x), c2 = bf_lo(yw[q][j].y), d = bf_hi(yw[q][j].y); sy += (a * a + b * b) + (c2 * c2 + d * d); }
;                 const float rsy = __builtin_amdgcn_rsqf(wave_sum(sy) * (1.f / DM) + EPS);
	v_lshlrev_b32_e32 v200, 16, v80
	v_and_b32_e32 v201, 0xffff0000, v80
	v_lshlrev_b32_e32 v202, 16, v81
	v_and_b32_e32 v203, 0xffff0000, v81
	v_mul_f32_e32 v208, v200, v200
	v_mul_f32_e32 v209, v201, v201
	v_fmac_f32_e32 v208, v202, v202
	v_fmac_f32_e32 v209, v203, v203
	v_lshlrev_b32_e32 v204, 16, v112
	v_and_b32_e32 v205, 0xffff0000, v112
	v_lshlrev_b32_e32 v206, 16, v113
	v_and_b32_e32 v207, 0xffff0000, v113
	v_mul_f32_e32 v210, v204, v204
	v_mul_f32_e32 v211, v205, v205
	v_fmac_f32_e32 v210, v206, v206
	v_fmac_f32_e32 v211, v207, v207
	v_lshlrev_b32_e32 v200, 16, v82
	v_and_b32_e32 v201, 0xffff0000, v82
	v_lshlrev_b32_e32 v202, 16, v83
	v_and_b32_e32 v203, 0xffff0000, v83
	v_fmac_f32_e32 v208, v200, v200
	v_fmac_f32_e32 v209, v201, v201
	v_fmac_f32_e32 v208, v202, v202
	v_fmac_f32_e32 v209, v203, v203
	v_lshlrev_b32_e32 v204, 16, v114
	v_and_b32_e32 v205, 0xffff0000, v114
	v_lshlrev_b32_e32 v206, 16, v115
	v_and_b32_e32 v207, 0xffff0000, v115
	v_fmac_f32_e32 v210, v204, v204
	v_fmac_f32_e32 v211, v205, v205
	v_fmac_f32_e32 v210, v206, v206
	v_fmac_f32_e32 v211, v207, v207
	v_lshlrev_b32_e32 v200, 16, v84
	v_and_b32_e32 v201, 0xffff0000, v84
	v_lshlrev_b32_e32 v202, 16, v85
	v_and_b32_e32 v203, 0xffff0000, v85
	v_fmac_f32_e32 v208, v200, v200
	v_fmac_f32_e32 v209, v201, v201
	v_fmac_f32_e32 v208, v202, v202
	v_fmac_f32_e32 v209, v203, v203
	v_lshlrev_b32_e32 v204, 16, v116
	v_and_b32_e32 v205, 0xffff0000, v116
	v_lshlrev_b32_e32 v206, 16, v117
	v_and_b32_e32 v207, 0xffff0000, v117
	v_fmac_f32_e32 v210, v204, v204
	v_fmac_f32_e32 v211, v205, v205
	v_fmac_f32_e32 v210, v206, v206
	v_fmac_f32_e32 v211, v207, v207
	v_lshlrev_b32_e32 v200, 16, v86
	v_and_b32_e32 v201, 0xffff0000, v86
	v_lshlrev_b32_e32 v202, 16, v87
	v_and_b32_e32 v203, 0xffff0000, v87
	v_fmac_f32_e32 v208, v200, v200
	v_fmac_f32_e32 v209, v201, v201
	v_fmac_f32_e32 v208, v202, v202
	v_fmac_f32_e32 v209, v203, v203
	v_lshlrev_b32_e32 v204, 16, v118
	v_and_b32_e32 v205, 0xffff0000, v118
	v_lshlrev_b32_e32 v206, 16, v119
	v_and_b32_e32 v207, 0xffff0000, v119
	v_fmac_f32_e32 v210, v204, v204
	v_fmac_f32_e32 v211, v205, v205
	v_fmac_f32_e32 v210, v206, v206
	v_fmac_f32_e32 v211, v207, v207
	v_lshlrev_b32_e32 v200, 16, v88
	v_and_b32_e32 v201, 0xffff0000, v88
	v_lshlrev_b32_e32 v202, 16, v89
	v_and_b32_e32 v203, 0xffff0000, v89
	v_fmac_f32_e32 v208, v200, v200
	v_fmac_f32_e32 v209, v201, v201
	v_fmac_f32_e32 v208, v202, v202
	v_fmac_f32_e32 v209, v203, v203
	v_lshlrev_b32_e32 v204, 16, v120
	v_and_b32_e32 v205, 0xffff0000, v120
	v_lshlrev_b32_e32 v206, 16, v121
	v_and_b32_e32 v207, 0xffff0000, v121
	v_fmac_f32_e32 v210, v204, v204
	v_fmac_f32_e32 v211, v205, v205
	v_fmac_f32_e32 v210, v206, v206
	v_fmac_f32_e32 v211, v207, v207
	v_lshlrev_b32_e32 v200, 16, v90
	v_and_b32_e32 v201, 0xffff0000, v90
	v_lshlrev_b32_e32 v202, 16, v91
	v_and_b32_e32 v203, 0xffff0000, v91
	v_fmac_f32_e32 v208, v200, v200
	v_fmac_f32_e32 v209, v201, v201
	v_fmac_f32_e32 v208, v202, v202
	v_fmac_f32_e32 v209, v203, v203
	v_lshlrev_b32_e32 v204, 16, v122
	v_and_b32_e32 v205, 0xffff0000, v122
	v_lshlrev_b32_e32 v206, 16, v123
	v_and_b32_e32 v207, 0xffff0000, v123
	v_fmac_f32_e32 v210, v204, v204
	v_fmac_f32_e32 v211, v205, v205
	v_fmac_f32_e32 v210, v206, v206
	v_fmac_f32_e32 v211, v207, v207
	v_lshlrev_b32_e32 v200, 16, v92
	v_and_b32_e32 v201, 0xffff0000, v92
	v_lshlrev_b32_e32 v202, 16, v93
	v_and_b32_e32 v203, 0xffff0000, v93
	v_fmac_f32_e32 v208, v200, v200
	v_fmac_f32_e32 v209, v201, v201
	v_fmac_f32_e32 v208, v202, v202
	v_fmac_f32_e32 v209, v203, v203
	v_lshlrev_b32_e32 v204, 16, v124
	v_and_b32_e32 v205, 0xffff0000, v124
	v_lshlrev_b32_e32 v206, 16, v125
	v_and_b32_e32 v207, 0xffff0000, v125
	v_fmac_f32_e32 v210, v204, v204
	v_fmac_f32_e32 v211, v205, v205
	v_fmac_f32_e32 v210, v206, v206
	v_fmac_f32_e32 v211, v207, v207
	v_lshlrev_b32_e32 v200, 16, v94
	v_and_b32_e32 v201, 0xffff0000, v94
	v_lshlrev_b32_e32 v202, 16, v95
	v_and_b32_e32 v203, 0xffff0000, v95
	v_fmac_f32_e32 v208, v200, v200
	v_fmac_f32_e32 v209, v201, v201
	v_fmac_f32_e32 v208, v202, v202
	v_fmac_f32_e32 v209, v203, v203
	v_lshlrev_b32_e32 v204, 16, v126
	v_and_b32_e32 v205, 0xffff0000, v126
	v_lshlrev_b32_e32 v206, 16, v127
	v_and_b32_e32 v207, 0xffff0000, v127
	v_fmac_f32_e32 v210, v204, v204
	v_fmac_f32_e32 v211, v205, v205
	v_fmac_f32_e32 v210, v206, v206
	v_fmac_f32_e32 v211, v207, v207
	v_add_f32_e32 v208, v208, v209
	v_add_f32_e32 v210, v210, v211
	s_nop 0
	v_add_f32_dpp v212, v208, v208 quad_perm:[1,0,3,2] row_mask:0xf bank_mask:0xf
	v_add_f32_dpp v213, v210, v210 quad_perm:[1,0,3,2] row_mask:0xf bank_mask:0xf
	s_nop 0
	v_add_f32_dpp v212, v212, v212 quad_perm:[2,3,0,1] row_mask:0xf bank_mask:0xf
	v_add_f32_dpp v213, v213, v213 quad_perm:[2,3,0,1] row_mask:0xf bank_mask:0xf
	s_nop 0
	v_add_f32_dpp v212, v212, v212 row_half_mirror row_mask:0xf bank_mask:0xf
	v_add_f32_dpp v213, v213, v213 row_half_mirror row_mask:0xf bank_mask:0xf
	s_nop 0
	v_add_f32_dpp v212, v212, v212 row_mirror row_mask:0xf bank_mask:0xf
	v_add_f32_dpp v213, v213, v213 row_mirror row_mask:0xf bank_mask:0xf
	s_nop 0
	v_readlane_b32 s4, v212, 0
	v_readlane_b32 s5, v212, 16
	v_readlane_b32 s6, v212, 32
	v_readlane_b32 s7, v212, 48
	v_readlane_b32 s24, v213, 0
	v_readlane_b32 s25, v213, 16
	v_readlane_b32 s26, v213, 32
	v_readlane_b32 s27, v213, 48
	s_nop 1
	v_mov_b32_e32 v214, s4
	v_mov_b32_e32 v215, s24
	v_add_f32_e32 v214, s5, v214
	v_add_f32_e32 v215, s25, v215
	v_add_f32_e32 v214, s6, v214
	v_add_f32_e32 v215, s26, v215
	v_add_f32_e32 v214, s7, v214
	v_add_f32_e32 v215, s27, v215
	v_fmamk_f32 v214, v214, 0x3a000000, v195
	v_fmamk_f32 v215, v215, 0x3a000000, v195
; __device__ __forceinline__ float bf_lo(unsigned w) { return __uint_as_float(w << 16); }
; __device__ __forceinline__ float bf_hi(unsigned w) { return __uint_as_float(w & 0xffff0000u); }
; __global__ void __launch_bounds__(NWAVES * 64, 2) mk_fwd(Args args) {
;     ...
;                 const float rsy = __builtin_amdgcn_rsqf(wave_sum(sy) * (1.f / DM) + EPS);
; #pragma unroll
;                 for (int j = 0; j < 8; ++j) { const int col = 4 * F.lane + 256 * j;
;                     const f32x4 y4 = (f32x4){bf_lo(yw[q][j].x), bf_hi(yw[q][j].x), bf_lo(yw[q][j].y), bf_hi(yw[q][j].y)};
;                     *(f32x4*)(args.out + (size_t)row * DM + col) = v[q][j] + PA[j] * (y4 * rsy); }
	v_rsq_f32_e32 v214, v214
	v_rsq_f32_e32 v215, v215
	s_nop 0
	v_lshlrev_b32_e32 v200, 16, v80
	v_and_b32_e32 v201, 0xffff0000, v80
	v_lshlrev_b32_e32 v202, 16, v81
	v_and_b32_e32 v203, 0xffff0000, v81
	v_lshlrev_b32_e32 v204, 16, v112
	v_and_b32_e32 v205, 0xffff0000, v112
	v_lshlrev_b32_e32 v206, 16, v113
	v_and_b32_e32 v207, 0xffff0000, v113
	v_mul_f32_e32 v200, v214, v200
	v_mul_f32_e32 v201, v214, v201
	v_mul_f32_e32 v202, v214, v202
	v_mul_f32_e32 v203, v214, v203
	v_mul_f32_e32 v204, v215, v204
	v_mul_f32_e32 v205, v215, v205
	v_mul_f32_e32 v206, v215, v206
	v_mul_f32_e32 v207, v215, v207
	v_fmac_f32_e32 v32, v128, v200
	v_fmac_f32_e32 v33, v129, v201
	v_fmac_f32_e32 v34, v130, v202
	v_fmac_f32_e32 v35, v131, v203
	v_fmac_f32_e32 v32, v160, v204
	v_fmac_f32_e32 v33, v161, v205
	v_fmac_f32_e32 v34, v162, v206
	v_fmac_f32_e32 v35, v163, v207
	global_store_dwordx4 v192, v[32:35], s[18:19] offset:0
	v_lshlrev_b32_e32 v200, 16, v82
	v_and_b32_e32 v201, 0xffff0000, v82
	v_lshlrev_b32_e32 v202, 16, v83
	v_and_b32_e32 v203, 0xffff0000, v83
	v_lshlrev_b32_e32 v204, 16, v114
	v_and_b32_e32 v205, 0xffff0000, v114
	v_lshlrev_b32_e32 v206, 16, v115
	v_and_b32_e32 v207, 0xffff0000, v115
	v_mul_f32_e32 v200, v214, v200
	v_mul_f32_e32 v201, v214, v201
	v_mul_f32_e32 v202, v214, v202
	v_mul_f32_e32 v203, v214, v203
	v_mul_f32_e32 v204, v215, v204
	v_mul_f32_e32 v205, v215, v205
	v_mul_f32_e32 v206, v215, v206
	v_mul_f32_e32 v207, v215, v207
	v_fmac_f32_e32 v36, v132, v200
	v_fmac_f32_e32 v37, v133, v201
	v_fmac_f32_e32 v38, v134, v202
	v_fmac_f32_e32 v39, v135, v203
	v_fmac_f32_e32 v36, v164, v204
	v_fmac_f32_e32 v37, v165, v205
	v_fmac_f32_e32 v38, v166, v206
	v_fmac_f32_e32 v39, v167, v207
	global_store_dwordx4 v192, v[36:39], s[18:19] offset:1024
	v_lshlrev_b32_e32 v200, 16, v84
	v_and_b32_e32 v201, 0xffff0000, v84
	v_lshlrev_b32_e32 v202, 16, v85
	v_and_b32_e32 v203, 0xffff0000, v85
	v_lshlrev_b32_e32 v204, 16, v116
	v_and_b32_e32 v205, 0xffff0000, v116
	v_lshlrev_b32_e32 v206, 16, v117
	v_and_b32_e32 v207, 0xffff0000, v117
	v_mul_f32_e32 v200, v214, v200
	v_mul_f32_e32 v201, v214, v201
	v_mul_f32_e32 v202, v214, v202
	v_mul_f32_e32 v203, v214, v203
	v_mul_f32_e32 v204, v215, v204
	v_mul_f32_e32 v205, v215, v205
	v_mul_f32_e32 v206, v215, v206
	v_mul_f32_e32 v207, v215, v207
	v_fmac_f32_e32 v40, v136, v200
	v_fmac_f32_e32 v41, v137, v201
	v_fmac_f32_e32 v42, v138, v202
	v_fmac_f32_e32 v43, v139, v203
	v_fmac_f32_e32 v40, v168, v204
	v_fmac_f32_e32 v41, v169, v205
	v_fmac_f32_e32 v42, v170, v206
	v_fmac_f32_e32 v43, v171, v207
	global_store_dwordx4 v192, v[40:43], s[18:19] offset:2048
	v_lshlrev_b32_e32 v200, 16, v86
	v_and_b32_e32 v201, 0xffff0000, v86
	v_lshlrev_b32_e32 v202, 16, v87
	v_and_b32_e32 v203, 0xffff0000, v87
	v_lshlrev_b32_e32 v204, 16, v118
	v_and_b32_e32 v205, 0xffff0000, v118
	v_lshlrev_b32_e32 v206, 16, v119
	v_and_b32_e32 v207, 0xffff0000, v119
	v_mul_f32_e32 v200, v214, v200
	v_mul_f32_e32 v201, v214, v201
	v_mul_f32_e32 v202, v214, v202
	v_mul_f32_e32 v203, v214, v203
	v_mul_f32_e32 v204, v215, v204
	v_mul_f32_e32 v205, v215, v205
	v_mul_f32_e32 v206, v215, v206
	v_mul_f32_e32 v207, v215, v207
	v_fmac_f32_e32 v44, v140, v200
	v_fmac_f32_e32 v45, v141, v201
	v_fmac_f32_e32 v46, v142, v202
	v_fmac_f32_e32 v47, v143, v203
	v_fmac_f32_e32 v44, v172, v204
	v_fmac_f32_e32 v45, v173, v205
	v_fmac_f32_e32 v46, v174, v206
	v_fmac_f32_e32 v47, v175, v207
	global_store_dwordx4 v192, v[44:47], s[18:19] offset:3072
	v_lshlrev_b32_e32 v200, 16, v88
	v_and_b32_e32 v201, 0xffff0000, v88
	v_lshlrev_b32_e32 v202, 16, v89
	v_and_b32_e32 v203, 0xffff0000, v89
	v_lshlrev_b32_e32 v204, 16, v120
	v_and_b32_e32 v205, 0xffff0000, v120
	v_lshlrev_b32_e32 v206, 16, v121
	v_and_b32_e32 v207, 0xffff0000, v121
	v_mul_f32_e32 v200, v214, v200
	v_mul_f32_e32 v201, v214, v201
	v_mul_f32_e32 v202, v214, v202
	v_mul_f32_e32 v203, v214, v203
	v_mul_f32_e32 v204, v215, v204
	v_mul_f32_e32 v205, v215, v205
	v_mul_f32_e32 v206, v215, v206
	v_mul_f32_e32 v207, v215, v207
	v_fmac_f32_e32 v48, v144, v200
	v_fmac_f32_e32 v49, v145, v201
	v_fmac_f32_e32 v50, v146, v202
	v_fmac_f32_e32 v51, v147, v203
	v_fmac_f32_e32 v48, v176, v204
	v_fmac_f32_e32 v49, v177, v205
	v_fmac_f32_e32 v50, v178, v206
	v_fmac_f32_e32 v51, v179, v207
	global_store_dwordx4 v193, v[48:51], s[18:19] offset:0
	v_lshlrev_b32_e32 v200, 16, v90
	v_and_b32_e32 v201, 0xffff0000, v90
	v_lshlrev_b32_e32 v202, 16, v91
	v_and_b32_e32 v203, 0xffff0000, v91
	v_lshlrev_b32_e32 v204, 16, v122
	v_and_b32_e32 v205, 0xffff0000, v122
	v_lshlrev_b32_e32 v206, 16, v123
	v_and_b32_e32 v207, 0xffff0000, v123
	v_mul_f32_e32 v200, v214, v200
	v_mul_f32_e32 v201, v214, v201
	v_mul_f32_e32 v202, v214, v202
	v_mul_f32_e32 v203, v214, v203
	v_mul_f32_e32 v204, v215, v204
	v_mul_f32_e32 v205, v215, v205
	v_mul_f32_e32 v206, v215, v206
	v_mul_f32_e32 v207, v215, v207
	v_fmac_f32_e32 v52, v148, v200
	v_fmac_f32_e32 v53, v149, v201
	v_fmac_f32_e32 v54, v150, v202
	v_fmac_f32_e32 v55, v151, v203
	v_fmac_f32_e32 v52, v180, v204
	v_fmac_f32_e32 v53, v181, v205
	v_fmac_f32_e32 v54, v182, v206
	v_fmac_f32_e32 v55, v183, v207
	global_store_dwordx4 v193, v[52:55], s[18:19] offset:1024
	v_lshlrev_b32_e32 v200, 16, v92
	v_and_b32_e32 v201, 0xffff0000, v92
	v_lshlrev_b32_e32 v202, 16, v93
	v_and_b32_e32 v203, 0xffff0000, v93
	v_lshlrev_b32_e32 v204, 16, v124
	v_and_b32_e32 v205, 0xffff0000, v124
	v_lshlrev_b32_e32 v206, 16, v125
	v_and_b32_e32 v207, 0xffff0000, v125
	v_mul_f32_e32 v200, v214, v200
	v_mul_f32_e32 v201, v214, v201
	v_mul_f32_e32 v202, v214, v202
	v_mul_f32_e32 v203, v214, v203
	v_mul_f32_e32 v204, v215, v204
	v_mul_f32_e32 v205, v215, v205
	v_mul_f32_e32 v206, v215, v206
	v_mul_f32_e32 v207, v215, v207
	v_fmac_f32_e32 v56, v152, v200
	v_fmac_f32_e32 v57, v153, v201
	v_fmac_f32_e32 v58, v154, v202
	v_fmac_f32_e32 v59, v155, v203
	v_fmac_f32_e32 v56, v184, v204
	v_fmac_f32_e32 v57, v185, v205
	v_fmac_f32_e32 v58, v186, v206
	v_fmac_f32_e32 v59, v187, v207
	global_store_dwordx4 v193, v[56:59], s[18:19] offset:2048
	v_lshlrev_b32_e32 v200, 16, v94
	v_and_b32_e32 v201, 0xffff0000, v94
	v_lshlrev_b32_e32 v202, 16, v95
	v_and_b32_e32 v203, 0xffff0000, v95
	v_lshlrev_b32_e32 v204, 16, v126
	v_and_b32_e32 v205, 0xffff0000, v126
	v_lshlrev_b32_e32 v206, 16, v127
	v_and_b32_e32 v207, 0xffff0000, v127
	v_mul_f32_e32 v200, v214, v200
	v_mul_f32_e32 v201, v214, v201
	v_mul_f32_e32 v202, v214, v202
	v_mul_f32_e32 v203, v214, v203
	v_mul_f32_e32 v204, v215, v204
	v_mul_f32_e32 v205, v215, v205
	v_mul_f32_e32 v206, v215, v206
	v_mul_f32_e32 v207, v215, v207
	v_fmac_f32_e32 v60, v156, v200
	v_fmac_f32_e32 v61, v157, v201
	v_fmac_f32_e32 v62, v158, v202
	v_fmac_f32_e32 v63, v159, v203
	v_fmac_f32_e32 v60, v188, v204
	v_fmac_f32_e32 v61, v189, v205
	v_fmac_f32_e32 v62, v190, v206
	v_fmac_f32_e32 v63, v191, v207
	global_store_dwordx4 v193, v[60:63], s[18:19] offset:3072
	s_add_u32 s18, s18, 0x2000
	s_addc_u32 s19, s19, 0
	s_branch .LBB0_1296
